# v28 + the vmcnt and lgkmcnt waits in front of every K-loop barrier merged into one s_waitcnt
# baseline (speedup 1.0000x reference)
; #define PG8_STAGE(bufoff, gbase, voff) do { _Pragma("unroll") for (int _i = 0; _i < 2; ++_i) \
;         __builtin_amdgcn_global_load_lds((const unsigned*)((const char*)(gbase) + (voff)[_i]), (PG8_LAS unsigned*)(lds + (bufoff) + ldsw + _i * 8192), 16, 0, 0); } while (0)
; #define PG8_LDA(dst, b, h) do { _Pragma("unroll") for (int m = 0; m < 4; ++m) _Pragma("unroll") for (int k = 0; k < 2; ++k) dst[m][k] = *(const PG8_LAS bf16x8*)(lds + PG8_SA(b, h) + aoff + m * 2048 + k * 1024); } while (0)
; #define PG8_LDB(dst, b, h) do { _Pragma("unroll") for (int n = 0; n < 2; ++n) _Pragma("unroll") for (int k = 0; k < 2; ++k) dst[n][k] = *(const PG8_LAS bf16x8*)(lds + PG8_SB(b, h) + boff + n * 2048 + k * 1024); } while (0)
; #define PG8_WAIT_V(n) asm volatile("s_waitcnt vmcnt(" #n ")" ::: "memory")
; #define PG8_WAIT_L(n) asm volatile("s_waitcnt lgkmcnt(" #n ")" ::: "memory")
; #define PG8_BAR __builtin_amdgcn_s_barrier()
; #define PG8_SCHED __builtin_amdgcn_sched_barrier(0)
; template <class Epi, class Sched, bool ALIGN_EPI = false, bool SP2 = false>
; __device__ __forceinline__ void gemm_phase(PG8_LAS unsigned char* lds, const Gemm g, const Sched& S, const Epi& E, int tid_in) {
;     ...
;         const char* nA = has_next ? (const char*)g.A + (size_t)nxt.pm * tstep : cA; const char* nB = has_next ? (const char*)g.Bt + (size_t)nxt.pn * tstep : cB;
;         for (int t = 0; t < nt; t += 2) {
;             if constexpr (Epi::MIDK) { if (t == Epi::MIDK_T) { if (wr == 0) PG8_BAR; E.mid(acc, cur, wr, wc, fr, fq); if (wr == 1) PG8_BAR; } }
;             const bool last = (t == nt - 2);
;             const char* a1 = cA + (size_t)(t + 1) * kstep;
;             const char* a2 = last ? nA : cA + (size_t)(t + 2) * kstep; const char* b2 = last ? nB : cB + (size_t)(t + 2) * kstep;
;             const char* a3 = a2 + kstep; const char* b3 = b2 + kstep;
;             if (last && has_next) S.a_ready(nxt);
;             if constexpr (SP2) {
;             PG8_LDB(B0, 0, 0); PG8_LDB(B1, 0, 1); PG8_SCHED; PG8_LDA(At, 0, 0); PG8_STAGE(PG8_SA(1, 1), a1 + hstep, voffA);
;             PG8_WAIT_V(8); PG8_WAIT_L(0); PG8_BAR; PG8_MMA(0, 0, At, B0); PG8_MMA(0, 1, At, B1); PG8_BAR; PG8_SCHED;
;             PG8_LDA(At, 0, 1); PG8_STAGE(PG8_SB(0, 0), b2, voffB); PG8_STAGE(PG8_SB(0, 1), b2 + hstep, voffB); PG8_STAGE(PG8_SA(0, 0), a2, voffA);
.LBB0_375:
	s_ashr_i32 s17, s16, 31
	s_lshl_b64 s[18:19], s[16:17], 19
	s_add_u32 s18, s0, s18
	s_addc_u32 s19, s1, s19
	s_and_b64 s[20:21], s[2:3], exec
	s_cselect_b32 s17, s19, s25
	s_cselect_b32 s52, s18, s24
	s_ashr_i32 s15, s14, 31
	s_lshl_b64 s[20:21], s[14:15], 19
	s_add_u32 s20, s30, s20
	s_addc_u32 s21, s31, s21
	s_and_b64 s[28:29], s[2:3], exec
	s_cselect_b32 s15, s21, s27
	s_cselect_b32 s53, s20, s26
	s_add_u32 s24, s24, 0x40080
	s_addc_u32 s25, s25, 0
	s_add_u32 s54, s26, 0x100
	s_addc_u32 s55, s27, 0
	s_mov_b32 s56, -2
	s_add_u32 s26, s24, 0xfffc0080
	s_addc_u32 s27, s25, -1
	s_cmp_eq_u32 s56, 12
	s_cselect_b32 s29, s17, s27
	s_cselect_b32 s28, s52, s26
	s_cselect_b32 s27, s15, s55
	s_cselect_b32 s26, s53, s54
	s_add_i32 m0, s23, 0xc000
	ds_read_b128 v[150:153], v147
	global_load_lds_dwordx4 v136, s[24:25]
	s_add_i32 m0, s23, 0xe000
	ds_read_b128 v[154:157], v147 offset:1024
	global_load_lds_dwordx4 v138, s[24:25]
	ds_read_b128 v[158:161], v147 offset:2048
	ds_read_b128 v[162:165], v147 offset:3072
	ds_read_b128 v[166:169], v148
	ds_read_b128 v[170:173], v148 offset:1024
	ds_read_b128 v[174:177], v148 offset:2048
	ds_read_b128 v[178:181], v148 offset:3072
	ds_read_b128 v[182:185], v149
	ds_read_b128 v[186:189], v149 offset:1024
	ds_read_b128 v[190:193], v149 offset:2048
	ds_read_b128 v[194:197], v149 offset:3072
	ds_read_b128 v[198:201], v149 offset:4096
	ds_read_b128 v[202:205], v149 offset:5120
	ds_read_b128 v[206:209], v149 offset:6144
	ds_read_b128 v[210:213], v149 offset:7168
	s_waitcnt vmcnt(8) lgkmcnt(0)
	s_barrier
	v_mfma_f32_16x16x32_bf16 v[124:127], v[150:153], v[182:185], 0
	v_mfma_f32_16x16x32_bf16 v[120:123], v[158:161], v[182:185], 0
	v_mfma_f32_16x16x32_bf16 v[108:111], v[150:153], v[190:193], 0
	v_mfma_f32_16x16x32_bf16 v[104:107], v[158:161], v[190:193], 0
	v_mfma_f32_16x16x32_bf16 v[92:95], v[150:153], v[198:201], 0
	v_mfma_f32_16x16x32_bf16 v[88:91], v[158:161], v[198:201], 0
	v_mfma_f32_16x16x32_bf16 v[76:79], v[150:153], v[206:209], 0
	v_mfma_f32_16x16x32_bf16 v[72:75], v[158:161], v[206:209], 0
	v_mfma_f32_16x16x32_bf16 v[124:127], v[154:157], v[186:189], v[124:127]
	v_mfma_f32_16x16x32_bf16 v[120:123], v[162:165], v[186:189], v[120:123]
	v_mfma_f32_16x16x32_bf16 v[108:111], v[154:157], v[194:197], v[108:111]
	v_mfma_f32_16x16x32_bf16 v[104:107], v[162:165], v[194:197], v[104:107]
	v_mfma_f32_16x16x32_bf16 v[92:95], v[154:157], v[202:205], v[92:95]
	v_mfma_f32_16x16x32_bf16 v[88:91], v[162:165], v[202:205], v[88:91]
	v_mfma_f32_16x16x32_bf16 v[76:79], v[154:157], v[210:213], v[76:79]
	v_mfma_f32_16x16x32_bf16 v[72:75], v[162:165], v[210:213], v[72:75]
	v_mfma_f32_16x16x32_bf16 v[116:119], v[166:169], v[182:185], 0
	v_mfma_f32_16x16x32_bf16 v[112:115], v[174:177], v[182:185], 0
	v_mfma_f32_16x16x32_bf16 v[100:103], v[166:169], v[190:193], 0
	v_mfma_f32_16x16x32_bf16 v[96:99], v[174:177], v[190:193], 0
	v_mfma_f32_16x16x32_bf16 v[84:87], v[166:169], v[198:201], 0
	v_mfma_f32_16x16x32_bf16 v[80:83], v[174:177], v[198:201], 0
	v_mfma_f32_16x16x32_bf16 v[68:71], v[166:169], v[206:209], 0
	v_mfma_f32_16x16x32_bf16 v[64:67], v[174:177], v[206:209], 0
	v_mfma_f32_16x16x32_bf16 v[116:119], v[170:173], v[186:189], v[116:119]
	v_mfma_f32_16x16x32_bf16 v[112:115], v[178:181], v[186:189], v[112:115]
	v_mfma_f32_16x16x32_bf16 v[100:103], v[170:173], v[194:197], v[100:103]
	v_mfma_f32_16x16x32_bf16 v[96:99], v[178:181], v[194:197], v[96:99]
	v_mfma_f32_16x16x32_bf16 v[84:87], v[170:173], v[202:205], v[84:87]
	v_mfma_f32_16x16x32_bf16 v[80:83], v[178:181], v[202:205], v[80:83]
	v_mfma_f32_16x16x32_bf16 v[68:71], v[170:173], v[210:213], v[68:71]
	v_mfma_f32_16x16x32_bf16 v[64:67], v[178:181], v[210:213], v[64:67]
	s_barrier
	s_add_u32 s98, s26, s10
	s_addc_u32 s99, s27, s11
	s_add_u32 s100, s28, s10
	s_addc_u32 s101, s29, s11
	s_add_i32 s57, s48, s34
	s_mov_b32 m0, s57
	ds_read_b128 v[182:185], v149 offset:16384
	global_load_lds_dwordx4 v132, s[26:27]
	s_add_i32 m0, s57, 0x2000
	s_add_u32 s60, s26, 0x40000
	s_addc_u32 s61, s27, 0
	s_add_i32 s57, s49, s34
	global_load_lds_dwordx4 v128, s[26:27]
	s_mov_b32 m0, s57
	ds_read_b128 v[186:189], v149 offset:17408
	global_load_lds_dwordx4 v132, s[60:61]
	s_add_i32 m0, s57, 0x2000
	ds_read_b128 v[190:193], v149 offset:18432
	global_load_lds_dwordx4 v128, s[60:61]
	s_mov_b32 m0, s23
	ds_read_b128 v[194:197], v149 offset:19456
	global_load_lds_dwordx4 v134, s[28:29]
	s_mov_b32 m0, s37
	ds_read_b128 v[198:201], v149 offset:20480
	global_load_lds_dwordx4 v130, s[28:29]
	ds_read_b128 v[202:205], v149 offset:21504
	ds_read_b128 v[206:209], v149 offset:22528
	ds_read_b128 v[210:213], v149 offset:23552
	s_waitcnt vmcnt(8) lgkmcnt(0)
	s_barrier
; #define PG8_STAGE(bufoff, gbase, voff) do { _Pragma("unroll") for (int _i = 0; _i < 2; ++_i) \
;         __builtin_amdgcn_global_load_lds((const unsigned*)((const char*)(gbase) + (voff)[_i]), (PG8_LAS unsigned*)(lds + (bufoff) + ldsw + _i * 8192), 16, 0, 0); } while (0)
; #define PG8_LDA(dst, b, h) do { _Pragma("unroll") for (int m = 0; m < 4; ++m) _Pragma("unroll") for (int k = 0; k < 2; ++k) dst[m][k] = *(const PG8_LAS bf16x8*)(lds + PG8_SA(b, h) + aoff + m * 2048 + k * 1024); } while (0)
; #define PG8_LDB(dst, b, h) do { _Pragma("unroll") for (int n = 0; n < 2; ++n) _Pragma("unroll") for (int k = 0; k < 2; ++k) dst[n][k] = *(const PG8_LAS bf16x8*)(lds + PG8_SB(b, h) + boff + n * 2048 + k * 1024); } while (0)
; #define PG8_MMA(ai, bj, At, Bt) do { __builtin_amdgcn_s_setprio(1); _Pragma("unroll") for (int m = 0; m < 4; ++m) _Pragma("unroll") for (int n = 0; n < 2; ++n) _Pragma("unroll") for (int k = 0; k < 2; ++k) \
;         acc[ai][bj][m][n] = __builtin_amdgcn_mfma_f32_16x16x32_bf16(Bt[n][k], At[m][k], acc[ai][bj][m][n], 0, 0, 0); __builtin_amdgcn_s_setprio(0); } while (0)
; #define PG8_WAIT_V(n) asm volatile("s_waitcnt vmcnt(" #n ")" ::: "memory")
; #define PG8_WAIT_L(n) asm volatile("s_waitcnt lgkmcnt(" #n ")" ::: "memory")
; #define PG8_BAR __builtin_amdgcn_s_barrier()
; #define PG8_SCHED __builtin_amdgcn_sched_barrier(0)
; template <class Epi, class Sched, bool ALIGN_EPI = false, bool SP2 = false>
; __device__ __forceinline__ void gemm_phase(PG8_LAS unsigned char* lds, const Gemm g, const Sched& S, const Epi& E, int tid_in) {
;     ...
;             PG8_WAIT_V(8); PG8_WAIT_L(0); PG8_BAR; PG8_MMA(1, 0, At, B0); PG8_MMA(1, 1, At, B1); PG8_BAR; PG8_SCHED;
;             PG8_LDB(B0, 1, 0); PG8_LDB(B1, 1, 1); PG8_SCHED; PG8_LDA(At, 1, 0); PG8_STAGE(PG8_SA(0, 1), a2 + hstep, voffA);
;             PG8_WAIT_V(8); PG8_WAIT_L(0); PG8_BAR; PG8_MMA(0, 0, At, B0); PG8_MMA(0, 1, At, B1); PG8_BAR; PG8_SCHED;
	v_mfma_f32_16x16x32_bf16 v[60:63], v[150:153], v[182:185], 0
	v_mfma_f32_16x16x32_bf16 v[56:59], v[158:161], v[182:185], 0
	v_mfma_f32_16x16x32_bf16 v[44:47], v[150:153], v[190:193], 0
	v_mfma_f32_16x16x32_bf16 v[40:43], v[158:161], v[190:193], 0
	v_mfma_f32_16x16x32_bf16 v[28:31], v[150:153], v[198:201], 0
	v_mfma_f32_16x16x32_bf16 v[24:27], v[158:161], v[198:201], 0
	v_mfma_f32_16x16x32_bf16 v[12:15], v[150:153], v[206:209], 0
	v_mfma_f32_16x16x32_bf16 v[8:11], v[158:161], v[206:209], 0
	v_mfma_f32_16x16x32_bf16 v[60:63], v[154:157], v[186:189], v[60:63]
	v_mfma_f32_16x16x32_bf16 v[56:59], v[162:165], v[186:189], v[56:59]
	v_mfma_f32_16x16x32_bf16 v[44:47], v[154:157], v[194:197], v[44:47]
	v_mfma_f32_16x16x32_bf16 v[40:43], v[162:165], v[194:197], v[40:43]
	v_mfma_f32_16x16x32_bf16 v[28:31], v[154:157], v[202:205], v[28:31]
	v_mfma_f32_16x16x32_bf16 v[24:27], v[162:165], v[202:205], v[24:27]
	v_mfma_f32_16x16x32_bf16 v[12:15], v[154:157], v[210:213], v[12:15]
	v_mfma_f32_16x16x32_bf16 v[8:11], v[162:165], v[210:213], v[8:11]
	v_mfma_f32_16x16x32_bf16 v[52:55], v[166:169], v[182:185], 0
	v_mfma_f32_16x16x32_bf16 v[48:51], v[174:177], v[182:185], 0
	v_mfma_f32_16x16x32_bf16 v[36:39], v[166:169], v[190:193], 0
	v_mfma_f32_16x16x32_bf16 v[32:35], v[174:177], v[190:193], 0
	v_mfma_f32_16x16x32_bf16 v[20:23], v[166:169], v[198:201], 0
	v_mfma_f32_16x16x32_bf16 v[16:19], v[174:177], v[198:201], 0
	v_mfma_f32_16x16x32_bf16 v[4:7], v[166:169], v[206:209], 0
	v_mfma_f32_16x16x32_bf16 v[0:3], v[174:177], v[206:209], 0
	v_mfma_f32_16x16x32_bf16 v[52:55], v[170:173], v[186:189], v[52:55]
	v_mfma_f32_16x16x32_bf16 v[48:51], v[178:181], v[186:189], v[48:51]
	v_mfma_f32_16x16x32_bf16 v[36:39], v[170:173], v[194:197], v[36:39]
	v_mfma_f32_16x16x32_bf16 v[32:35], v[178:181], v[194:197], v[32:35]
	v_mfma_f32_16x16x32_bf16 v[20:23], v[170:173], v[202:205], v[20:23]
	v_mfma_f32_16x16x32_bf16 v[16:19], v[178:181], v[202:205], v[16:19]
	v_mfma_f32_16x16x32_bf16 v[4:7], v[170:173], v[210:213], v[4:7]
	v_mfma_f32_16x16x32_bf16 v[0:3], v[178:181], v[210:213], v[0:3]
	s_barrier
	s_add_i32 s57, 0, 0x18000
	s_add_i32 s59, 0, 0x1c000
	s_add_u32 s28, s28, 0x40000
	s_addc_u32 s29, s29, 0
	s_mov_b32 m0, s38
	s_nop 0
	global_load_lds_dwordx4 v134, s[28:29]
	s_mov_b32 m0, s39
	s_nop 0
	global_load_lds_dwordx4 v130, s[28:29]
	v_add_u32_e32 v162, s57, v145
	v_add_u32_e32 v178, s59, v145
	ds_read_b128 v[150:153], v162
	ds_read_b128 v[154:157], v162 offset:1024
	ds_read_b128 v[158:161], v162 offset:2048
	ds_read_b128 v[162:165], v162 offset:3072
	ds_read_b128 v[166:169], v178
	ds_read_b128 v[170:173], v178 offset:1024
	ds_read_b128 v[174:177], v178 offset:2048
	ds_read_b128 v[178:181], v178 offset:3072
	ds_read_b128 v[182:185], v149 offset:32768
	ds_read_b128 v[186:189], v149 offset:33792
	ds_read_b128 v[190:193], v149 offset:34816
	ds_read_b128 v[194:197], v149 offset:35840
	ds_read_b128 v[198:201], v149 offset:36864
	ds_read_b128 v[202:205], v149 offset:37888
	ds_read_b128 v[206:209], v149 offset:38912
	ds_read_b128 v[210:213], v149 offset:39936
	s_waitcnt vmcnt(8) lgkmcnt(0)
	s_barrier
	v_mfma_f32_16x16x32_bf16 v[124:127], v[150:153], v[182:185], v[124:127]
	v_mfma_f32_16x16x32_bf16 v[120:123], v[158:161], v[182:185], v[120:123]
	v_mfma_f32_16x16x32_bf16 v[108:111], v[150:153], v[190:193], v[108:111]
	v_mfma_f32_16x16x32_bf16 v[104:107], v[158:161], v[190:193], v[104:107]
	v_mfma_f32_16x16x32_bf16 v[92:95], v[150:153], v[198:201], v[92:95]
	v_mfma_f32_16x16x32_bf16 v[88:91], v[158:161], v[198:201], v[88:91]
	v_mfma_f32_16x16x32_bf16 v[76:79], v[150:153], v[206:209], v[76:79]
	v_mfma_f32_16x16x32_bf16 v[72:75], v[158:161], v[206:209], v[72:75]
	v_mfma_f32_16x16x32_bf16 v[124:127], v[154:157], v[186:189], v[124:127]
	v_mfma_f32_16x16x32_bf16 v[120:123], v[162:165], v[186:189], v[120:123]
	v_mfma_f32_16x16x32_bf16 v[108:111], v[154:157], v[194:197], v[108:111]
	v_mfma_f32_16x16x32_bf16 v[104:107], v[162:165], v[194:197], v[104:107]
	v_mfma_f32_16x16x32_bf16 v[92:95], v[154:157], v[202:205], v[92:95]
	v_mfma_f32_16x16x32_bf16 v[88:91], v[162:165], v[202:205], v[88:91]
	v_mfma_f32_16x16x32_bf16 v[76:79], v[154:157], v[210:213], v[76:79]
	v_mfma_f32_16x16x32_bf16 v[72:75], v[162:165], v[210:213], v[72:75]
	v_mfma_f32_16x16x32_bf16 v[116:119], v[166:169], v[182:185], v[116:119]
	v_mfma_f32_16x16x32_bf16 v[112:115], v[174:177], v[182:185], v[112:115]
	v_mfma_f32_16x16x32_bf16 v[100:103], v[166:169], v[190:193], v[100:103]
	v_mfma_f32_16x16x32_bf16 v[96:99], v[174:177], v[190:193], v[96:99]
	v_mfma_f32_16x16x32_bf16 v[84:87], v[166:169], v[198:201], v[84:87]
	v_mfma_f32_16x16x32_bf16 v[80:83], v[174:177], v[198:201], v[80:83]
	v_mfma_f32_16x16x32_bf16 v[68:71], v[166:169], v[206:209], v[68:71]
	v_mfma_f32_16x16x32_bf16 v[64:67], v[174:177], v[206:209], v[64:67]
	v_mfma_f32_16x16x32_bf16 v[116:119], v[170:173], v[186:189], v[116:119]
	v_mfma_f32_16x16x32_bf16 v[112:115], v[178:181], v[186:189], v[112:115]
	v_mfma_f32_16x16x32_bf16 v[100:103], v[170:173], v[194:197], v[100:103]
	v_mfma_f32_16x16x32_bf16 v[96:99], v[178:181], v[194:197], v[96:99]
	v_mfma_f32_16x16x32_bf16 v[84:87], v[170:173], v[202:205], v[84:87]
	v_mfma_f32_16x16x32_bf16 v[80:83], v[178:181], v[202:205], v[80:83]
	v_mfma_f32_16x16x32_bf16 v[68:71], v[170:173], v[210:213], v[68:71]
	v_mfma_f32_16x16x32_bf16 v[64:67], v[178:181], v[210:213], v[64:67]
	s_barrier
; #define PG8_STAGE(bufoff, gbase, voff) do { _Pragma("unroll") for (int _i = 0; _i < 2; ++_i) \
;         __builtin_amdgcn_global_load_lds((const unsigned*)((const char*)(gbase) + (voff)[_i]), (PG8_LAS unsigned*)(lds + (bufoff) + ldsw + _i * 8192), 16, 0, 0); } while (0)
; #define PG8_LDA(dst, b, h) do { _Pragma("unroll") for (int m = 0; m < 4; ++m) _Pragma("unroll") for (int k = 0; k < 2; ++k) dst[m][k] = *(const PG8_LAS bf16x8*)(lds + PG8_SA(b, h) + aoff + m * 2048 + k * 1024); } while (0)
; #define PG8_LDB(dst, b, h) do { _Pragma("unroll") for (int n = 0; n < 2; ++n) _Pragma("unroll") for (int k = 0; k < 2; ++k) dst[n][k] = *(const PG8_LAS bf16x8*)(lds + PG8_SB(b, h) + boff + n * 2048 + k * 1024); } while (0)
; #define PG8_WAIT_V(n) asm volatile("s_waitcnt vmcnt(" #n ")" ::: "memory")
; #define PG8_BAR __builtin_amdgcn_s_barrier()
; template <class Epi, class Sched, bool ALIGN_EPI = false, bool SP2 = false>
; __device__ __forceinline__ void gemm_phase(PG8_LAS unsigned char* lds, const Gemm g, const Sched& S, const Epi& E, int tid_in) {
;     ...
;             const char* a2 = last ? nA : cA + (size_t)(t + 2) * kstep; const char* b2 = last ? nB : cB + (size_t)(t + 2) * kstep;
;             const char* a3 = a2 + kstep; const char* b3 = b2 + kstep;
;             if (last && has_next) S.a_ready(nxt);
;             if constexpr (SP2) {
;             PG8_LDB(B0, 0, 0); PG8_LDB(B1, 0, 1); PG8_SCHED; PG8_LDA(At, 0, 0); PG8_STAGE(PG8_SA(1, 1), a1 + hstep, voffA);
;             PG8_WAIT_V(8); PG8_WAIT_L(0); PG8_BAR; PG8_MMA(0, 0, At, B0); PG8_MMA(0, 1, At, B1); PG8_BAR; PG8_SCHED;
;             PG8_LDA(At, 0, 1); PG8_STAGE(PG8_SB(0, 0), b2, voffB); PG8_STAGE(PG8_SB(0, 1), b2 + hstep, voffB); PG8_STAGE(PG8_SA(0, 0), a2, voffA);
;             PG8_WAIT_V(8); PG8_WAIT_L(0); PG8_BAR; PG8_MMA(1, 0, At, B0); PG8_MMA(1, 1, At, B1); PG8_BAR; PG8_SCHED;
;             PG8_LDB(B0, 1, 0); PG8_LDB(B1, 1, 1); PG8_SCHED; PG8_LDA(At, 1, 0); PG8_STAGE(PG8_SA(0, 1), a2 + hstep, voffA);
;             PG8_WAIT_V(8); PG8_WAIT_L(0); PG8_BAR; PG8_MMA(0, 0, At, B0); PG8_MMA(0, 1, At, B1); PG8_BAR; PG8_SCHED;
;             PG8_LDA(At, 1, 1); PG8_STAGE(PG8_SB(1, 0), b3, voffB); PG8_STAGE(PG8_SB(1, 1), b3 + hstep, voffB); PG8_STAGE(PG8_SA(1, 0), a3, voffA);
;             PG8_WAIT_V(8); PG8_WAIT_L(0); PG8_BAR; PG8_MMA(1, 0, At, B0); PG8_MMA(1, 1, At, B1); PG8_BAR; PG8_SCHED;
	s_add_i32 s28, s57, s34
	s_mov_b32 m0, s28
	ds_read_b128 v[182:185], v149 offset:49152
	global_load_lds_dwordx4 v132, s[98:99]
	s_add_i32 m0, s28, 0x2000
	s_add_u32 s26, s26, 0x40080
	s_addc_u32 s27, s27, 0
	s_add_i32 s28, s59, s34
	global_load_lds_dwordx4 v128, s[98:99]
	s_mov_b32 m0, s28
	ds_read_b128 v[186:189], v149 offset:50176
	global_load_lds_dwordx4 v132, s[26:27]
	s_add_i32 m0, s28, 0x2000
	ds_read_b128 v[190:193], v149 offset:51200
	global_load_lds_dwordx4 v128, s[26:27]
	s_mov_b32 m0, s44
	ds_read_b128 v[194:197], v149 offset:52224
	global_load_lds_dwordx4 v134, s[100:101]
	s_mov_b32 m0, s45
	ds_read_b128 v[198:201], v149 offset:53248
	global_load_lds_dwordx4 v130, s[100:101]
	ds_read_b128 v[202:205], v149 offset:54272
	ds_read_b128 v[206:209], v149 offset:55296
	ds_read_b128 v[210:213], v149 offset:56320
	s_waitcnt vmcnt(8) lgkmcnt(0)
	s_barrier
	v_mfma_f32_16x16x32_bf16 v[60:63], v[150:153], v[182:185], v[60:63]
	v_mfma_f32_16x16x32_bf16 v[56:59], v[158:161], v[182:185], v[56:59]
	v_mfma_f32_16x16x32_bf16 v[44:47], v[150:153], v[190:193], v[44:47]
	v_mfma_f32_16x16x32_bf16 v[40:43], v[158:161], v[190:193], v[40:43]
	v_mfma_f32_16x16x32_bf16 v[28:31], v[150:153], v[198:201], v[28:31]
	v_mfma_f32_16x16x32_bf16 v[24:27], v[158:161], v[198:201], v[24:27]
	v_mfma_f32_16x16x32_bf16 v[12:15], v[150:153], v[206:209], v[12:15]
	v_mfma_f32_16x16x32_bf16 v[8:11], v[158:161], v[206:209], v[8:11]
	v_mfma_f32_16x16x32_bf16 v[60:63], v[154:157], v[186:189], v[60:63]
	v_mfma_f32_16x16x32_bf16 v[56:59], v[162:165], v[186:189], v[56:59]
	v_mfma_f32_16x16x32_bf16 v[44:47], v[154:157], v[194:197], v[44:47]
	v_mfma_f32_16x16x32_bf16 v[40:43], v[162:165], v[194:197], v[40:43]
	v_mfma_f32_16x16x32_bf16 v[28:31], v[154:157], v[202:205], v[28:31]
	v_mfma_f32_16x16x32_bf16 v[24:27], v[162:165], v[202:205], v[24:27]
	v_mfma_f32_16x16x32_bf16 v[12:15], v[154:157], v[210:213], v[12:15]
	v_mfma_f32_16x16x32_bf16 v[8:11], v[162:165], v[210:213], v[8:11]
	v_mfma_f32_16x16x32_bf16 v[52:55], v[166:169], v[182:185], v[52:55]
	v_mfma_f32_16x16x32_bf16 v[48:51], v[174:177], v[182:185], v[48:51]
	v_mfma_f32_16x16x32_bf16 v[36:39], v[166:169], v[190:193], v[36:39]
	v_mfma_f32_16x16x32_bf16 v[32:35], v[174:177], v[190:193], v[32:35]
	v_mfma_f32_16x16x32_bf16 v[20:23], v[166:169], v[198:201], v[20:23]
	v_mfma_f32_16x16x32_bf16 v[16:19], v[174:177], v[198:201], v[16:19]
	v_mfma_f32_16x16x32_bf16 v[4:7], v[166:169], v[206:209], v[4:7]
	v_mfma_f32_16x16x32_bf16 v[0:3], v[174:177], v[206:209], v[0:3]
	v_mfma_f32_16x16x32_bf16 v[52:55], v[170:173], v[186:189], v[52:55]
	v_mfma_f32_16x16x32_bf16 v[48:51], v[178:181], v[186:189], v[48:51]
	v_mfma_f32_16x16x32_bf16 v[36:39], v[170:173], v[194:197], v[36:39]
	v_mfma_f32_16x16x32_bf16 v[32:35], v[178:181], v[194:197], v[32:35]
	v_mfma_f32_16x16x32_bf16 v[20:23], v[170:173], v[202:205], v[20:23]
	v_mfma_f32_16x16x32_bf16 v[16:19], v[178:181], v[202:205], v[16:19]
	v_mfma_f32_16x16x32_bf16 v[4:7], v[170:173], v[210:213], v[4:7]
	v_mfma_f32_16x16x32_bf16 v[0:3], v[178:181], v[210:213], v[0:3]
	s_barrier
	s_add_i32 s56, s56, 2
	s_add_u32 s24, s24, 0x100
	s_addc_u32 s25, s25, 0
	s_add_u32 s54, s54, 0x100
	s_addc_u32 s55, s55, 0
.LBB0_376:
	s_add_u32 s26, s24, 0xfffc0080
	s_addc_u32 s27, s25, -1
	s_cmp_eq_u32 s56, 12
	s_cselect_b32 s29, s17, s27
	s_cselect_b32 s28, s52, s26
	s_cselect_b32 s27, s15, s55
	s_cselect_b32 s26, s53, s54
	s_add_i32 m0, s23, 0xc000
	ds_read_b128 v[150:153], v147
	global_load_lds_dwordx4 v136, s[24:25]
	s_add_i32 m0, s23, 0xe000
	ds_read_b128 v[154:157], v147 offset:1024
	global_load_lds_dwordx4 v138, s[24:25]
	ds_read_b128 v[158:161], v147 offset:2048
	ds_read_b128 v[162:165], v147 offset:3072
	ds_read_b128 v[166:169], v148
	ds_read_b128 v[170:173], v148 offset:1024
	ds_read_b128 v[174:177], v148 offset:2048
	ds_read_b128 v[178:181], v148 offset:3072
	ds_read_b128 v[182:185], v149
	ds_read_b128 v[186:189], v149 offset:1024
	ds_read_b128 v[190:193], v149 offset:2048
	ds_read_b128 v[194:197], v149 offset:3072
	ds_read_b128 v[198:201], v149 offset:4096
	ds_read_b128 v[202:205], v149 offset:5120
	ds_read_b128 v[206:209], v149 offset:6144
	ds_read_b128 v[210:213], v149 offset:7168
	s_waitcnt vmcnt(8) lgkmcnt(0)
	s_barrier
	v_mfma_f32_16x16x32_bf16 v[124:127], v[150:153], v[182:185], v[124:127]
	v_mfma_f32_16x16x32_bf16 v[120:123], v[158:161], v[182:185], v[120:123]
	v_mfma_f32_16x16x32_bf16 v[108:111], v[150:153], v[190:193], v[108:111]
	v_mfma_f32_16x16x32_bf16 v[104:107], v[158:161], v[190:193], v[104:107]
	v_mfma_f32_16x16x32_bf16 v[92:95], v[150:153], v[198:201], v[92:95]
	v_mfma_f32_16x16x32_bf16 v[88:91], v[158:161], v[198:201], v[88:91]
	v_mfma_f32_16x16x32_bf16 v[76:79], v[150:153], v[206:209], v[76:79]
	v_mfma_f32_16x16x32_bf16 v[72:75], v[158:161], v[206:209], v[72:75]
	v_mfma_f32_16x16x32_bf16 v[124:127], v[154:157], v[186:189], v[124:127]
	v_mfma_f32_16x16x32_bf16 v[120:123], v[162:165], v[186:189], v[120:123]
	v_mfma_f32_16x16x32_bf16 v[108:111], v[154:157], v[194:197], v[108:111]
	v_mfma_f32_16x16x32_bf16 v[104:107], v[162:165], v[194:197], v[104:107]
	v_mfma_f32_16x16x32_bf16 v[92:95], v[154:157], v[202:205], v[92:95]
	v_mfma_f32_16x16x32_bf16 v[88:91], v[162:165], v[202:205], v[88:91]
	v_mfma_f32_16x16x32_bf16 v[76:79], v[154:157], v[210:213], v[76:79]
	v_mfma_f32_16x16x32_bf16 v[72:75], v[162:165], v[210:213], v[72:75]
	v_mfma_f32_16x16x32_bf16 v[116:119], v[166:169], v[182:185], v[116:119]
	v_mfma_f32_16x16x32_bf16 v[112:115], v[174:177], v[182:185], v[112:115]
	v_mfma_f32_16x16x32_bf16 v[100:103], v[166:169], v[190:193], v[100:103]
	v_mfma_f32_16x16x32_bf16 v[96:99], v[174:177], v[190:193], v[96:99]
	v_mfma_f32_16x16x32_bf16 v[84:87], v[166:169], v[198:201], v[84:87]
	v_mfma_f32_16x16x32_bf16 v[80:83], v[174:177], v[198:201], v[80:83]
	v_mfma_f32_16x16x32_bf16 v[68:71], v[166:169], v[206:209], v[68:71]
	v_mfma_f32_16x16x32_bf16 v[64:67], v[174:177], v[206:209], v[64:67]
	v_mfma_f32_16x16x32_bf16 v[116:119], v[170:173], v[186:189], v[116:119]
	v_mfma_f32_16x16x32_bf16 v[112:115], v[178:181], v[186:189], v[112:115]
	v_mfma_f32_16x16x32_bf16 v[100:103], v[170:173], v[194:197], v[100:103]
	v_mfma_f32_16x16x32_bf16 v[96:99], v[178:181], v[194:197], v[96:99]
	v_mfma_f32_16x16x32_bf16 v[84:87], v[170:173], v[202:205], v[84:87]
	v_mfma_f32_16x16x32_bf16 v[80:83], v[178:181], v[202:205], v[80:83]
	v_mfma_f32_16x16x32_bf16 v[68:71], v[170:173], v[210:213], v[68:71]
	v_mfma_f32_16x16x32_bf16 v[64:67], v[178:181], v[210:213], v[64:67]
	s_barrier
; #define PG8_STAGE(bufoff, gbase, voff) do { _Pragma("unroll") for (int _i = 0; _i < 2; ++_i) \
;         __builtin_amdgcn_global_load_lds((const unsigned*)((const char*)(gbase) + (voff)[_i]), (PG8_LAS unsigned*)(lds + (bufoff) + ldsw + _i * 8192), 16, 0, 0); } while (0)
; #define PG8_LDA(dst, b, h) do { _Pragma("unroll") for (int m = 0; m < 4; ++m) _Pragma("unroll") for (int k = 0; k < 2; ++k) dst[m][k] = *(const PG8_LAS bf16x8*)(lds + PG8_SA(b, h) + aoff + m * 2048 + k * 1024); } while (0)
; #define PG8_LDB(dst, b, h) do { _Pragma("unroll") for (int n = 0; n < 2; ++n) _Pragma("unroll") for (int k = 0; k < 2; ++k) dst[n][k] = *(const PG8_LAS bf16x8*)(lds + PG8_SB(b, h) + boff + n * 2048 + k * 1024); } while (0)
; #define PG8_MMA(ai, bj, At, Bt) do { __builtin_amdgcn_s_setprio(1); _Pragma("unroll") for (int m = 0; m < 4; ++m) _Pragma("unroll") for (int n = 0; n < 2; ++n) _Pragma("unroll") for (int k = 0; k < 2; ++k) \
;         acc[ai][bj][m][n] = __builtin_amdgcn_mfma_f32_16x16x32_bf16(Bt[n][k], At[m][k], acc[ai][bj][m][n], 0, 0, 0); __builtin_amdgcn_s_setprio(0); } while (0)
; #define PG8_WAIT_V(n) asm volatile("s_waitcnt vmcnt(" #n ")" ::: "memory")
; #define PG8_WAIT_L(n) asm volatile("s_waitcnt lgkmcnt(" #n ")" ::: "memory")
; #define PG8_BAR __builtin_amdgcn_s_barrier()
; #define PG8_SCHED __builtin_amdgcn_sched_barrier(0)
; template <class Epi, class Sched, bool ALIGN_EPI = false, bool SP2 = false>
; __device__ __forceinline__ void gemm_phase(PG8_LAS unsigned char* lds, const Gemm g, const Sched& S, const Epi& E, int tid_in) {
;     ...
;             PG8_LDA(At, 0, 1); PG8_STAGE(PG8_SB(0, 0), b2, voffB); PG8_STAGE(PG8_SB(0, 1), b2 + hstep, voffB); PG8_STAGE(PG8_SA(0, 0), a2, voffA);
;             PG8_WAIT_V(8); PG8_WAIT_L(0); PG8_BAR; PG8_MMA(1, 0, At, B0); PG8_MMA(1, 1, At, B1); PG8_BAR; PG8_SCHED;
;             PG8_LDB(B0, 1, 0); PG8_LDB(B1, 1, 1); PG8_SCHED; PG8_LDA(At, 1, 0); PG8_STAGE(PG8_SA(0, 1), a2 + hstep, voffA);
	s_add_u32 s98, s26, s10
	s_addc_u32 s99, s27, s11
	s_add_u32 s100, s28, s10
	s_addc_u32 s101, s29, s11
	s_add_i32 s57, s48, s34
	s_mov_b32 m0, s57
	ds_read_b128 v[182:185], v149 offset:16384
	global_load_lds_dwordx4 v132, s[26:27]
	s_add_i32 m0, s57, 0x2000
	s_add_u32 s60, s26, 0x40000
	s_addc_u32 s61, s27, 0
	s_add_i32 s57, s49, s34
	global_load_lds_dwordx4 v128, s[26:27]
	s_mov_b32 m0, s57
	ds_read_b128 v[186:189], v149 offset:17408
	global_load_lds_dwordx4 v132, s[60:61]
	s_add_i32 m0, s57, 0x2000
	ds_read_b128 v[190:193], v149 offset:18432
	global_load_lds_dwordx4 v128, s[60:61]
	s_mov_b32 m0, s23
	ds_read_b128 v[194:197], v149 offset:19456
	global_load_lds_dwordx4 v134, s[28:29]
	s_mov_b32 m0, s37
	ds_read_b128 v[198:201], v149 offset:20480
	global_load_lds_dwordx4 v130, s[28:29]
	ds_read_b128 v[202:205], v149 offset:21504
	ds_read_b128 v[206:209], v149 offset:22528
	ds_read_b128 v[210:213], v149 offset:23552
	s_waitcnt vmcnt(8) lgkmcnt(0)
	s_barrier
	v_mfma_f32_16x16x32_bf16 v[60:63], v[150:153], v[182:185], v[60:63]
	v_mfma_f32_16x16x32_bf16 v[56:59], v[158:161], v[182:185], v[56:59]
	v_mfma_f32_16x16x32_bf16 v[44:47], v[150:153], v[190:193], v[44:47]
	v_mfma_f32_16x16x32_bf16 v[40:43], v[158:161], v[190:193], v[40:43]
	v_mfma_f32_16x16x32_bf16 v[28:31], v[150:153], v[198:201], v[28:31]
	v_mfma_f32_16x16x32_bf16 v[24:27], v[158:161], v[198:201], v[24:27]
	v_mfma_f32_16x16x32_bf16 v[12:15], v[150:153], v[206:209], v[12:15]
	v_mfma_f32_16x16x32_bf16 v[8:11], v[158:161], v[206:209], v[8:11]
	v_mfma_f32_16x16x32_bf16 v[60:63], v[154:157], v[186:189], v[60:63]
	v_mfma_f32_16x16x32_bf16 v[56:59], v[162:165], v[186:189], v[56:59]
	v_mfma_f32_16x16x32_bf16 v[44:47], v[154:157], v[194:197], v[44:47]
	v_mfma_f32_16x16x32_bf16 v[40:43], v[162:165], v[194:197], v[40:43]
	v_mfma_f32_16x16x32_bf16 v[28:31], v[154:157], v[202:205], v[28:31]
	v_mfma_f32_16x16x32_bf16 v[24:27], v[162:165], v[202:205], v[24:27]
	v_mfma_f32_16x16x32_bf16 v[12:15], v[154:157], v[210:213], v[12:15]
	v_mfma_f32_16x16x32_bf16 v[8:11], v[162:165], v[210:213], v[8:11]
	v_mfma_f32_16x16x32_bf16 v[52:55], v[166:169], v[182:185], v[52:55]
	v_mfma_f32_16x16x32_bf16 v[48:51], v[174:177], v[182:185], v[48:51]
	v_mfma_f32_16x16x32_bf16 v[36:39], v[166:169], v[190:193], v[36:39]
	v_mfma_f32_16x16x32_bf16 v[32:35], v[174:177], v[190:193], v[32:35]
	v_mfma_f32_16x16x32_bf16 v[20:23], v[166:169], v[198:201], v[20:23]
	v_mfma_f32_16x16x32_bf16 v[16:19], v[174:177], v[198:201], v[16:19]
	v_mfma_f32_16x16x32_bf16 v[4:7], v[166:169], v[206:209], v[4:7]
	v_mfma_f32_16x16x32_bf16 v[0:3], v[174:177], v[206:209], v[0:3]
	v_mfma_f32_16x16x32_bf16 v[52:55], v[170:173], v[186:189], v[52:55]
	v_mfma_f32_16x16x32_bf16 v[48:51], v[178:181], v[186:189], v[48:51]
	v_mfma_f32_16x16x32_bf16 v[36:39], v[170:173], v[194:197], v[36:39]
	v_mfma_f32_16x16x32_bf16 v[32:35], v[178:181], v[194:197], v[32:35]
	v_mfma_f32_16x16x32_bf16 v[20:23], v[170:173], v[202:205], v[20:23]
	v_mfma_f32_16x16x32_bf16 v[16:19], v[178:181], v[202:205], v[16:19]
	v_mfma_f32_16x16x32_bf16 v[4:7], v[170:173], v[210:213], v[4:7]
	v_mfma_f32_16x16x32_bf16 v[0:3], v[178:181], v[210:213], v[0:3]
	s_barrier
	s_add_i32 s57, 0, 0x18000
	s_add_i32 s59, 0, 0x1c000
	s_add_u32 s28, s28, 0x40000
	s_addc_u32 s29, s29, 0
	s_mov_b32 m0, s38
	s_nop 0
	global_load_lds_dwordx4 v134, s[28:29]
	s_mov_b32 m0, s39
	s_nop 0
	global_load_lds_dwordx4 v130, s[28:29]
	v_add_u32_e32 v162, s57, v145
	v_add_u32_e32 v178, s59, v145
	ds_read_b128 v[150:153], v162
	ds_read_b128 v[154:157], v162 offset:1024
	ds_read_b128 v[158:161], v162 offset:2048
	ds_read_b128 v[162:165], v162 offset:3072
	ds_read_b128 v[166:169], v178
	ds_read_b128 v[170:173], v178 offset:1024
	ds_read_b128 v[174:177], v178 offset:2048
	ds_read_b128 v[178:181], v178 offset:3072
	ds_read_b128 v[182:185], v149 offset:32768
	ds_read_b128 v[186:189], v149 offset:33792
	ds_read_b128 v[190:193], v149 offset:34816
	ds_read_b128 v[194:197], v149 offset:35840
	ds_read_b128 v[198:201], v149 offset:36864
	ds_read_b128 v[202:205], v149 offset:37888
	ds_read_b128 v[206:209], v149 offset:38912
	ds_read_b128 v[210:213], v149 offset:39936
	s_waitcnt vmcnt(8) lgkmcnt(0)
	s_barrier
; #define PG8_STAGE(bufoff, gbase, voff) do { _Pragma("unroll") for (int _i = 0; _i < 2; ++_i) \
;         __builtin_amdgcn_global_load_lds((const unsigned*)((const char*)(gbase) + (voff)[_i]), (PG8_LAS unsigned*)(lds + (bufoff) + ldsw + _i * 8192), 16, 0, 0); } while (0)
; #define PG8_LDA(dst, b, h) do { _Pragma("unroll") for (int m = 0; m < 4; ++m) _Pragma("unroll") for (int k = 0; k < 2; ++k) dst[m][k] = *(const PG8_LAS bf16x8*)(lds + PG8_SA(b, h) + aoff + m * 2048 + k * 1024); } while (0)
; #define PG8_MMA(ai, bj, At, Bt) do { __builtin_amdgcn_s_setprio(1); _Pragma("unroll") for (int m = 0; m < 4; ++m) _Pragma("unroll") for (int n = 0; n < 2; ++n) _Pragma("unroll") for (int k = 0; k < 2; ++k) \
;         acc[ai][bj][m][n] = __builtin_amdgcn_mfma_f32_16x16x32_bf16(Bt[n][k], At[m][k], acc[ai][bj][m][n], 0, 0, 0); __builtin_amdgcn_s_setprio(0); } while (0)
; #define PG8_WAIT_V(n) asm volatile("s_waitcnt vmcnt(" #n ")" ::: "memory")
; #define PG8_WAIT_L(n) asm volatile("s_waitcnt lgkmcnt(" #n ")" ::: "memory")
; #define PG8_BAR __builtin_amdgcn_s_barrier()
; #define PG8_SCHED __builtin_amdgcn_sched_barrier(0)
; template <class Epi, class Sched, bool ALIGN_EPI = false, bool SP2 = false>
; __device__ __forceinline__ void gemm_phase(PG8_LAS unsigned char* lds, const Gemm g, const Sched& S, const Epi& E, int tid_in) {
;     ...
;             PG8_WAIT_V(8); PG8_WAIT_L(0); PG8_BAR; PG8_MMA(0, 0, At, B0); PG8_MMA(0, 1, At, B1); PG8_BAR; PG8_SCHED;
;             PG8_LDA(At, 1, 1); PG8_STAGE(PG8_SB(1, 0), b3, voffB); PG8_STAGE(PG8_SB(1, 1), b3 + hstep, voffB); PG8_STAGE(PG8_SA(1, 0), a3, voffA);
;             PG8_WAIT_V(8); PG8_WAIT_L(0); PG8_BAR; PG8_MMA(1, 0, At, B0); PG8_MMA(1, 1, At, B1); PG8_BAR; PG8_SCHED;
;     ...
;         if constexpr (ALIGN_EPI) { if (wr == 0) PG8_BAR; }
	v_mfma_f32_16x16x32_bf16 v[124:127], v[150:153], v[182:185], v[124:127]
	v_mfma_f32_16x16x32_bf16 v[120:123], v[158:161], v[182:185], v[120:123]
	v_mfma_f32_16x16x32_bf16 v[108:111], v[150:153], v[190:193], v[108:111]
	v_mfma_f32_16x16x32_bf16 v[104:107], v[158:161], v[190:193], v[104:107]
	v_mfma_f32_16x16x32_bf16 v[92:95], v[150:153], v[198:201], v[92:95]
	v_mfma_f32_16x16x32_bf16 v[88:91], v[158:161], v[198:201], v[88:91]
	v_mfma_f32_16x16x32_bf16 v[76:79], v[150:153], v[206:209], v[76:79]
	v_mfma_f32_16x16x32_bf16 v[72:75], v[158:161], v[206:209], v[72:75]
	v_mfma_f32_16x16x32_bf16 v[124:127], v[154:157], v[186:189], v[124:127]
	v_mfma_f32_16x16x32_bf16 v[120:123], v[162:165], v[186:189], v[120:123]
	v_mfma_f32_16x16x32_bf16 v[108:111], v[154:157], v[194:197], v[108:111]
	v_mfma_f32_16x16x32_bf16 v[104:107], v[162:165], v[194:197], v[104:107]
	v_mfma_f32_16x16x32_bf16 v[92:95], v[154:157], v[202:205], v[92:95]
	v_mfma_f32_16x16x32_bf16 v[88:91], v[162:165], v[202:205], v[88:91]
	v_mfma_f32_16x16x32_bf16 v[76:79], v[154:157], v[210:213], v[76:79]
	v_mfma_f32_16x16x32_bf16 v[72:75], v[162:165], v[210:213], v[72:75]
	v_mfma_f32_16x16x32_bf16 v[116:119], v[166:169], v[182:185], v[116:119]
	v_mfma_f32_16x16x32_bf16 v[112:115], v[174:177], v[182:185], v[112:115]
	v_mfma_f32_16x16x32_bf16 v[100:103], v[166:169], v[190:193], v[100:103]
	v_mfma_f32_16x16x32_bf16 v[96:99], v[174:177], v[190:193], v[96:99]
	v_mfma_f32_16x16x32_bf16 v[84:87], v[166:169], v[198:201], v[84:87]
	v_mfma_f32_16x16x32_bf16 v[80:83], v[174:177], v[198:201], v[80:83]
	v_mfma_f32_16x16x32_bf16 v[68:71], v[166:169], v[206:209], v[68:71]
	v_mfma_f32_16x16x32_bf16 v[64:67], v[174:177], v[206:209], v[64:67]
	v_mfma_f32_16x16x32_bf16 v[116:119], v[170:173], v[186:189], v[116:119]
	v_mfma_f32_16x16x32_bf16 v[112:115], v[178:181], v[186:189], v[112:115]
	v_mfma_f32_16x16x32_bf16 v[100:103], v[170:173], v[194:197], v[100:103]
	v_mfma_f32_16x16x32_bf16 v[96:99], v[178:181], v[194:197], v[96:99]
	v_mfma_f32_16x16x32_bf16 v[84:87], v[170:173], v[202:205], v[84:87]
	v_mfma_f32_16x16x32_bf16 v[80:83], v[178:181], v[202:205], v[80:83]
	v_mfma_f32_16x16x32_bf16 v[68:71], v[170:173], v[210:213], v[68:71]
	v_mfma_f32_16x16x32_bf16 v[64:67], v[178:181], v[210:213], v[64:67]
	s_barrier
	s_add_i32 s28, s57, s34
	s_mov_b32 m0, s28
	ds_read_b128 v[182:185], v149 offset:49152
	global_load_lds_dwordx4 v132, s[98:99]
	s_add_i32 m0, s28, 0x2000
	s_add_u32 s26, s26, 0x40080
	s_addc_u32 s27, s27, 0
	s_add_i32 s28, s59, s34
	global_load_lds_dwordx4 v128, s[98:99]
	s_mov_b32 m0, s28
	ds_read_b128 v[186:189], v149 offset:50176
	global_load_lds_dwordx4 v132, s[26:27]
	s_add_i32 m0, s28, 0x2000
	ds_read_b128 v[190:193], v149 offset:51200
	global_load_lds_dwordx4 v128, s[26:27]
	s_mov_b32 m0, s44
	ds_read_b128 v[194:197], v149 offset:52224
	global_load_lds_dwordx4 v134, s[100:101]
	s_mov_b32 m0, s45
	ds_read_b128 v[198:201], v149 offset:53248
	global_load_lds_dwordx4 v130, s[100:101]
	ds_read_b128 v[202:205], v149 offset:54272
	ds_read_b128 v[206:209], v149 offset:55296
	ds_read_b128 v[210:213], v149 offset:56320
	s_waitcnt vmcnt(8) lgkmcnt(0)
	s_barrier
	v_mfma_f32_16x16x32_bf16 v[60:63], v[150:153], v[182:185], v[60:63]
	v_mfma_f32_16x16x32_bf16 v[56:59], v[158:161], v[182:185], v[56:59]
	v_mfma_f32_16x16x32_bf16 v[44:47], v[150:153], v[190:193], v[44:47]
	v_mfma_f32_16x16x32_bf16 v[40:43], v[158:161], v[190:193], v[40:43]
	v_mfma_f32_16x16x32_bf16 v[28:31], v[150:153], v[198:201], v[28:31]
	v_mfma_f32_16x16x32_bf16 v[24:27], v[158:161], v[198:201], v[24:27]
	v_mfma_f32_16x16x32_bf16 v[12:15], v[150:153], v[206:209], v[12:15]
	v_mfma_f32_16x16x32_bf16 v[8:11], v[158:161], v[206:209], v[8:11]
	v_mfma_f32_16x16x32_bf16 v[60:63], v[154:157], v[186:189], v[60:63]
	v_mfma_f32_16x16x32_bf16 v[56:59], v[162:165], v[186:189], v[56:59]
	v_mfma_f32_16x16x32_bf16 v[44:47], v[154:157], v[194:197], v[44:47]
	v_mfma_f32_16x16x32_bf16 v[40:43], v[162:165], v[194:197], v[40:43]
	v_mfma_f32_16x16x32_bf16 v[28:31], v[154:157], v[202:205], v[28:31]
	v_mfma_f32_16x16x32_bf16 v[24:27], v[162:165], v[202:205], v[24:27]
	v_mfma_f32_16x16x32_bf16 v[12:15], v[154:157], v[210:213], v[12:15]
	v_mfma_f32_16x16x32_bf16 v[8:11], v[162:165], v[210:213], v[8:11]
	v_mfma_f32_16x16x32_bf16 v[52:55], v[166:169], v[182:185], v[52:55]
	v_mfma_f32_16x16x32_bf16 v[48:51], v[174:177], v[182:185], v[48:51]
	v_mfma_f32_16x16x32_bf16 v[36:39], v[166:169], v[190:193], v[36:39]
	v_mfma_f32_16x16x32_bf16 v[32:35], v[174:177], v[190:193], v[32:35]
	v_mfma_f32_16x16x32_bf16 v[20:23], v[166:169], v[198:201], v[20:23]
	v_mfma_f32_16x16x32_bf16 v[16:19], v[174:177], v[198:201], v[16:19]
	v_mfma_f32_16x16x32_bf16 v[4:7], v[166:169], v[206:209], v[4:7]
	v_mfma_f32_16x16x32_bf16 v[0:3], v[174:177], v[206:209], v[0:3]
	v_mfma_f32_16x16x32_bf16 v[52:55], v[170:173], v[186:189], v[52:55]
	v_mfma_f32_16x16x32_bf16 v[48:51], v[178:181], v[186:189], v[48:51]
	v_mfma_f32_16x16x32_bf16 v[36:39], v[170:173], v[194:197], v[36:39]
	v_mfma_f32_16x16x32_bf16 v[32:35], v[178:181], v[194:197], v[32:35]
	v_mfma_f32_16x16x32_bf16 v[20:23], v[170:173], v[202:205], v[20:23]
	v_mfma_f32_16x16x32_bf16 v[16:19], v[178:181], v[202:205], v[16:19]
	v_mfma_f32_16x16x32_bf16 v[4:7], v[170:173], v[210:213], v[4:7]
	v_mfma_f32_16x16x32_bf16 v[0:3], v[178:181], v[210:213], v[0:3]
	s_barrier
	s_add_i32 s56, s56, 2
	s_add_u32 s24, s24, 0x100
	s_addc_u32 s25, s25, 0
	s_add_u32 s54, s54, 0x100
	s_addc_u32 s55, s55, 0
	s_cmp_gt_u32 s56, 13
	s_cbranch_scc0 .LBB0_376
	s_and_b64 vcc, exec, s[12:13]
	s_cbranch_vccz .LBB0_379
	s_barrier

; #define PG8_STAGE(bufoff, gbase, voff) do { _Pragma("unroll") for (int _i = 0; _i < 2; ++_i) \
;         __builtin_amdgcn_global_load_lds((const unsigned*)((const char*)(gbase) + (voff)[_i]), (PG8_LAS unsigned*)(lds + (bufoff) + ldsw + _i * 8192), 16, 0, 0); } while (0)
; #define PG8_LDA(dst, b, h) do { _Pragma("unroll") for (int m = 0; m < 4; ++m) _Pragma("unroll") for (int k = 0; k < 2; ++k) dst[m][k] = *(const PG8_LAS bf16x8*)(lds + PG8_SA(b, h) + aoff + m * 2048 + k * 1024); } while (0)
; #define PG8_LDB(dst, b, h) do { _Pragma("unroll") for (int n = 0; n < 2; ++n) _Pragma("unroll") for (int k = 0; k < 2; ++k) dst[n][k] = *(const PG8_LAS bf16x8*)(lds + PG8_SB(b, h) + boff + n * 2048 + k * 1024); } while (0)
; #define PG8_MMA(ai, bj, At, Bt) do { __builtin_amdgcn_s_setprio(1); _Pragma("unroll") for (int m = 0; m < 4; ++m) _Pragma("unroll") for (int n = 0; n < 2; ++n) _Pragma("unroll") for (int k = 0; k < 2; ++k) \
;         acc[ai][bj][m][n] = __builtin_amdgcn_mfma_f32_16x16x32_bf16(Bt[n][k], At[m][k], acc[ai][bj][m][n], 0, 0, 0); __builtin_amdgcn_s_setprio(0); } while (0)
; #define PG8_WAIT_V(n) asm volatile("s_waitcnt vmcnt(" #n ")" ::: "memory")
; #define PG8_WAIT_L(n) asm volatile("s_waitcnt lgkmcnt(" #n ")" ::: "memory")
; #define PG8_BAR __builtin_amdgcn_s_barrier()
; #define PG8_SCHED __builtin_amdgcn_sched_barrier(0)
; template <class Epi, class Sched, bool ALIGN_EPI = false, bool SP2 = false>
; __device__ __forceinline__ void gemm_phase(PG8_LAS unsigned char* lds, const Gemm g, const Sched& S, const Epi& E, int tid_in) {
;     ...
;             const char* a2 = last ? nA : cA + (size_t)(t + 2) * kstep; const char* b2 = last ? nB : cB + (size_t)(t + 2) * kstep;
;             const char* a3 = a2 + kstep; const char* b3 = b2 + kstep;
;             if (last && has_next) S.a_ready(nxt);
;             if constexpr (SP2) {
;             PG8_LDB(B0, 0, 0); PG8_LDB(B1, 0, 1); PG8_SCHED; PG8_LDA(At, 0, 0); PG8_STAGE(PG8_SA(1, 1), a1 + hstep, voffA);
;             PG8_WAIT_V(8); PG8_WAIT_L(0); PG8_BAR; PG8_MMA(0, 0, At, B0); PG8_MMA(0, 1, At, B1); PG8_BAR; PG8_SCHED;
;             PG8_LDA(At, 0, 1); PG8_STAGE(PG8_SB(0, 0), b2, voffB); PG8_STAGE(PG8_SB(0, 1), b2 + hstep, voffB); PG8_STAGE(PG8_SA(0, 0), a2, voffA);
;             PG8_WAIT_V(8); PG8_WAIT_L(0); PG8_BAR; PG8_MMA(1, 0, At, B0); PG8_MMA(1, 1, At, B1); PG8_BAR; PG8_SCHED;
.LBB0_460:
	s_add_u32 s12, s50, 0x100
	s_addc_u32 s75, s51, 0
	s_mov_b32 s76, -2
	s_waitcnt lgkmcnt(0)
	s_add_u32 s6, s48, 0x100
	s_addc_u32 s7, s49, 0
	s_cmp_eq_u32 s76, 40
	s_cselect_b32 s53, s45, s7
	s_cselect_b32 s52, s44, s6
	s_cselect_b32 s51, s47, s75
	s_cselect_b32 s50, s46, s12
	s_add_i32 m0, s60, 0xc000
	ds_read_b128 v[128:131], v236
	global_load_lds_dwordx4 v200, s[48:49]
	s_add_i32 m0, s60, 0xe000
	ds_read_b128 v[132:135], v236 offset:1024
	global_load_lds_dwordx4 v202, s[48:49]
	ds_read_b128 v[136:139], v236 offset:2048
	ds_read_b128 v[140:143], v236 offset:3072
	ds_read_b128 v[144:147], v237
	ds_read_b128 v[148:151], v237 offset:1024
	ds_read_b128 v[152:155], v237 offset:2048
	ds_read_b128 v[156:159], v237 offset:3072
	ds_read_b128 v[160:163], v238
	ds_read_b128 v[164:167], v238 offset:1024
	ds_read_b128 v[168:171], v238 offset:2048
	ds_read_b128 v[172:175], v238 offset:3072
	ds_read_b128 v[176:179], v238 offset:4096
	ds_read_b128 v[180:183], v238 offset:5120
	ds_read_b128 v[184:187], v238 offset:6144
	ds_read_b128 v[188:191], v238 offset:7168
	s_waitcnt vmcnt(8) lgkmcnt(0)
	s_barrier
	v_mfma_f32_16x16x32_bf16 v[124:127], v[128:131], v[160:163], 0
	v_mfma_f32_16x16x32_bf16 v[120:123], v[136:139], v[160:163], 0
	v_mfma_f32_16x16x32_bf16 v[108:111], v[128:131], v[168:171], 0
	v_mfma_f32_16x16x32_bf16 v[104:107], v[136:139], v[168:171], 0
	v_mfma_f32_16x16x32_bf16 v[92:95], v[128:131], v[176:179], 0
	v_mfma_f32_16x16x32_bf16 v[88:91], v[136:139], v[176:179], 0
	v_mfma_f32_16x16x32_bf16 v[76:79], v[128:131], v[184:187], 0
	v_mfma_f32_16x16x32_bf16 v[72:75], v[136:139], v[184:187], 0
	v_mfma_f32_16x16x32_bf16 v[124:127], v[132:135], v[164:167], v[124:127]
	v_mfma_f32_16x16x32_bf16 v[120:123], v[140:143], v[164:167], v[120:123]
	v_mfma_f32_16x16x32_bf16 v[108:111], v[132:135], v[172:175], v[108:111]
	v_mfma_f32_16x16x32_bf16 v[104:107], v[140:143], v[172:175], v[104:107]
	v_mfma_f32_16x16x32_bf16 v[92:95], v[132:135], v[180:183], v[92:95]
	v_mfma_f32_16x16x32_bf16 v[88:91], v[140:143], v[180:183], v[88:91]
	v_mfma_f32_16x16x32_bf16 v[76:79], v[132:135], v[188:191], v[76:79]
	v_mfma_f32_16x16x32_bf16 v[72:75], v[140:143], v[188:191], v[72:75]
	v_mfma_f32_16x16x32_bf16 v[116:119], v[144:147], v[160:163], 0
	v_mfma_f32_16x16x32_bf16 v[112:115], v[152:155], v[160:163], 0
	v_mfma_f32_16x16x32_bf16 v[100:103], v[144:147], v[168:171], 0
	v_mfma_f32_16x16x32_bf16 v[96:99], v[152:155], v[168:171], 0
	v_mfma_f32_16x16x32_bf16 v[84:87], v[144:147], v[176:179], 0
	v_mfma_f32_16x16x32_bf16 v[80:83], v[152:155], v[176:179], 0
	v_mfma_f32_16x16x32_bf16 v[68:71], v[144:147], v[184:187], 0
	v_mfma_f32_16x16x32_bf16 v[64:67], v[152:155], v[184:187], 0
	v_mfma_f32_16x16x32_bf16 v[116:119], v[148:151], v[164:167], v[116:119]
	v_mfma_f32_16x16x32_bf16 v[112:115], v[156:159], v[164:167], v[112:115]
	v_mfma_f32_16x16x32_bf16 v[100:103], v[148:151], v[172:175], v[100:103]
	v_mfma_f32_16x16x32_bf16 v[96:99], v[156:159], v[172:175], v[96:99]
	v_mfma_f32_16x16x32_bf16 v[84:87], v[148:151], v[180:183], v[84:87]
	v_mfma_f32_16x16x32_bf16 v[80:83], v[156:159], v[180:183], v[80:83]
	v_mfma_f32_16x16x32_bf16 v[68:71], v[148:151], v[188:191], v[68:71]
	v_mfma_f32_16x16x32_bf16 v[64:67], v[156:159], v[188:191], v[64:67]
	s_barrier
	s_add_u32 s98, s50, s22
	s_addc_u32 s99, s51, s23
	s_add_u32 s100, s52, s22
	s_addc_u32 s101, s53, s23
	s_add_i32 s48, s70, s59
	s_mov_b32 m0, s48
	ds_read_b128 v[160:163], v238 offset:16384
	global_load_lds_dwordx4 v194, s[50:51]
	s_add_i32 m0, s48, 0x2000
	s_add_u32 s48, s50, 0xb0000
	s_addc_u32 s49, s51, 0
	s_add_i32 s77, s71, s59
	global_load_lds_dwordx4 v198, s[50:51]
	s_mov_b32 m0, s77
	ds_read_b128 v[164:167], v238 offset:17408
	global_load_lds_dwordx4 v194, s[48:49]
	s_add_i32 m0, s77, 0x2000
	ds_read_b128 v[168:171], v238 offset:18432
	global_load_lds_dwordx4 v198, s[48:49]
	s_mov_b32 m0, s60
	ds_read_b128 v[172:175], v238 offset:19456
	global_load_lds_dwordx4 v192, s[52:53]
	s_mov_b32 m0, s61
	ds_read_b128 v[176:179], v238 offset:20480
	global_load_lds_dwordx4 v196, s[52:53]
	ds_read_b128 v[180:183], v238 offset:21504
	ds_read_b128 v[184:187], v238 offset:22528
	ds_read_b128 v[188:191], v238 offset:23552
	s_waitcnt vmcnt(8) lgkmcnt(0)
	s_barrier
	v_mfma_f32_16x16x32_bf16 v[60:63], v[128:131], v[160:163], 0
	v_mfma_f32_16x16x32_bf16 v[56:59], v[136:139], v[160:163], 0
	v_mfma_f32_16x16x32_bf16 v[44:47], v[128:131], v[168:171], 0
	v_mfma_f32_16x16x32_bf16 v[40:43], v[136:139], v[168:171], 0
	v_mfma_f32_16x16x32_bf16 v[28:31], v[128:131], v[176:179], 0
	v_mfma_f32_16x16x32_bf16 v[24:27], v[136:139], v[176:179], 0
	v_mfma_f32_16x16x32_bf16 v[12:15], v[128:131], v[184:187], 0
	v_mfma_f32_16x16x32_bf16 v[8:11], v[136:139], v[184:187], 0
	v_mfma_f32_16x16x32_bf16 v[60:63], v[132:135], v[164:167], v[60:63]
	v_mfma_f32_16x16x32_bf16 v[56:59], v[140:143], v[164:167], v[56:59]
	v_mfma_f32_16x16x32_bf16 v[44:47], v[132:135], v[172:175], v[44:47]
	v_mfma_f32_16x16x32_bf16 v[40:43], v[140:143], v[172:175], v[40:43]
	v_mfma_f32_16x16x32_bf16 v[28:31], v[132:135], v[180:183], v[28:31]
	v_mfma_f32_16x16x32_bf16 v[24:27], v[140:143], v[180:183], v[24:27]
	v_mfma_f32_16x16x32_bf16 v[12:15], v[132:135], v[188:191], v[12:15]
	v_mfma_f32_16x16x32_bf16 v[8:11], v[140:143], v[188:191], v[8:11]
	v_mfma_f32_16x16x32_bf16 v[52:55], v[144:147], v[160:163], 0
	v_mfma_f32_16x16x32_bf16 v[48:51], v[152:155], v[160:163], 0
	v_mfma_f32_16x16x32_bf16 v[36:39], v[144:147], v[168:171], 0
	v_mfma_f32_16x16x32_bf16 v[32:35], v[152:155], v[168:171], 0
	v_mfma_f32_16x16x32_bf16 v[20:23], v[144:147], v[176:179], 0
	v_mfma_f32_16x16x32_bf16 v[16:19], v[152:155], v[176:179], 0
	v_mfma_f32_16x16x32_bf16 v[4:7], v[144:147], v[184:187], 0
	v_mfma_f32_16x16x32_bf16 v[0:3], v[152:155], v[184:187], 0
	v_mfma_f32_16x16x32_bf16 v[52:55], v[148:151], v[164:167], v[52:55]
	v_mfma_f32_16x16x32_bf16 v[48:51], v[156:159], v[164:167], v[48:51]
	v_mfma_f32_16x16x32_bf16 v[36:39], v[148:151], v[172:175], v[36:39]
	v_mfma_f32_16x16x32_bf16 v[32:35], v[156:159], v[172:175], v[32:35]
	v_mfma_f32_16x16x32_bf16 v[20:23], v[148:151], v[180:183], v[20:23]
	v_mfma_f32_16x16x32_bf16 v[16:19], v[156:159], v[180:183], v[16:19]
	v_mfma_f32_16x16x32_bf16 v[4:7], v[148:151], v[188:191], v[4:7]
	v_mfma_f32_16x16x32_bf16 v[0:3], v[156:159], v[188:191], v[0:3]
	s_barrier
; #define PG8_STAGE(bufoff, gbase, voff) do { _Pragma("unroll") for (int _i = 0; _i < 2; ++_i) \
;         __builtin_amdgcn_global_load_lds((const unsigned*)((const char*)(gbase) + (voff)[_i]), (PG8_LAS unsigned*)(lds + (bufoff) + ldsw + _i * 8192), 16, 0, 0); } while (0)
; #define PG8_LDA(dst, b, h) do { _Pragma("unroll") for (int m = 0; m < 4; ++m) _Pragma("unroll") for (int k = 0; k < 2; ++k) dst[m][k] = *(const PG8_LAS bf16x8*)(lds + PG8_SA(b, h) + aoff + m * 2048 + k * 1024); } while (0)
; #define PG8_LDB(dst, b, h) do { _Pragma("unroll") for (int n = 0; n < 2; ++n) _Pragma("unroll") for (int k = 0; k < 2; ++k) dst[n][k] = *(const PG8_LAS bf16x8*)(lds + PG8_SB(b, h) + boff + n * 2048 + k * 1024); } while (0)
; #define PG8_MMA(ai, bj, At, Bt) do { __builtin_amdgcn_s_setprio(1); _Pragma("unroll") for (int m = 0; m < 4; ++m) _Pragma("unroll") for (int n = 0; n < 2; ++n) _Pragma("unroll") for (int k = 0; k < 2; ++k) \
;         acc[ai][bj][m][n] = __builtin_amdgcn_mfma_f32_16x16x32_bf16(Bt[n][k], At[m][k], acc[ai][bj][m][n], 0, 0, 0); __builtin_amdgcn_s_setprio(0); } while (0)
; #define PG8_WAIT_V(n) asm volatile("s_waitcnt vmcnt(" #n ")" ::: "memory")
; #define PG8_WAIT_L(n) asm volatile("s_waitcnt lgkmcnt(" #n ")" ::: "memory")
; #define PG8_BAR __builtin_amdgcn_s_barrier()
; #define PG8_SCHED __builtin_amdgcn_sched_barrier(0)
; template <class Epi, class Sched, bool ALIGN_EPI = false, bool SP2 = false>
; __device__ __forceinline__ void gemm_phase(PG8_LAS unsigned char* lds, const Gemm g, const Sched& S, const Epi& E, int tid_in) {
;     ...
;             PG8_LDB(B0, 1, 0); PG8_LDB(B1, 1, 1); PG8_SCHED; PG8_LDA(At, 1, 0); PG8_STAGE(PG8_SA(0, 1), a2 + hstep, voffA);
;             PG8_WAIT_V(8); PG8_WAIT_L(0); PG8_BAR; PG8_MMA(0, 0, At, B0); PG8_MMA(0, 1, At, B1); PG8_BAR; PG8_SCHED;
;             PG8_LDA(At, 1, 1); PG8_STAGE(PG8_SB(1, 0), b3, voffB); PG8_STAGE(PG8_SB(1, 1), b3 + hstep, voffB); PG8_STAGE(PG8_SA(1, 0), a3, voffA);
;             PG8_WAIT_V(8); PG8_WAIT_L(0); PG8_BAR; PG8_MMA(1, 0, At, B0); PG8_MMA(1, 1, At, B1); PG8_BAR; PG8_SCHED;
	s_add_i32 s77, 0, 0x18000
	s_add_i32 s78, 0, 0x1c000
	s_add_u32 s48, s52, 0xb0000
	s_addc_u32 s49, s53, 0
	s_mov_b32 m0, s62
	s_nop 0
	global_load_lds_dwordx4 v192, s[48:49]
	s_mov_b32 m0, s63
	s_nop 0
	global_load_lds_dwordx4 v196, s[48:49]
	v_add_u32_e32 v140, s77, v232
	v_add_u32_e32 v156, s78, v232
	ds_read_b128 v[128:131], v140
	ds_read_b128 v[132:135], v140 offset:1024
	ds_read_b128 v[136:139], v140 offset:2048
	ds_read_b128 v[140:143], v140 offset:3072
	ds_read_b128 v[144:147], v156
	ds_read_b128 v[148:151], v156 offset:1024
	ds_read_b128 v[152:155], v156 offset:2048
	ds_read_b128 v[156:159], v156 offset:3072
	ds_read_b128 v[160:163], v238 offset:32768
	ds_read_b128 v[164:167], v238 offset:33792
	ds_read_b128 v[168:171], v238 offset:34816
	ds_read_b128 v[172:175], v238 offset:35840
	ds_read_b128 v[176:179], v238 offset:36864
	ds_read_b128 v[180:183], v238 offset:37888
	ds_read_b128 v[184:187], v238 offset:38912
	ds_read_b128 v[188:191], v238 offset:39936
	s_waitcnt vmcnt(8) lgkmcnt(0)
	s_barrier
	v_mfma_f32_16x16x32_bf16 v[124:127], v[128:131], v[160:163], v[124:127]
	v_mfma_f32_16x16x32_bf16 v[120:123], v[136:139], v[160:163], v[120:123]
	v_mfma_f32_16x16x32_bf16 v[108:111], v[128:131], v[168:171], v[108:111]
	v_mfma_f32_16x16x32_bf16 v[104:107], v[136:139], v[168:171], v[104:107]
	v_mfma_f32_16x16x32_bf16 v[92:95], v[128:131], v[176:179], v[92:95]
	v_mfma_f32_16x16x32_bf16 v[88:91], v[136:139], v[176:179], v[88:91]
	v_mfma_f32_16x16x32_bf16 v[76:79], v[128:131], v[184:187], v[76:79]
	v_mfma_f32_16x16x32_bf16 v[72:75], v[136:139], v[184:187], v[72:75]
	v_mfma_f32_16x16x32_bf16 v[124:127], v[132:135], v[164:167], v[124:127]
	v_mfma_f32_16x16x32_bf16 v[120:123], v[140:143], v[164:167], v[120:123]
	v_mfma_f32_16x16x32_bf16 v[108:111], v[132:135], v[172:175], v[108:111]
	v_mfma_f32_16x16x32_bf16 v[104:107], v[140:143], v[172:175], v[104:107]
	v_mfma_f32_16x16x32_bf16 v[92:95], v[132:135], v[180:183], v[92:95]
	v_mfma_f32_16x16x32_bf16 v[88:91], v[140:143], v[180:183], v[88:91]
	v_mfma_f32_16x16x32_bf16 v[76:79], v[132:135], v[188:191], v[76:79]
	v_mfma_f32_16x16x32_bf16 v[72:75], v[140:143], v[188:191], v[72:75]
	v_mfma_f32_16x16x32_bf16 v[116:119], v[144:147], v[160:163], v[116:119]
	v_mfma_f32_16x16x32_bf16 v[112:115], v[152:155], v[160:163], v[112:115]
	v_mfma_f32_16x16x32_bf16 v[100:103], v[144:147], v[168:171], v[100:103]
	v_mfma_f32_16x16x32_bf16 v[96:99], v[152:155], v[168:171], v[96:99]
	v_mfma_f32_16x16x32_bf16 v[84:87], v[144:147], v[176:179], v[84:87]
	v_mfma_f32_16x16x32_bf16 v[80:83], v[152:155], v[176:179], v[80:83]
	v_mfma_f32_16x16x32_bf16 v[68:71], v[144:147], v[184:187], v[68:71]
	v_mfma_f32_16x16x32_bf16 v[64:67], v[152:155], v[184:187], v[64:67]
	v_mfma_f32_16x16x32_bf16 v[116:119], v[148:151], v[164:167], v[116:119]
	v_mfma_f32_16x16x32_bf16 v[112:115], v[156:159], v[164:167], v[112:115]
	v_mfma_f32_16x16x32_bf16 v[100:103], v[148:151], v[172:175], v[100:103]
	v_mfma_f32_16x16x32_bf16 v[96:99], v[156:159], v[172:175], v[96:99]
	v_mfma_f32_16x16x32_bf16 v[84:87], v[148:151], v[180:183], v[84:87]
	v_mfma_f32_16x16x32_bf16 v[80:83], v[156:159], v[180:183], v[80:83]
	v_mfma_f32_16x16x32_bf16 v[68:71], v[148:151], v[188:191], v[68:71]
	v_mfma_f32_16x16x32_bf16 v[64:67], v[156:159], v[188:191], v[64:67]
	s_barrier
	s_add_i32 s48, s77, s59
	s_mov_b32 m0, s48
	ds_read_b128 v[160:163], v238 offset:49152
	global_load_lds_dwordx4 v194, s[98:99]
	s_add_i32 m0, s48, 0x2000
	s_add_u32 s48, s50, 0xb0080
	s_addc_u32 s49, s51, 0
	s_add_i32 s50, s78, s59
	global_load_lds_dwordx4 v198, s[98:99]
	s_mov_b32 m0, s50
	ds_read_b128 v[164:167], v238 offset:50176
	global_load_lds_dwordx4 v194, s[48:49]
	s_add_i32 m0, s50, 0x2000
	ds_read_b128 v[168:171], v238 offset:51200
	global_load_lds_dwordx4 v198, s[48:49]
	s_mov_b32 m0, s65
	ds_read_b128 v[172:175], v238 offset:52224
	global_load_lds_dwordx4 v192, s[100:101]
	s_mov_b32 m0, s67
	ds_read_b128 v[176:179], v238 offset:53248
	global_load_lds_dwordx4 v196, s[100:101]
	ds_read_b128 v[180:183], v238 offset:54272
	ds_read_b128 v[184:187], v238 offset:55296
	ds_read_b128 v[188:191], v238 offset:56320
	s_waitcnt vmcnt(8) lgkmcnt(0)
	s_barrier
	v_mfma_f32_16x16x32_bf16 v[60:63], v[128:131], v[160:163], v[60:63]
	v_mfma_f32_16x16x32_bf16 v[56:59], v[136:139], v[160:163], v[56:59]
	v_mfma_f32_16x16x32_bf16 v[44:47], v[128:131], v[168:171], v[44:47]
	v_mfma_f32_16x16x32_bf16 v[40:43], v[136:139], v[168:171], v[40:43]
	v_mfma_f32_16x16x32_bf16 v[28:31], v[128:131], v[176:179], v[28:31]
	v_mfma_f32_16x16x32_bf16 v[24:27], v[136:139], v[176:179], v[24:27]
	v_mfma_f32_16x16x32_bf16 v[12:15], v[128:131], v[184:187], v[12:15]
	v_mfma_f32_16x16x32_bf16 v[8:11], v[136:139], v[184:187], v[8:11]
	v_mfma_f32_16x16x32_bf16 v[60:63], v[132:135], v[164:167], v[60:63]
	v_mfma_f32_16x16x32_bf16 v[56:59], v[140:143], v[164:167], v[56:59]
	v_mfma_f32_16x16x32_bf16 v[44:47], v[132:135], v[172:175], v[44:47]
	v_mfma_f32_16x16x32_bf16 v[40:43], v[140:143], v[172:175], v[40:43]
	v_mfma_f32_16x16x32_bf16 v[28:31], v[132:135], v[180:183], v[28:31]
	v_mfma_f32_16x16x32_bf16 v[24:27], v[140:143], v[180:183], v[24:27]
	v_mfma_f32_16x16x32_bf16 v[12:15], v[132:135], v[188:191], v[12:15]
	v_mfma_f32_16x16x32_bf16 v[8:11], v[140:143], v[188:191], v[8:11]
	v_mfma_f32_16x16x32_bf16 v[52:55], v[144:147], v[160:163], v[52:55]
	v_mfma_f32_16x16x32_bf16 v[48:51], v[152:155], v[160:163], v[48:51]
	v_mfma_f32_16x16x32_bf16 v[36:39], v[144:147], v[168:171], v[36:39]
	v_mfma_f32_16x16x32_bf16 v[32:35], v[152:155], v[168:171], v[32:35]
	v_mfma_f32_16x16x32_bf16 v[20:23], v[144:147], v[176:179], v[20:23]
	v_mfma_f32_16x16x32_bf16 v[16:19], v[152:155], v[176:179], v[16:19]
	v_mfma_f32_16x16x32_bf16 v[4:7], v[144:147], v[184:187], v[4:7]
	v_mfma_f32_16x16x32_bf16 v[0:3], v[152:155], v[184:187], v[0:3]
	v_mfma_f32_16x16x32_bf16 v[52:55], v[148:151], v[164:167], v[52:55]
	v_mfma_f32_16x16x32_bf16 v[48:51], v[156:159], v[164:167], v[48:51]
	v_mfma_f32_16x16x32_bf16 v[36:39], v[148:151], v[172:175], v[36:39]
	v_mfma_f32_16x16x32_bf16 v[32:35], v[156:159], v[172:175], v[32:35]
	v_mfma_f32_16x16x32_bf16 v[20:23], v[148:151], v[180:183], v[20:23]
	v_mfma_f32_16x16x32_bf16 v[16:19], v[156:159], v[180:183], v[16:19]
	v_mfma_f32_16x16x32_bf16 v[4:7], v[148:151], v[188:191], v[4:7]
	v_mfma_f32_16x16x32_bf16 v[0:3], v[156:159], v[188:191], v[0:3]
	s_barrier
	s_add_i32 s76, s76, 2
	s_add_u32 s12, s12, 0x100
	s_addc_u32 s75, s75, 0
	s_mov_b64 s[48:49], s[6:7]
; #define PG8_STAGE(bufoff, gbase, voff) do { _Pragma("unroll") for (int _i = 0; _i < 2; ++_i) \
;         __builtin_amdgcn_global_load_lds((const unsigned*)((const char*)(gbase) + (voff)[_i]), (PG8_LAS unsigned*)(lds + (bufoff) + ldsw + _i * 8192), 16, 0, 0); } while (0)
; #define PG8_LDA(dst, b, h) do { _Pragma("unroll") for (int m = 0; m < 4; ++m) _Pragma("unroll") for (int k = 0; k < 2; ++k) dst[m][k] = *(const PG8_LAS bf16x8*)(lds + PG8_SA(b, h) + aoff + m * 2048 + k * 1024); } while (0)
; #define PG8_LDB(dst, b, h) do { _Pragma("unroll") for (int n = 0; n < 2; ++n) _Pragma("unroll") for (int k = 0; k < 2; ++k) dst[n][k] = *(const PG8_LAS bf16x8*)(lds + PG8_SB(b, h) + boff + n * 2048 + k * 1024); } while (0)
; #define PG8_MMA(ai, bj, At, Bt) do { __builtin_amdgcn_s_setprio(1); _Pragma("unroll") for (int m = 0; m < 4; ++m) _Pragma("unroll") for (int n = 0; n < 2; ++n) _Pragma("unroll") for (int k = 0; k < 2; ++k) \
;         acc[ai][bj][m][n] = __builtin_amdgcn_mfma_f32_16x16x32_bf16(Bt[n][k], At[m][k], acc[ai][bj][m][n], 0, 0, 0); __builtin_amdgcn_s_setprio(0); } while (0)
; #define PG8_WAIT_V(n) asm volatile("s_waitcnt vmcnt(" #n ")" ::: "memory")
; #define PG8_WAIT_L(n) asm volatile("s_waitcnt lgkmcnt(" #n ")" ::: "memory")
; #define PG8_BAR __builtin_amdgcn_s_barrier()
; #define PG8_SCHED __builtin_amdgcn_sched_barrier(0)
; template <class Epi, class Sched, bool ALIGN_EPI = false, bool SP2 = false>
; __device__ __forceinline__ void gemm_phase(PG8_LAS unsigned char* lds, const Gemm g, const Sched& S, const Epi& E, int tid_in) {
;     ...
;             const char* a2 = last ? nA : cA + (size_t)(t + 2) * kstep; const char* b2 = last ? nB : cB + (size_t)(t + 2) * kstep;
;             const char* a3 = a2 + kstep; const char* b3 = b2 + kstep;
;             if (last && has_next) S.a_ready(nxt);
;             if constexpr (SP2) {
;             PG8_LDB(B0, 0, 0); PG8_LDB(B1, 0, 1); PG8_SCHED; PG8_LDA(At, 0, 0); PG8_STAGE(PG8_SA(1, 1), a1 + hstep, voffA);
;             PG8_WAIT_V(8); PG8_WAIT_L(0); PG8_BAR; PG8_MMA(0, 0, At, B0); PG8_MMA(0, 1, At, B1); PG8_BAR; PG8_SCHED;
;             PG8_LDA(At, 0, 1); PG8_STAGE(PG8_SB(0, 0), b2, voffB); PG8_STAGE(PG8_SB(0, 1), b2 + hstep, voffB); PG8_STAGE(PG8_SA(0, 0), a2, voffA);
;             PG8_WAIT_V(8); PG8_WAIT_L(0); PG8_BAR; PG8_MMA(1, 0, At, B0); PG8_MMA(1, 1, At, B1); PG8_BAR; PG8_SCHED;
.LBB0_461:
	s_add_u32 s6, s48, 0x100
	s_addc_u32 s7, s49, 0
	s_cmp_eq_u32 s76, 40
	s_cselect_b32 s53, s45, s7
	s_cselect_b32 s52, s44, s6
	s_cselect_b32 s51, s47, s75
	s_cselect_b32 s50, s46, s12
	s_add_i32 m0, s60, 0xc000
	ds_read_b128 v[128:131], v236
	global_load_lds_dwordx4 v200, s[48:49]
	s_add_i32 m0, s60, 0xe000
	ds_read_b128 v[132:135], v236 offset:1024
	global_load_lds_dwordx4 v202, s[48:49]
	ds_read_b128 v[136:139], v236 offset:2048
	ds_read_b128 v[140:143], v236 offset:3072
	ds_read_b128 v[144:147], v237
	ds_read_b128 v[148:151], v237 offset:1024
	ds_read_b128 v[152:155], v237 offset:2048
	ds_read_b128 v[156:159], v237 offset:3072
	ds_read_b128 v[160:163], v238
	ds_read_b128 v[164:167], v238 offset:1024
	ds_read_b128 v[168:171], v238 offset:2048
	ds_read_b128 v[172:175], v238 offset:3072
	ds_read_b128 v[176:179], v238 offset:4096
	ds_read_b128 v[180:183], v238 offset:5120
	ds_read_b128 v[184:187], v238 offset:6144
	ds_read_b128 v[188:191], v238 offset:7168
	s_waitcnt vmcnt(8) lgkmcnt(0)
	s_barrier
	v_mfma_f32_16x16x32_bf16 v[124:127], v[128:131], v[160:163], v[124:127]
	v_mfma_f32_16x16x32_bf16 v[120:123], v[136:139], v[160:163], v[120:123]
	v_mfma_f32_16x16x32_bf16 v[108:111], v[128:131], v[168:171], v[108:111]
	v_mfma_f32_16x16x32_bf16 v[104:107], v[136:139], v[168:171], v[104:107]
	v_mfma_f32_16x16x32_bf16 v[92:95], v[128:131], v[176:179], v[92:95]
	v_mfma_f32_16x16x32_bf16 v[88:91], v[136:139], v[176:179], v[88:91]
	v_mfma_f32_16x16x32_bf16 v[76:79], v[128:131], v[184:187], v[76:79]
	v_mfma_f32_16x16x32_bf16 v[72:75], v[136:139], v[184:187], v[72:75]
	v_mfma_f32_16x16x32_bf16 v[124:127], v[132:135], v[164:167], v[124:127]
	v_mfma_f32_16x16x32_bf16 v[120:123], v[140:143], v[164:167], v[120:123]
	v_mfma_f32_16x16x32_bf16 v[108:111], v[132:135], v[172:175], v[108:111]
	v_mfma_f32_16x16x32_bf16 v[104:107], v[140:143], v[172:175], v[104:107]
	v_mfma_f32_16x16x32_bf16 v[92:95], v[132:135], v[180:183], v[92:95]
	v_mfma_f32_16x16x32_bf16 v[88:91], v[140:143], v[180:183], v[88:91]
	v_mfma_f32_16x16x32_bf16 v[76:79], v[132:135], v[188:191], v[76:79]
	v_mfma_f32_16x16x32_bf16 v[72:75], v[140:143], v[188:191], v[72:75]
	v_mfma_f32_16x16x32_bf16 v[116:119], v[144:147], v[160:163], v[116:119]
	v_mfma_f32_16x16x32_bf16 v[112:115], v[152:155], v[160:163], v[112:115]
	v_mfma_f32_16x16x32_bf16 v[100:103], v[144:147], v[168:171], v[100:103]
	v_mfma_f32_16x16x32_bf16 v[96:99], v[152:155], v[168:171], v[96:99]
	v_mfma_f32_16x16x32_bf16 v[84:87], v[144:147], v[176:179], v[84:87]
	v_mfma_f32_16x16x32_bf16 v[80:83], v[152:155], v[176:179], v[80:83]
	v_mfma_f32_16x16x32_bf16 v[68:71], v[144:147], v[184:187], v[68:71]
	v_mfma_f32_16x16x32_bf16 v[64:67], v[152:155], v[184:187], v[64:67]
	v_mfma_f32_16x16x32_bf16 v[116:119], v[148:151], v[164:167], v[116:119]
	v_mfma_f32_16x16x32_bf16 v[112:115], v[156:159], v[164:167], v[112:115]
	v_mfma_f32_16x16x32_bf16 v[100:103], v[148:151], v[172:175], v[100:103]
	v_mfma_f32_16x16x32_bf16 v[96:99], v[156:159], v[172:175], v[96:99]
	v_mfma_f32_16x16x32_bf16 v[84:87], v[148:151], v[180:183], v[84:87]
	v_mfma_f32_16x16x32_bf16 v[80:83], v[156:159], v[180:183], v[80:83]
	v_mfma_f32_16x16x32_bf16 v[68:71], v[148:151], v[188:191], v[68:71]
	v_mfma_f32_16x16x32_bf16 v[64:67], v[156:159], v[188:191], v[64:67]
	s_barrier
	s_add_u32 s98, s50, s22
	s_addc_u32 s99, s51, s23
	s_add_u32 s100, s52, s22
	s_addc_u32 s101, s53, s23
	s_add_i32 s48, s70, s59
	s_mov_b32 m0, s48
	ds_read_b128 v[160:163], v238 offset:16384
	global_load_lds_dwordx4 v194, s[50:51]
	s_add_i32 m0, s48, 0x2000
	s_add_u32 s48, s50, 0xb0000
	s_addc_u32 s49, s51, 0
	s_add_i32 s77, s71, s59
	global_load_lds_dwordx4 v198, s[50:51]
	s_mov_b32 m0, s77
	ds_read_b128 v[164:167], v238 offset:17408
	global_load_lds_dwordx4 v194, s[48:49]
	s_add_i32 m0, s77, 0x2000
	ds_read_b128 v[168:171], v238 offset:18432
	global_load_lds_dwordx4 v198, s[48:49]
	s_mov_b32 m0, s60
	ds_read_b128 v[172:175], v238 offset:19456
	global_load_lds_dwordx4 v192, s[52:53]
	s_mov_b32 m0, s61
	ds_read_b128 v[176:179], v238 offset:20480
	global_load_lds_dwordx4 v196, s[52:53]
	ds_read_b128 v[180:183], v238 offset:21504
	ds_read_b128 v[184:187], v238 offset:22528
	ds_read_b128 v[188:191], v238 offset:23552
	s_waitcnt vmcnt(8) lgkmcnt(0)
	s_barrier
	v_mfma_f32_16x16x32_bf16 v[60:63], v[128:131], v[160:163], v[60:63]
	v_mfma_f32_16x16x32_bf16 v[56:59], v[136:139], v[160:163], v[56:59]
	v_mfma_f32_16x16x32_bf16 v[44:47], v[128:131], v[168:171], v[44:47]
	v_mfma_f32_16x16x32_bf16 v[40:43], v[136:139], v[168:171], v[40:43]
	v_mfma_f32_16x16x32_bf16 v[28:31], v[128:131], v[176:179], v[28:31]
	v_mfma_f32_16x16x32_bf16 v[24:27], v[136:139], v[176:179], v[24:27]
	v_mfma_f32_16x16x32_bf16 v[12:15], v[128:131], v[184:187], v[12:15]
	v_mfma_f32_16x16x32_bf16 v[8:11], v[136:139], v[184:187], v[8:11]
	v_mfma_f32_16x16x32_bf16 v[60:63], v[132:135], v[164:167], v[60:63]
	v_mfma_f32_16x16x32_bf16 v[56:59], v[140:143], v[164:167], v[56:59]
	v_mfma_f32_16x16x32_bf16 v[44:47], v[132:135], v[172:175], v[44:47]
	v_mfma_f32_16x16x32_bf16 v[40:43], v[140:143], v[172:175], v[40:43]
	v_mfma_f32_16x16x32_bf16 v[28:31], v[132:135], v[180:183], v[28:31]
	v_mfma_f32_16x16x32_bf16 v[24:27], v[140:143], v[180:183], v[24:27]
	v_mfma_f32_16x16x32_bf16 v[12:15], v[132:135], v[188:191], v[12:15]
	v_mfma_f32_16x16x32_bf16 v[8:11], v[140:143], v[188:191], v[8:11]
	v_mfma_f32_16x16x32_bf16 v[52:55], v[144:147], v[160:163], v[52:55]
	v_mfma_f32_16x16x32_bf16 v[48:51], v[152:155], v[160:163], v[48:51]
	v_mfma_f32_16x16x32_bf16 v[36:39], v[144:147], v[168:171], v[36:39]
	v_mfma_f32_16x16x32_bf16 v[32:35], v[152:155], v[168:171], v[32:35]
	v_mfma_f32_16x16x32_bf16 v[20:23], v[144:147], v[176:179], v[20:23]
	v_mfma_f32_16x16x32_bf16 v[16:19], v[152:155], v[176:179], v[16:19]
	v_mfma_f32_16x16x32_bf16 v[4:7], v[144:147], v[184:187], v[4:7]
	v_mfma_f32_16x16x32_bf16 v[0:3], v[152:155], v[184:187], v[0:3]
	v_mfma_f32_16x16x32_bf16 v[52:55], v[148:151], v[164:167], v[52:55]
	v_mfma_f32_16x16x32_bf16 v[48:51], v[156:159], v[164:167], v[48:51]
	v_mfma_f32_16x16x32_bf16 v[36:39], v[148:151], v[172:175], v[36:39]
	v_mfma_f32_16x16x32_bf16 v[32:35], v[156:159], v[172:175], v[32:35]
	v_mfma_f32_16x16x32_bf16 v[20:23], v[148:151], v[180:183], v[20:23]
	v_mfma_f32_16x16x32_bf16 v[16:19], v[156:159], v[180:183], v[16:19]
	v_mfma_f32_16x16x32_bf16 v[4:7], v[148:151], v[188:191], v[4:7]
	v_mfma_f32_16x16x32_bf16 v[0:3], v[156:159], v[188:191], v[0:3]
	s_barrier
; #define PG8_STAGE(bufoff, gbase, voff) do { _Pragma("unroll") for (int _i = 0; _i < 2; ++_i) \
;         __builtin_amdgcn_global_load_lds((const unsigned*)((const char*)(gbase) + (voff)[_i]), (PG8_LAS unsigned*)(lds + (bufoff) + ldsw + _i * 8192), 16, 0, 0); } while (0)
; #define PG8_LDA(dst, b, h) do { _Pragma("unroll") for (int m = 0; m < 4; ++m) _Pragma("unroll") for (int k = 0; k < 2; ++k) dst[m][k] = *(const PG8_LAS bf16x8*)(lds + PG8_SA(b, h) + aoff + m * 2048 + k * 1024); } while (0)
; #define PG8_LDB(dst, b, h) do { _Pragma("unroll") for (int n = 0; n < 2; ++n) _Pragma("unroll") for (int k = 0; k < 2; ++k) dst[n][k] = *(const PG8_LAS bf16x8*)(lds + PG8_SB(b, h) + boff + n * 2048 + k * 1024); } while (0)
; #define PG8_MMA(ai, bj, At, Bt) do { __builtin_amdgcn_s_setprio(1); _Pragma("unroll") for (int m = 0; m < 4; ++m) _Pragma("unroll") for (int n = 0; n < 2; ++n) _Pragma("unroll") for (int k = 0; k < 2; ++k) \
;         acc[ai][bj][m][n] = __builtin_amdgcn_mfma_f32_16x16x32_bf16(Bt[n][k], At[m][k], acc[ai][bj][m][n], 0, 0, 0); __builtin_amdgcn_s_setprio(0); } while (0)
; #define PG8_WAIT_V(n) asm volatile("s_waitcnt vmcnt(" #n ")" ::: "memory")
; #define PG8_WAIT_L(n) asm volatile("s_waitcnt lgkmcnt(" #n ")" ::: "memory")
; #define PG8_BAR __builtin_amdgcn_s_barrier()
; #define PG8_SCHED __builtin_amdgcn_sched_barrier(0)
; template <class Epi, class Sched, bool ALIGN_EPI = false, bool SP2 = false>
; __device__ __forceinline__ void gemm_phase(PG8_LAS unsigned char* lds, const Gemm g, const Sched& S, const Epi& E, int tid_in) {
;     ...
;             PG8_LDB(B0, 1, 0); PG8_LDB(B1, 1, 1); PG8_SCHED; PG8_LDA(At, 1, 0); PG8_STAGE(PG8_SA(0, 1), a2 + hstep, voffA);
;             PG8_WAIT_V(8); PG8_WAIT_L(0); PG8_BAR; PG8_MMA(0, 0, At, B0); PG8_MMA(0, 1, At, B1); PG8_BAR; PG8_SCHED;
;             PG8_LDA(At, 1, 1); PG8_STAGE(PG8_SB(1, 0), b3, voffB); PG8_STAGE(PG8_SB(1, 1), b3 + hstep, voffB); PG8_STAGE(PG8_SA(1, 0), a3, voffA);
;             PG8_WAIT_V(8); PG8_WAIT_L(0); PG8_BAR; PG8_MMA(1, 0, At, B0); PG8_MMA(1, 1, At, B1); PG8_BAR; PG8_SCHED;
;     ...
;         if constexpr (ALIGN_EPI) { if (wr == 0) PG8_BAR; }
	s_add_i32 s77, 0, 0x18000
	s_add_i32 s78, 0, 0x1c000
	s_add_u32 s48, s52, 0xb0000
	s_addc_u32 s49, s53, 0
	s_mov_b32 m0, s62
	s_nop 0
	global_load_lds_dwordx4 v192, s[48:49]
	s_mov_b32 m0, s63
	s_nop 0
	global_load_lds_dwordx4 v196, s[48:49]
	v_add_u32_e32 v140, s77, v232
	v_add_u32_e32 v156, s78, v232
	ds_read_b128 v[128:131], v140
	ds_read_b128 v[132:135], v140 offset:1024
	ds_read_b128 v[136:139], v140 offset:2048
	ds_read_b128 v[140:143], v140 offset:3072
	ds_read_b128 v[144:147], v156
	ds_read_b128 v[148:151], v156 offset:1024
	ds_read_b128 v[152:155], v156 offset:2048
	ds_read_b128 v[156:159], v156 offset:3072
	ds_read_b128 v[160:163], v238 offset:32768
	ds_read_b128 v[164:167], v238 offset:33792
	ds_read_b128 v[168:171], v238 offset:34816
	ds_read_b128 v[172:175], v238 offset:35840
	ds_read_b128 v[176:179], v238 offset:36864
	ds_read_b128 v[180:183], v238 offset:37888
	ds_read_b128 v[184:187], v238 offset:38912
	ds_read_b128 v[188:191], v238 offset:39936
	s_waitcnt vmcnt(8) lgkmcnt(0)
	s_barrier
	v_mfma_f32_16x16x32_bf16 v[124:127], v[128:131], v[160:163], v[124:127]
	v_mfma_f32_16x16x32_bf16 v[120:123], v[136:139], v[160:163], v[120:123]
	v_mfma_f32_16x16x32_bf16 v[108:111], v[128:131], v[168:171], v[108:111]
	v_mfma_f32_16x16x32_bf16 v[104:107], v[136:139], v[168:171], v[104:107]
	v_mfma_f32_16x16x32_bf16 v[92:95], v[128:131], v[176:179], v[92:95]
	v_mfma_f32_16x16x32_bf16 v[88:91], v[136:139], v[176:179], v[88:91]
	v_mfma_f32_16x16x32_bf16 v[76:79], v[128:131], v[184:187], v[76:79]
	v_mfma_f32_16x16x32_bf16 v[72:75], v[136:139], v[184:187], v[72:75]
	v_mfma_f32_16x16x32_bf16 v[124:127], v[132:135], v[164:167], v[124:127]
	v_mfma_f32_16x16x32_bf16 v[120:123], v[140:143], v[164:167], v[120:123]
	v_mfma_f32_16x16x32_bf16 v[108:111], v[132:135], v[172:175], v[108:111]
	v_mfma_f32_16x16x32_bf16 v[104:107], v[140:143], v[172:175], v[104:107]
	v_mfma_f32_16x16x32_bf16 v[92:95], v[132:135], v[180:183], v[92:95]
	v_mfma_f32_16x16x32_bf16 v[88:91], v[140:143], v[180:183], v[88:91]
	v_mfma_f32_16x16x32_bf16 v[76:79], v[132:135], v[188:191], v[76:79]
	v_mfma_f32_16x16x32_bf16 v[72:75], v[140:143], v[188:191], v[72:75]
	v_mfma_f32_16x16x32_bf16 v[116:119], v[144:147], v[160:163], v[116:119]
	v_mfma_f32_16x16x32_bf16 v[112:115], v[152:155], v[160:163], v[112:115]
	v_mfma_f32_16x16x32_bf16 v[100:103], v[144:147], v[168:171], v[100:103]
	v_mfma_f32_16x16x32_bf16 v[96:99], v[152:155], v[168:171], v[96:99]
	v_mfma_f32_16x16x32_bf16 v[84:87], v[144:147], v[176:179], v[84:87]
	v_mfma_f32_16x16x32_bf16 v[80:83], v[152:155], v[176:179], v[80:83]
	v_mfma_f32_16x16x32_bf16 v[68:71], v[144:147], v[184:187], v[68:71]
	v_mfma_f32_16x16x32_bf16 v[64:67], v[152:155], v[184:187], v[64:67]
	v_mfma_f32_16x16x32_bf16 v[116:119], v[148:151], v[164:167], v[116:119]
	v_mfma_f32_16x16x32_bf16 v[112:115], v[156:159], v[164:167], v[112:115]
	v_mfma_f32_16x16x32_bf16 v[100:103], v[148:151], v[172:175], v[100:103]
	v_mfma_f32_16x16x32_bf16 v[96:99], v[156:159], v[172:175], v[96:99]
	v_mfma_f32_16x16x32_bf16 v[84:87], v[148:151], v[180:183], v[84:87]
	v_mfma_f32_16x16x32_bf16 v[80:83], v[156:159], v[180:183], v[80:83]
	v_mfma_f32_16x16x32_bf16 v[68:71], v[148:151], v[188:191], v[68:71]
	v_mfma_f32_16x16x32_bf16 v[64:67], v[156:159], v[188:191], v[64:67]
	s_barrier
	s_add_i32 s48, s77, s59
	s_mov_b32 m0, s48
	ds_read_b128 v[160:163], v238 offset:49152
	global_load_lds_dwordx4 v194, s[98:99]
	s_add_i32 m0, s48, 0x2000
	s_add_u32 s48, s50, 0xb0080
	s_addc_u32 s49, s51, 0
	s_add_i32 s50, s78, s59
	global_load_lds_dwordx4 v198, s[98:99]
	s_mov_b32 m0, s50
	ds_read_b128 v[164:167], v238 offset:50176
	global_load_lds_dwordx4 v194, s[48:49]
	s_add_i32 m0, s50, 0x2000
	ds_read_b128 v[168:171], v238 offset:51200
	global_load_lds_dwordx4 v198, s[48:49]
	s_mov_b32 m0, s65
	ds_read_b128 v[172:175], v238 offset:52224
	global_load_lds_dwordx4 v192, s[100:101]
	s_mov_b32 m0, s67
	ds_read_b128 v[176:179], v238 offset:53248
	global_load_lds_dwordx4 v196, s[100:101]
	ds_read_b128 v[180:183], v238 offset:54272
	ds_read_b128 v[184:187], v238 offset:55296
	ds_read_b128 v[188:191], v238 offset:56320
	s_waitcnt vmcnt(8) lgkmcnt(0)
	s_barrier
	v_mfma_f32_16x16x32_bf16 v[60:63], v[128:131], v[160:163], v[60:63]
	v_mfma_f32_16x16x32_bf16 v[56:59], v[136:139], v[160:163], v[56:59]
	v_mfma_f32_16x16x32_bf16 v[44:47], v[128:131], v[168:171], v[44:47]
	v_mfma_f32_16x16x32_bf16 v[40:43], v[136:139], v[168:171], v[40:43]
	v_mfma_f32_16x16x32_bf16 v[28:31], v[128:131], v[176:179], v[28:31]
	v_mfma_f32_16x16x32_bf16 v[24:27], v[136:139], v[176:179], v[24:27]
	v_mfma_f32_16x16x32_bf16 v[12:15], v[128:131], v[184:187], v[12:15]
	v_mfma_f32_16x16x32_bf16 v[8:11], v[136:139], v[184:187], v[8:11]
	v_mfma_f32_16x16x32_bf16 v[60:63], v[132:135], v[164:167], v[60:63]
	v_mfma_f32_16x16x32_bf16 v[56:59], v[140:143], v[164:167], v[56:59]
	v_mfma_f32_16x16x32_bf16 v[44:47], v[132:135], v[172:175], v[44:47]
	v_mfma_f32_16x16x32_bf16 v[40:43], v[140:143], v[172:175], v[40:43]
	v_mfma_f32_16x16x32_bf16 v[28:31], v[132:135], v[180:183], v[28:31]
	v_mfma_f32_16x16x32_bf16 v[24:27], v[140:143], v[180:183], v[24:27]
	v_mfma_f32_16x16x32_bf16 v[12:15], v[132:135], v[188:191], v[12:15]
	v_mfma_f32_16x16x32_bf16 v[8:11], v[140:143], v[188:191], v[8:11]
	v_mfma_f32_16x16x32_bf16 v[52:55], v[144:147], v[160:163], v[52:55]
	v_mfma_f32_16x16x32_bf16 v[48:51], v[152:155], v[160:163], v[48:51]
	v_mfma_f32_16x16x32_bf16 v[36:39], v[144:147], v[168:171], v[36:39]
	v_mfma_f32_16x16x32_bf16 v[32:35], v[152:155], v[168:171], v[32:35]
	v_mfma_f32_16x16x32_bf16 v[20:23], v[144:147], v[176:179], v[20:23]
	v_mfma_f32_16x16x32_bf16 v[16:19], v[152:155], v[176:179], v[16:19]
	v_mfma_f32_16x16x32_bf16 v[4:7], v[144:147], v[184:187], v[4:7]
	v_mfma_f32_16x16x32_bf16 v[0:3], v[152:155], v[184:187], v[0:3]
	v_mfma_f32_16x16x32_bf16 v[52:55], v[148:151], v[164:167], v[52:55]
	v_mfma_f32_16x16x32_bf16 v[48:51], v[156:159], v[164:167], v[48:51]
	v_mfma_f32_16x16x32_bf16 v[36:39], v[148:151], v[172:175], v[36:39]
	v_mfma_f32_16x16x32_bf16 v[32:35], v[156:159], v[172:175], v[32:35]
	v_mfma_f32_16x16x32_bf16 v[20:23], v[148:151], v[180:183], v[20:23]
	v_mfma_f32_16x16x32_bf16 v[16:19], v[156:159], v[180:183], v[16:19]
	v_mfma_f32_16x16x32_bf16 v[4:7], v[148:151], v[188:191], v[4:7]
	v_mfma_f32_16x16x32_bf16 v[0:3], v[156:159], v[188:191], v[0:3]
	s_barrier
	s_add_i32 s76, s76, 2
	s_add_u32 s12, s12, 0x100
	s_addc_u32 s75, s75, 0
	s_cmp_gt_u32 s76, 41
	s_mov_b64 s[48:49], s[6:7]
	s_cbranch_scc0 .LBB0_461
	s_and_b64 vcc, exec, s[24:25]
	s_cbranch_vccz .LBB0_464
	s_barrier

; #define PG8_STAGE(bufoff, gbase, voff) do { _Pragma("unroll") for (int _i = 0; _i < 2; ++_i) \
;         __builtin_amdgcn_global_load_lds((const unsigned*)((const char*)(gbase) + (voff)[_i]), (PG8_LAS unsigned*)(lds + (bufoff) + ldsw + _i * 8192), 16, 0, 0); } while (0)
; #define PG8_LDA(dst, b, h) do { _Pragma("unroll") for (int m = 0; m < 4; ++m) _Pragma("unroll") for (int k = 0; k < 2; ++k) dst[m][k] = *(const PG8_LAS bf16x8*)(lds + PG8_SA(b, h) + aoff + m * 2048 + k * 1024); } while (0)
; #define PG8_LDB(dst, b, h) do { _Pragma("unroll") for (int n = 0; n < 2; ++n) _Pragma("unroll") for (int k = 0; k < 2; ++k) dst[n][k] = *(const PG8_LAS bf16x8*)(lds + PG8_SB(b, h) + boff + n * 2048 + k * 1024); } while (0)
; #define PG8_WAIT_V(n) asm volatile("s_waitcnt vmcnt(" #n ")" ::: "memory")
; #define PG8_WAIT_L(n) asm volatile("s_waitcnt lgkmcnt(" #n ")" ::: "memory")
; #define PG8_BAR __builtin_amdgcn_s_barrier()
; #define PG8_SCHED __builtin_amdgcn_sched_barrier(0)
; template <class Epi, class Sched, bool ALIGN_EPI = false, bool SP2 = false>
; __device__ __forceinline__ void gemm_phase(PG8_LAS unsigned char* lds, const Gemm g, const Sched& S, const Epi& E, int tid_in) {
;     ...
;         const char* nA = has_next ? (const char*)g.A + (size_t)nxt.pm * tstep : cA; const char* nB = has_next ? (const char*)g.Bt + (size_t)nxt.pn * tstep : cB;
;         for (int t = 0; t < nt; t += 2) {
;             if constexpr (Epi::MIDK) { if (t == Epi::MIDK_T) { if (wr == 0) PG8_BAR; E.mid(acc, cur, wr, wc, fr, fq); if (wr == 1) PG8_BAR; } }
;             const bool last = (t == nt - 2);
;             const char* a1 = cA + (size_t)(t + 1) * kstep;
;             const char* a2 = last ? nA : cA + (size_t)(t + 2) * kstep; const char* b2 = last ? nB : cB + (size_t)(t + 2) * kstep;
;             const char* a3 = a2 + kstep; const char* b3 = b2 + kstep;
;             if (last && has_next) S.a_ready(nxt);
;             if constexpr (SP2) {
;             PG8_LDB(B0, 0, 0); PG8_LDB(B1, 0, 1); PG8_SCHED; PG8_LDA(At, 0, 0); PG8_STAGE(PG8_SA(1, 1), a1 + hstep, voffA);
;             PG8_WAIT_V(8); PG8_WAIT_L(0); PG8_BAR; PG8_MMA(0, 0, At, B0); PG8_MMA(0, 1, At, B1); PG8_BAR; PG8_SCHED;
;             PG8_LDA(At, 0, 1); PG8_STAGE(PG8_SB(0, 0), b2, voffB); PG8_STAGE(PG8_SB(0, 1), b2 + hstep, voffB); PG8_STAGE(PG8_SA(0, 0), a2, voffA);
.LBB0_563:
	s_ashr_i32 s35, s34, 31
	s_lshl_b64 s[0:1], s[34:35], 19
	s_add_u32 s36, s54, s0
	s_addc_u32 s37, s55, s1
	s_and_b64 s[0:1], s[4:5], exec
	s_cselect_b32 s0, s37, s47
	s_cselect_b32 s1, s36, s46
	s_ashr_i32 s31, s30, 31
	s_lshl_b64 s[38:39], s[30:31], 19
	s_add_u32 s38, s56, s38
	s_addc_u32 s39, s57, s39
	s_and_b64 s[50:51], s[4:5], exec
	s_cselect_b32 s7, s39, s49
	s_cselect_b32 s31, s38, s48
	s_add_u32 s46, s46, 0x40080
	s_addc_u32 s47, s47, 0
	s_add_u32 s35, s48, 0x100
	s_addc_u32 s45, s49, 0
	s_mov_b32 s52, -2
	s_add_u32 s48, s46, 0xfffc0080
	s_addc_u32 s49, s47, -1
	s_cmp_eq_u32 s52, 12
	s_cselect_b32 s51, s0, s49
	s_cselect_b32 s50, s1, s48
	s_cselect_b32 s49, s7, s45
	s_cselect_b32 s48, s31, s35
	s_add_i32 m0, s59, 0xc000
	ds_read_b128 v[128:131], v180
	global_load_lds_dwordx4 v158, s[46:47]
	s_add_i32 m0, s59, 0xe000
	ds_read_b128 v[132:135], v180 offset:1024
	global_load_lds_dwordx4 v160, s[46:47]
	ds_read_b128 v[136:139], v180 offset:2048
	ds_read_b128 v[140:143], v180 offset:3072
	ds_read_b128 v[166:169], v181
	ds_read_b128 v[170:173], v181 offset:1024
	ds_read_b128 v[174:177], v181 offset:2048
	ds_read_b128 v[184:187], v181 offset:3072
	ds_read_b128 v[188:191], v182
	ds_read_b128 v[192:195], v182 offset:1024
	ds_read_b128 v[196:199], v182 offset:2048
	ds_read_b128 v[200:203], v182 offset:3072
	ds_read_b128 v[204:207], v182 offset:4096
	ds_read_b128 v[208:211], v182 offset:5120
	ds_read_b128 v[212:215], v182 offset:6144
	ds_read_b128 v[216:219], v182 offset:7168
	s_waitcnt vmcnt(8) lgkmcnt(0)
	s_barrier
	v_mfma_f32_16x16x32_bf16 v[68:71], v[128:131], v[188:191], 0
	v_mfma_f32_16x16x32_bf16 v[56:59], v[136:139], v[188:191], 0
	v_mfma_f32_16x16x32_bf16 v[52:55], v[128:131], v[196:199], 0
	v_mfma_f32_16x16x32_bf16 v[48:51], v[136:139], v[196:199], 0
	v_mfma_f32_16x16x32_bf16 v[44:47], v[128:131], v[204:207], 0
	v_mfma_f32_16x16x32_bf16 v[40:43], v[136:139], v[204:207], 0
	v_mfma_f32_16x16x32_bf16 v[36:39], v[128:131], v[212:215], 0
	v_mfma_f32_16x16x32_bf16 v[32:35], v[136:139], v[212:215], 0
	v_mfma_f32_16x16x32_bf16 v[68:71], v[132:135], v[192:195], v[68:71]
	v_mfma_f32_16x16x32_bf16 v[56:59], v[140:143], v[192:195], v[56:59]
	v_mfma_f32_16x16x32_bf16 v[52:55], v[132:135], v[200:203], v[52:55]
	v_mfma_f32_16x16x32_bf16 v[48:51], v[140:143], v[200:203], v[48:51]
	v_mfma_f32_16x16x32_bf16 v[44:47], v[132:135], v[208:211], v[44:47]
	v_mfma_f32_16x16x32_bf16 v[40:43], v[140:143], v[208:211], v[40:43]
	v_mfma_f32_16x16x32_bf16 v[36:39], v[132:135], v[216:219], v[36:39]
	v_mfma_f32_16x16x32_bf16 v[32:35], v[140:143], v[216:219], v[32:35]
	v_mfma_f32_16x16x32_bf16 v[124:127], v[166:169], v[188:191], 0
	v_mfma_f32_16x16x32_bf16 v[120:123], v[174:177], v[188:191], 0
	v_mfma_f32_16x16x32_bf16 v[116:119], v[166:169], v[196:199], 0
	v_mfma_f32_16x16x32_bf16 v[112:115], v[174:177], v[196:199], 0
	v_mfma_f32_16x16x32_bf16 v[108:111], v[166:169], v[204:207], 0
	v_mfma_f32_16x16x32_bf16 v[104:107], v[174:177], v[204:207], 0
	v_mfma_f32_16x16x32_bf16 v[100:103], v[166:169], v[212:215], 0
	v_mfma_f32_16x16x32_bf16 v[96:99], v[174:177], v[212:215], 0
	v_mfma_f32_16x16x32_bf16 v[124:127], v[170:173], v[192:195], v[124:127]
	v_mfma_f32_16x16x32_bf16 v[120:123], v[184:187], v[192:195], v[120:123]
	v_mfma_f32_16x16x32_bf16 v[116:119], v[170:173], v[200:203], v[116:119]
	v_mfma_f32_16x16x32_bf16 v[112:115], v[184:187], v[200:203], v[112:115]
	v_mfma_f32_16x16x32_bf16 v[108:111], v[170:173], v[208:211], v[108:111]
	v_mfma_f32_16x16x32_bf16 v[104:107], v[184:187], v[208:211], v[104:107]
	v_mfma_f32_16x16x32_bf16 v[100:103], v[170:173], v[216:219], v[100:103]
	v_mfma_f32_16x16x32_bf16 v[96:99], v[184:187], v[216:219], v[96:99]
	s_barrier
	s_add_u32 s98, s48, s14
	s_addc_u32 s99, s49, s15
	s_add_u32 s100, s50, s14
	s_addc_u32 s101, s51, s15
	s_add_i32 s53, s77, s29
	s_mov_b32 m0, s53
	ds_read_b128 v[188:191], v182 offset:16384
	global_load_lds_dwordx4 v146, s[48:49]
	s_add_i32 m0, s53, 0x2000
	s_add_u32 s88, s48, 0x40000
	s_addc_u32 s89, s49, 0
	s_add_i32 s53, s78, s29
	global_load_lds_dwordx4 v150, s[48:49]
	s_mov_b32 m0, s53
	ds_read_b128 v[192:195], v182 offset:17408
	global_load_lds_dwordx4 v146, s[88:89]
	s_add_i32 m0, s53, 0x2000
	ds_read_b128 v[196:199], v182 offset:18432
	global_load_lds_dwordx4 v150, s[88:89]
	s_mov_b32 m0, s59
	ds_read_b128 v[200:203], v182 offset:19456
	global_load_lds_dwordx4 v144, s[50:51]
	s_mov_b32 m0, s60
	ds_read_b128 v[204:207], v182 offset:20480
	global_load_lds_dwordx4 v148, s[50:51]
	ds_read_b128 v[208:211], v182 offset:21504
	ds_read_b128 v[212:215], v182 offset:22528
	ds_read_b128 v[216:219], v182 offset:23552
	s_waitcnt vmcnt(8) lgkmcnt(0)
	s_barrier
; #define PG8_STAGE(bufoff, gbase, voff) do { _Pragma("unroll") for (int _i = 0; _i < 2; ++_i) \
;         __builtin_amdgcn_global_load_lds((const unsigned*)((const char*)(gbase) + (voff)[_i]), (PG8_LAS unsigned*)(lds + (bufoff) + ldsw + _i * 8192), 16, 0, 0); } while (0)
; #define PG8_LDA(dst, b, h) do { _Pragma("unroll") for (int m = 0; m < 4; ++m) _Pragma("unroll") for (int k = 0; k < 2; ++k) dst[m][k] = *(const PG8_LAS bf16x8*)(lds + PG8_SA(b, h) + aoff + m * 2048 + k * 1024); } while (0)
; #define PG8_LDB(dst, b, h) do { _Pragma("unroll") for (int n = 0; n < 2; ++n) _Pragma("unroll") for (int k = 0; k < 2; ++k) dst[n][k] = *(const PG8_LAS bf16x8*)(lds + PG8_SB(b, h) + boff + n * 2048 + k * 1024); } while (0)
; #define PG8_MMA(ai, bj, At, Bt) do { __builtin_amdgcn_s_setprio(1); _Pragma("unroll") for (int m = 0; m < 4; ++m) _Pragma("unroll") for (int n = 0; n < 2; ++n) _Pragma("unroll") for (int k = 0; k < 2; ++k) \
;         acc[ai][bj][m][n] = __builtin_amdgcn_mfma_f32_16x16x32_bf16(Bt[n][k], At[m][k], acc[ai][bj][m][n], 0, 0, 0); __builtin_amdgcn_s_setprio(0); } while (0)
; #define PG8_WAIT_V(n) asm volatile("s_waitcnt vmcnt(" #n ")" ::: "memory")
; #define PG8_WAIT_L(n) asm volatile("s_waitcnt lgkmcnt(" #n ")" ::: "memory")
; #define PG8_BAR __builtin_amdgcn_s_barrier()
; #define PG8_SCHED __builtin_amdgcn_sched_barrier(0)
; template <class Epi, class Sched, bool ALIGN_EPI = false, bool SP2 = false>
; __device__ __forceinline__ void gemm_phase(PG8_LAS unsigned char* lds, const Gemm g, const Sched& S, const Epi& E, int tid_in) {
;     ...
;             PG8_WAIT_V(8); PG8_WAIT_L(0); PG8_BAR; PG8_MMA(1, 0, At, B0); PG8_MMA(1, 1, At, B1); PG8_BAR; PG8_SCHED;
;             PG8_LDB(B0, 1, 0); PG8_LDB(B1, 1, 1); PG8_SCHED; PG8_LDA(At, 1, 0); PG8_STAGE(PG8_SA(0, 1), a2 + hstep, voffA);
;             PG8_WAIT_V(8); PG8_WAIT_L(0); PG8_BAR; PG8_MMA(0, 0, At, B0); PG8_MMA(0, 1, At, B1); PG8_BAR; PG8_SCHED;
	v_mfma_f32_16x16x32_bf16 v[28:31], v[128:131], v[188:191], 0
	v_mfma_f32_16x16x32_bf16 v[24:27], v[136:139], v[188:191], 0
	v_mfma_f32_16x16x32_bf16 v[20:23], v[128:131], v[196:199], 0
	v_mfma_f32_16x16x32_bf16 v[16:19], v[136:139], v[196:199], 0
	v_mfma_f32_16x16x32_bf16 v[12:15], v[128:131], v[204:207], 0
	v_mfma_f32_16x16x32_bf16 v[8:11], v[136:139], v[204:207], 0
	v_mfma_f32_16x16x32_bf16 v[4:7], v[128:131], v[212:215], 0
	v_mfma_f32_16x16x32_bf16 v[0:3], v[136:139], v[212:215], 0
	v_mfma_f32_16x16x32_bf16 v[28:31], v[132:135], v[192:195], v[28:31]
	v_mfma_f32_16x16x32_bf16 v[24:27], v[140:143], v[192:195], v[24:27]
	v_mfma_f32_16x16x32_bf16 v[20:23], v[132:135], v[200:203], v[20:23]
	v_mfma_f32_16x16x32_bf16 v[16:19], v[140:143], v[200:203], v[16:19]
	v_mfma_f32_16x16x32_bf16 v[12:15], v[132:135], v[208:211], v[12:15]
	v_mfma_f32_16x16x32_bf16 v[8:11], v[140:143], v[208:211], v[8:11]
	v_mfma_f32_16x16x32_bf16 v[4:7], v[132:135], v[216:219], v[4:7]
	v_mfma_f32_16x16x32_bf16 v[0:3], v[140:143], v[216:219], v[0:3]
	v_mfma_f32_16x16x32_bf16 v[92:95], v[166:169], v[188:191], 0
	v_mfma_f32_16x16x32_bf16 v[88:91], v[174:177], v[188:191], 0
	v_mfma_f32_16x16x32_bf16 v[84:87], v[166:169], v[196:199], 0
	v_mfma_f32_16x16x32_bf16 v[80:83], v[174:177], v[196:199], 0
	v_mfma_f32_16x16x32_bf16 v[76:79], v[166:169], v[204:207], 0
	v_mfma_f32_16x16x32_bf16 v[72:75], v[174:177], v[204:207], 0
	v_mfma_f32_16x16x32_bf16 v[64:67], v[166:169], v[212:215], 0
	v_mfma_f32_16x16x32_bf16 v[60:63], v[174:177], v[212:215], 0
	v_mfma_f32_16x16x32_bf16 v[92:95], v[170:173], v[192:195], v[92:95]
	v_mfma_f32_16x16x32_bf16 v[88:91], v[184:187], v[192:195], v[88:91]
	v_mfma_f32_16x16x32_bf16 v[84:87], v[170:173], v[200:203], v[84:87]
	v_mfma_f32_16x16x32_bf16 v[80:83], v[184:187], v[200:203], v[80:83]
	v_mfma_f32_16x16x32_bf16 v[76:79], v[170:173], v[208:211], v[76:79]
	v_mfma_f32_16x16x32_bf16 v[72:75], v[184:187], v[208:211], v[72:75]
	v_mfma_f32_16x16x32_bf16 v[64:67], v[170:173], v[216:219], v[64:67]
	v_mfma_f32_16x16x32_bf16 v[60:63], v[184:187], v[216:219], v[60:63]
	s_barrier
	s_add_i32 s53, 0, 0x18000
	s_add_i32 s88, 0, 0x1c000
	s_add_u32 s50, s50, 0x40000
	s_addc_u32 s51, s51, 0
	s_mov_b32 m0, s61
	s_nop 0
	global_load_lds_dwordx4 v144, s[50:51]
	s_mov_b32 m0, s62
	s_nop 0
	global_load_lds_dwordx4 v148, s[50:51]
	v_add_u32_e32 v140, s53, v179
	v_add_u32_e32 v184, s88, v179
	ds_read_b128 v[128:131], v140
	ds_read_b128 v[132:135], v140 offset:1024
	ds_read_b128 v[136:139], v140 offset:2048
	ds_read_b128 v[140:143], v140 offset:3072
	ds_read_b128 v[166:169], v184
	ds_read_b128 v[170:173], v184 offset:1024
	ds_read_b128 v[174:177], v184 offset:2048
	ds_read_b128 v[184:187], v184 offset:3072
	ds_read_b128 v[188:191], v182 offset:32768
	ds_read_b128 v[192:195], v182 offset:33792
	ds_read_b128 v[196:199], v182 offset:34816
	ds_read_b128 v[200:203], v182 offset:35840
	ds_read_b128 v[204:207], v182 offset:36864
	ds_read_b128 v[208:211], v182 offset:37888
	ds_read_b128 v[212:215], v182 offset:38912
	ds_read_b128 v[216:219], v182 offset:39936
	s_waitcnt vmcnt(8) lgkmcnt(0)
	s_barrier
	v_mfma_f32_16x16x32_bf16 v[68:71], v[128:131], v[188:191], v[68:71]
	v_mfma_f32_16x16x32_bf16 v[56:59], v[136:139], v[188:191], v[56:59]
	v_mfma_f32_16x16x32_bf16 v[52:55], v[128:131], v[196:199], v[52:55]
	v_mfma_f32_16x16x32_bf16 v[48:51], v[136:139], v[196:199], v[48:51]
	v_mfma_f32_16x16x32_bf16 v[44:47], v[128:131], v[204:207], v[44:47]
	v_mfma_f32_16x16x32_bf16 v[40:43], v[136:139], v[204:207], v[40:43]
	v_mfma_f32_16x16x32_bf16 v[36:39], v[128:131], v[212:215], v[36:39]
	v_mfma_f32_16x16x32_bf16 v[32:35], v[136:139], v[212:215], v[32:35]
	v_mfma_f32_16x16x32_bf16 v[68:71], v[132:135], v[192:195], v[68:71]
	v_mfma_f32_16x16x32_bf16 v[56:59], v[140:143], v[192:195], v[56:59]
	v_mfma_f32_16x16x32_bf16 v[52:55], v[132:135], v[200:203], v[52:55]
	v_mfma_f32_16x16x32_bf16 v[48:51], v[140:143], v[200:203], v[48:51]
	v_mfma_f32_16x16x32_bf16 v[44:47], v[132:135], v[208:211], v[44:47]
	v_mfma_f32_16x16x32_bf16 v[40:43], v[140:143], v[208:211], v[40:43]
	v_mfma_f32_16x16x32_bf16 v[36:39], v[132:135], v[216:219], v[36:39]
	v_mfma_f32_16x16x32_bf16 v[32:35], v[140:143], v[216:219], v[32:35]
	v_mfma_f32_16x16x32_bf16 v[124:127], v[166:169], v[188:191], v[124:127]
	v_mfma_f32_16x16x32_bf16 v[120:123], v[174:177], v[188:191], v[120:123]
	v_mfma_f32_16x16x32_bf16 v[116:119], v[166:169], v[196:199], v[116:119]
	v_mfma_f32_16x16x32_bf16 v[112:115], v[174:177], v[196:199], v[112:115]
	v_mfma_f32_16x16x32_bf16 v[108:111], v[166:169], v[204:207], v[108:111]
	v_mfma_f32_16x16x32_bf16 v[104:107], v[174:177], v[204:207], v[104:107]
	v_mfma_f32_16x16x32_bf16 v[100:103], v[166:169], v[212:215], v[100:103]
	v_mfma_f32_16x16x32_bf16 v[96:99], v[174:177], v[212:215], v[96:99]
	v_mfma_f32_16x16x32_bf16 v[124:127], v[170:173], v[192:195], v[124:127]
	v_mfma_f32_16x16x32_bf16 v[120:123], v[184:187], v[192:195], v[120:123]
	v_mfma_f32_16x16x32_bf16 v[116:119], v[170:173], v[200:203], v[116:119]
	v_mfma_f32_16x16x32_bf16 v[112:115], v[184:187], v[200:203], v[112:115]
	v_mfma_f32_16x16x32_bf16 v[108:111], v[170:173], v[208:211], v[108:111]
	v_mfma_f32_16x16x32_bf16 v[104:107], v[184:187], v[208:211], v[104:107]
	v_mfma_f32_16x16x32_bf16 v[100:103], v[170:173], v[216:219], v[100:103]
	v_mfma_f32_16x16x32_bf16 v[96:99], v[184:187], v[216:219], v[96:99]
	s_barrier
; #define PG8_STAGE(bufoff, gbase, voff) do { _Pragma("unroll") for (int _i = 0; _i < 2; ++_i) \
;         __builtin_amdgcn_global_load_lds((const unsigned*)((const char*)(gbase) + (voff)[_i]), (PG8_LAS unsigned*)(lds + (bufoff) + ldsw + _i * 8192), 16, 0, 0); } while (0)
; #define PG8_LDA(dst, b, h) do { _Pragma("unroll") for (int m = 0; m < 4; ++m) _Pragma("unroll") for (int k = 0; k < 2; ++k) dst[m][k] = *(const PG8_LAS bf16x8*)(lds + PG8_SA(b, h) + aoff + m * 2048 + k * 1024); } while (0)
; #define PG8_LDB(dst, b, h) do { _Pragma("unroll") for (int n = 0; n < 2; ++n) _Pragma("unroll") for (int k = 0; k < 2; ++k) dst[n][k] = *(const PG8_LAS bf16x8*)(lds + PG8_SB(b, h) + boff + n * 2048 + k * 1024); } while (0)
; #define PG8_WAIT_V(n) asm volatile("s_waitcnt vmcnt(" #n ")" ::: "memory")
; #define PG8_BAR __builtin_amdgcn_s_barrier()
; template <class Epi, class Sched, bool ALIGN_EPI = false, bool SP2 = false>
; __device__ __forceinline__ void gemm_phase(PG8_LAS unsigned char* lds, const Gemm g, const Sched& S, const Epi& E, int tid_in) {
;     ...
;             const char* a2 = last ? nA : cA + (size_t)(t + 2) * kstep; const char* b2 = last ? nB : cB + (size_t)(t + 2) * kstep;
;             const char* a3 = a2 + kstep; const char* b3 = b2 + kstep;
;             if (last && has_next) S.a_ready(nxt);
;             if constexpr (SP2) {
;             PG8_LDB(B0, 0, 0); PG8_LDB(B1, 0, 1); PG8_SCHED; PG8_LDA(At, 0, 0); PG8_STAGE(PG8_SA(1, 1), a1 + hstep, voffA);
;             PG8_WAIT_V(8); PG8_WAIT_L(0); PG8_BAR; PG8_MMA(0, 0, At, B0); PG8_MMA(0, 1, At, B1); PG8_BAR; PG8_SCHED;
;             PG8_LDA(At, 0, 1); PG8_STAGE(PG8_SB(0, 0), b2, voffB); PG8_STAGE(PG8_SB(0, 1), b2 + hstep, voffB); PG8_STAGE(PG8_SA(0, 0), a2, voffA);
;             PG8_WAIT_V(8); PG8_WAIT_L(0); PG8_BAR; PG8_MMA(1, 0, At, B0); PG8_MMA(1, 1, At, B1); PG8_BAR; PG8_SCHED;
;             PG8_LDB(B0, 1, 0); PG8_LDB(B1, 1, 1); PG8_SCHED; PG8_LDA(At, 1, 0); PG8_STAGE(PG8_SA(0, 1), a2 + hstep, voffA);
;             PG8_WAIT_V(8); PG8_WAIT_L(0); PG8_BAR; PG8_MMA(0, 0, At, B0); PG8_MMA(0, 1, At, B1); PG8_BAR; PG8_SCHED;
;             PG8_LDA(At, 1, 1); PG8_STAGE(PG8_SB(1, 0), b3, voffB); PG8_STAGE(PG8_SB(1, 1), b3 + hstep, voffB); PG8_STAGE(PG8_SA(1, 0), a3, voffA);
;             PG8_WAIT_V(8); PG8_WAIT_L(0); PG8_BAR; PG8_MMA(1, 0, At, B0); PG8_MMA(1, 1, At, B1); PG8_BAR; PG8_SCHED;
	s_add_i32 s50, s53, s29
	s_mov_b32 m0, s50
	ds_read_b128 v[188:191], v182 offset:49152
	global_load_lds_dwordx4 v146, s[98:99]
	s_add_i32 m0, s50, 0x2000
	s_add_u32 s48, s48, 0x40080
	s_addc_u32 s49, s49, 0
	s_add_i32 s50, s88, s29
	global_load_lds_dwordx4 v150, s[98:99]
	s_mov_b32 m0, s50
	ds_read_b128 v[192:195], v182 offset:50176
	global_load_lds_dwordx4 v146, s[48:49]
	s_add_i32 m0, s50, 0x2000
	ds_read_b128 v[196:199], v182 offset:51200
	global_load_lds_dwordx4 v150, s[48:49]
	s_mov_b32 m0, s63
	ds_read_b128 v[200:203], v182 offset:52224
	global_load_lds_dwordx4 v144, s[100:101]
	s_mov_b32 m0, s64
	ds_read_b128 v[204:207], v182 offset:53248
	global_load_lds_dwordx4 v148, s[100:101]
	ds_read_b128 v[208:211], v182 offset:54272
	ds_read_b128 v[212:215], v182 offset:55296
	ds_read_b128 v[216:219], v182 offset:56320
	s_waitcnt vmcnt(8) lgkmcnt(0)
	s_barrier
	v_mfma_f32_16x16x32_bf16 v[28:31], v[128:131], v[188:191], v[28:31]
	v_mfma_f32_16x16x32_bf16 v[24:27], v[136:139], v[188:191], v[24:27]
	v_mfma_f32_16x16x32_bf16 v[20:23], v[128:131], v[196:199], v[20:23]
	v_mfma_f32_16x16x32_bf16 v[16:19], v[136:139], v[196:199], v[16:19]
	v_mfma_f32_16x16x32_bf16 v[12:15], v[128:131], v[204:207], v[12:15]
	v_mfma_f32_16x16x32_bf16 v[8:11], v[136:139], v[204:207], v[8:11]
	v_mfma_f32_16x16x32_bf16 v[4:7], v[128:131], v[212:215], v[4:7]
	v_mfma_f32_16x16x32_bf16 v[0:3], v[136:139], v[212:215], v[0:3]
	v_mfma_f32_16x16x32_bf16 v[28:31], v[132:135], v[192:195], v[28:31]
	v_mfma_f32_16x16x32_bf16 v[24:27], v[140:143], v[192:195], v[24:27]
	v_mfma_f32_16x16x32_bf16 v[20:23], v[132:135], v[200:203], v[20:23]
	v_mfma_f32_16x16x32_bf16 v[16:19], v[140:143], v[200:203], v[16:19]
	v_mfma_f32_16x16x32_bf16 v[12:15], v[132:135], v[208:211], v[12:15]
	v_mfma_f32_16x16x32_bf16 v[8:11], v[140:143], v[208:211], v[8:11]
	v_mfma_f32_16x16x32_bf16 v[4:7], v[132:135], v[216:219], v[4:7]
	v_mfma_f32_16x16x32_bf16 v[0:3], v[140:143], v[216:219], v[0:3]
	v_mfma_f32_16x16x32_bf16 v[92:95], v[166:169], v[188:191], v[92:95]
	v_mfma_f32_16x16x32_bf16 v[88:91], v[174:177], v[188:191], v[88:91]
	v_mfma_f32_16x16x32_bf16 v[84:87], v[166:169], v[196:199], v[84:87]
	v_mfma_f32_16x16x32_bf16 v[80:83], v[174:177], v[196:199], v[80:83]
	v_mfma_f32_16x16x32_bf16 v[76:79], v[166:169], v[204:207], v[76:79]
	v_mfma_f32_16x16x32_bf16 v[72:75], v[174:177], v[204:207], v[72:75]
	v_mfma_f32_16x16x32_bf16 v[64:67], v[166:169], v[212:215], v[64:67]
	v_mfma_f32_16x16x32_bf16 v[60:63], v[174:177], v[212:215], v[60:63]
	v_mfma_f32_16x16x32_bf16 v[92:95], v[170:173], v[192:195], v[92:95]
	v_mfma_f32_16x16x32_bf16 v[88:91], v[184:187], v[192:195], v[88:91]
	v_mfma_f32_16x16x32_bf16 v[84:87], v[170:173], v[200:203], v[84:87]
	v_mfma_f32_16x16x32_bf16 v[80:83], v[184:187], v[200:203], v[80:83]
	v_mfma_f32_16x16x32_bf16 v[76:79], v[170:173], v[208:211], v[76:79]
	v_mfma_f32_16x16x32_bf16 v[72:75], v[184:187], v[208:211], v[72:75]
	v_mfma_f32_16x16x32_bf16 v[64:67], v[170:173], v[216:219], v[64:67]
	v_mfma_f32_16x16x32_bf16 v[60:63], v[184:187], v[216:219], v[60:63]
	s_barrier
	s_add_i32 s52, s52, 2
	s_add_u32 s46, s46, 0x100
	s_addc_u32 s47, s47, 0
	s_add_u32 s35, s35, 0x100
	s_addc_u32 s45, s45, 0
.LBB0_564:
	s_add_u32 s48, s46, 0xfffc0080
	s_addc_u32 s49, s47, -1
	s_cmp_eq_u32 s52, 12
	s_cselect_b32 s51, s0, s49
	s_cselect_b32 s50, s1, s48
	s_cselect_b32 s49, s7, s45
	s_cselect_b32 s48, s31, s35
	s_add_i32 m0, s59, 0xc000
	ds_read_b128 v[128:131], v180
	global_load_lds_dwordx4 v158, s[46:47]
	s_add_i32 m0, s59, 0xe000
	ds_read_b128 v[132:135], v180 offset:1024
	global_load_lds_dwordx4 v160, s[46:47]
	ds_read_b128 v[136:139], v180 offset:2048
	ds_read_b128 v[140:143], v180 offset:3072
	ds_read_b128 v[166:169], v181
	ds_read_b128 v[170:173], v181 offset:1024
	ds_read_b128 v[174:177], v181 offset:2048
	ds_read_b128 v[184:187], v181 offset:3072
	ds_read_b128 v[188:191], v182
	ds_read_b128 v[192:195], v182 offset:1024
	ds_read_b128 v[196:199], v182 offset:2048
	ds_read_b128 v[200:203], v182 offset:3072
	ds_read_b128 v[204:207], v182 offset:4096
	ds_read_b128 v[208:211], v182 offset:5120
	ds_read_b128 v[212:215], v182 offset:6144
	ds_read_b128 v[216:219], v182 offset:7168
	s_waitcnt vmcnt(8) lgkmcnt(0)
	s_barrier
	v_mfma_f32_16x16x32_bf16 v[68:71], v[128:131], v[188:191], v[68:71]
	v_mfma_f32_16x16x32_bf16 v[56:59], v[136:139], v[188:191], v[56:59]
	v_mfma_f32_16x16x32_bf16 v[52:55], v[128:131], v[196:199], v[52:55]
	v_mfma_f32_16x16x32_bf16 v[48:51], v[136:139], v[196:199], v[48:51]
	v_mfma_f32_16x16x32_bf16 v[44:47], v[128:131], v[204:207], v[44:47]
	v_mfma_f32_16x16x32_bf16 v[40:43], v[136:139], v[204:207], v[40:43]
	v_mfma_f32_16x16x32_bf16 v[36:39], v[128:131], v[212:215], v[36:39]
	v_mfma_f32_16x16x32_bf16 v[32:35], v[136:139], v[212:215], v[32:35]
	v_mfma_f32_16x16x32_bf16 v[68:71], v[132:135], v[192:195], v[68:71]
	v_mfma_f32_16x16x32_bf16 v[56:59], v[140:143], v[192:195], v[56:59]
	v_mfma_f32_16x16x32_bf16 v[52:55], v[132:135], v[200:203], v[52:55]
	v_mfma_f32_16x16x32_bf16 v[48:51], v[140:143], v[200:203], v[48:51]
	v_mfma_f32_16x16x32_bf16 v[44:47], v[132:135], v[208:211], v[44:47]
	v_mfma_f32_16x16x32_bf16 v[40:43], v[140:143], v[208:211], v[40:43]
	v_mfma_f32_16x16x32_bf16 v[36:39], v[132:135], v[216:219], v[36:39]
	v_mfma_f32_16x16x32_bf16 v[32:35], v[140:143], v[216:219], v[32:35]
	v_mfma_f32_16x16x32_bf16 v[124:127], v[166:169], v[188:191], v[124:127]
	v_mfma_f32_16x16x32_bf16 v[120:123], v[174:177], v[188:191], v[120:123]
	v_mfma_f32_16x16x32_bf16 v[116:119], v[166:169], v[196:199], v[116:119]
	v_mfma_f32_16x16x32_bf16 v[112:115], v[174:177], v[196:199], v[112:115]
	v_mfma_f32_16x16x32_bf16 v[108:111], v[166:169], v[204:207], v[108:111]
	v_mfma_f32_16x16x32_bf16 v[104:107], v[174:177], v[204:207], v[104:107]
	v_mfma_f32_16x16x32_bf16 v[100:103], v[166:169], v[212:215], v[100:103]
	v_mfma_f32_16x16x32_bf16 v[96:99], v[174:177], v[212:215], v[96:99]
	v_mfma_f32_16x16x32_bf16 v[124:127], v[170:173], v[192:195], v[124:127]
	v_mfma_f32_16x16x32_bf16 v[120:123], v[184:187], v[192:195], v[120:123]
	v_mfma_f32_16x16x32_bf16 v[116:119], v[170:173], v[200:203], v[116:119]
	v_mfma_f32_16x16x32_bf16 v[112:115], v[184:187], v[200:203], v[112:115]
	v_mfma_f32_16x16x32_bf16 v[108:111], v[170:173], v[208:211], v[108:111]
	v_mfma_f32_16x16x32_bf16 v[104:107], v[184:187], v[208:211], v[104:107]
	v_mfma_f32_16x16x32_bf16 v[100:103], v[170:173], v[216:219], v[100:103]
	v_mfma_f32_16x16x32_bf16 v[96:99], v[184:187], v[216:219], v[96:99]
	s_barrier
; #define PG8_STAGE(bufoff, gbase, voff) do { _Pragma("unroll") for (int _i = 0; _i < 2; ++_i) \
;         __builtin_amdgcn_global_load_lds((const unsigned*)((const char*)(gbase) + (voff)[_i]), (PG8_LAS unsigned*)(lds + (bufoff) + ldsw + _i * 8192), 16, 0, 0); } while (0)
; #define PG8_LDA(dst, b, h) do { _Pragma("unroll") for (int m = 0; m < 4; ++m) _Pragma("unroll") for (int k = 0; k < 2; ++k) dst[m][k] = *(const PG8_LAS bf16x8*)(lds + PG8_SA(b, h) + aoff + m * 2048 + k * 1024); } while (0)
; #define PG8_LDB(dst, b, h) do { _Pragma("unroll") for (int n = 0; n < 2; ++n) _Pragma("unroll") for (int k = 0; k < 2; ++k) dst[n][k] = *(const PG8_LAS bf16x8*)(lds + PG8_SB(b, h) + boff + n * 2048 + k * 1024); } while (0)
; #define PG8_MMA(ai, bj, At, Bt) do { __builtin_amdgcn_s_setprio(1); _Pragma("unroll") for (int m = 0; m < 4; ++m) _Pragma("unroll") for (int n = 0; n < 2; ++n) _Pragma("unroll") for (int k = 0; k < 2; ++k) \
;         acc[ai][bj][m][n] = __builtin_amdgcn_mfma_f32_16x16x32_bf16(Bt[n][k], At[m][k], acc[ai][bj][m][n], 0, 0, 0); __builtin_amdgcn_s_setprio(0); } while (0)
; #define PG8_WAIT_V(n) asm volatile("s_waitcnt vmcnt(" #n ")" ::: "memory")
; #define PG8_WAIT_L(n) asm volatile("s_waitcnt lgkmcnt(" #n ")" ::: "memory")
; #define PG8_BAR __builtin_amdgcn_s_barrier()
; #define PG8_SCHED __builtin_amdgcn_sched_barrier(0)
; template <class Epi, class Sched, bool ALIGN_EPI = false, bool SP2 = false>
; __device__ __forceinline__ void gemm_phase(PG8_LAS unsigned char* lds, const Gemm g, const Sched& S, const Epi& E, int tid_in) {
;     ...
;             PG8_LDA(At, 0, 1); PG8_STAGE(PG8_SB(0, 0), b2, voffB); PG8_STAGE(PG8_SB(0, 1), b2 + hstep, voffB); PG8_STAGE(PG8_SA(0, 0), a2, voffA);
;             PG8_WAIT_V(8); PG8_WAIT_L(0); PG8_BAR; PG8_MMA(1, 0, At, B0); PG8_MMA(1, 1, At, B1); PG8_BAR; PG8_SCHED;
;             PG8_LDB(B0, 1, 0); PG8_LDB(B1, 1, 1); PG8_SCHED; PG8_LDA(At, 1, 0); PG8_STAGE(PG8_SA(0, 1), a2 + hstep, voffA);
	s_add_u32 s98, s48, s14
	s_addc_u32 s99, s49, s15
	s_add_u32 s100, s50, s14
	s_addc_u32 s101, s51, s15
	s_add_i32 s53, s77, s29
	s_mov_b32 m0, s53
	ds_read_b128 v[188:191], v182 offset:16384
	global_load_lds_dwordx4 v146, s[48:49]
	s_add_i32 m0, s53, 0x2000
	s_add_u32 s88, s48, 0x40000
	s_addc_u32 s89, s49, 0
	s_add_i32 s53, s78, s29
	global_load_lds_dwordx4 v150, s[48:49]
	s_mov_b32 m0, s53
	ds_read_b128 v[192:195], v182 offset:17408
	global_load_lds_dwordx4 v146, s[88:89]
	s_add_i32 m0, s53, 0x2000
	ds_read_b128 v[196:199], v182 offset:18432
	global_load_lds_dwordx4 v150, s[88:89]
	s_mov_b32 m0, s59
	ds_read_b128 v[200:203], v182 offset:19456
	global_load_lds_dwordx4 v144, s[50:51]
	s_mov_b32 m0, s60
	ds_read_b128 v[204:207], v182 offset:20480
	global_load_lds_dwordx4 v148, s[50:51]
	ds_read_b128 v[208:211], v182 offset:21504
	ds_read_b128 v[212:215], v182 offset:22528
	ds_read_b128 v[216:219], v182 offset:23552
	s_waitcnt vmcnt(8) lgkmcnt(0)
	s_barrier
	v_mfma_f32_16x16x32_bf16 v[28:31], v[128:131], v[188:191], v[28:31]
	v_mfma_f32_16x16x32_bf16 v[24:27], v[136:139], v[188:191], v[24:27]
	v_mfma_f32_16x16x32_bf16 v[20:23], v[128:131], v[196:199], v[20:23]
	v_mfma_f32_16x16x32_bf16 v[16:19], v[136:139], v[196:199], v[16:19]
	v_mfma_f32_16x16x32_bf16 v[12:15], v[128:131], v[204:207], v[12:15]
	v_mfma_f32_16x16x32_bf16 v[8:11], v[136:139], v[204:207], v[8:11]
	v_mfma_f32_16x16x32_bf16 v[4:7], v[128:131], v[212:215], v[4:7]
	v_mfma_f32_16x16x32_bf16 v[0:3], v[136:139], v[212:215], v[0:3]
	v_mfma_f32_16x16x32_bf16 v[28:31], v[132:135], v[192:195], v[28:31]
	v_mfma_f32_16x16x32_bf16 v[24:27], v[140:143], v[192:195], v[24:27]
	v_mfma_f32_16x16x32_bf16 v[20:23], v[132:135], v[200:203], v[20:23]
	v_mfma_f32_16x16x32_bf16 v[16:19], v[140:143], v[200:203], v[16:19]
	v_mfma_f32_16x16x32_bf16 v[12:15], v[132:135], v[208:211], v[12:15]
	v_mfma_f32_16x16x32_bf16 v[8:11], v[140:143], v[208:211], v[8:11]
	v_mfma_f32_16x16x32_bf16 v[4:7], v[132:135], v[216:219], v[4:7]
	v_mfma_f32_16x16x32_bf16 v[0:3], v[140:143], v[216:219], v[0:3]
	v_mfma_f32_16x16x32_bf16 v[92:95], v[166:169], v[188:191], v[92:95]
	v_mfma_f32_16x16x32_bf16 v[88:91], v[174:177], v[188:191], v[88:91]
	v_mfma_f32_16x16x32_bf16 v[84:87], v[166:169], v[196:199], v[84:87]
	v_mfma_f32_16x16x32_bf16 v[80:83], v[174:177], v[196:199], v[80:83]
	v_mfma_f32_16x16x32_bf16 v[76:79], v[166:169], v[204:207], v[76:79]
	v_mfma_f32_16x16x32_bf16 v[72:75], v[174:177], v[204:207], v[72:75]
	v_mfma_f32_16x16x32_bf16 v[64:67], v[166:169], v[212:215], v[64:67]
	v_mfma_f32_16x16x32_bf16 v[60:63], v[174:177], v[212:215], v[60:63]
	v_mfma_f32_16x16x32_bf16 v[92:95], v[170:173], v[192:195], v[92:95]
	v_mfma_f32_16x16x32_bf16 v[88:91], v[184:187], v[192:195], v[88:91]
	v_mfma_f32_16x16x32_bf16 v[84:87], v[170:173], v[200:203], v[84:87]
	v_mfma_f32_16x16x32_bf16 v[80:83], v[184:187], v[200:203], v[80:83]
	v_mfma_f32_16x16x32_bf16 v[76:79], v[170:173], v[208:211], v[76:79]
	v_mfma_f32_16x16x32_bf16 v[72:75], v[184:187], v[208:211], v[72:75]
	v_mfma_f32_16x16x32_bf16 v[64:67], v[170:173], v[216:219], v[64:67]
	v_mfma_f32_16x16x32_bf16 v[60:63], v[184:187], v[216:219], v[60:63]
	s_barrier
	s_add_i32 s53, 0, 0x18000
	s_add_i32 s88, 0, 0x1c000
	s_add_u32 s50, s50, 0x40000
	s_addc_u32 s51, s51, 0
	s_mov_b32 m0, s61
	s_nop 0
	global_load_lds_dwordx4 v144, s[50:51]
	s_mov_b32 m0, s62
	s_nop 0
	global_load_lds_dwordx4 v148, s[50:51]
	v_add_u32_e32 v140, s53, v179
	v_add_u32_e32 v184, s88, v179
	ds_read_b128 v[128:131], v140
	ds_read_b128 v[132:135], v140 offset:1024
	ds_read_b128 v[136:139], v140 offset:2048
	ds_read_b128 v[140:143], v140 offset:3072
	ds_read_b128 v[166:169], v184
	ds_read_b128 v[170:173], v184 offset:1024
	ds_read_b128 v[174:177], v184 offset:2048
	ds_read_b128 v[184:187], v184 offset:3072
	ds_read_b128 v[188:191], v182 offset:32768
	ds_read_b128 v[192:195], v182 offset:33792
	ds_read_b128 v[196:199], v182 offset:34816
	ds_read_b128 v[200:203], v182 offset:35840
	ds_read_b128 v[204:207], v182 offset:36864
	ds_read_b128 v[208:211], v182 offset:37888
	ds_read_b128 v[212:215], v182 offset:38912
	ds_read_b128 v[216:219], v182 offset:39936
	s_waitcnt vmcnt(8) lgkmcnt(0)
	s_barrier
; #define PG8_STAGE(bufoff, gbase, voff) do { _Pragma("unroll") for (int _i = 0; _i < 2; ++_i) \
;         __builtin_amdgcn_global_load_lds((const unsigned*)((const char*)(gbase) + (voff)[_i]), (PG8_LAS unsigned*)(lds + (bufoff) + ldsw + _i * 8192), 16, 0, 0); } while (0)
; #define PG8_LDA(dst, b, h) do { _Pragma("unroll") for (int m = 0; m < 4; ++m) _Pragma("unroll") for (int k = 0; k < 2; ++k) dst[m][k] = *(const PG8_LAS bf16x8*)(lds + PG8_SA(b, h) + aoff + m * 2048 + k * 1024); } while (0)
; #define PG8_LDB(dst, b, h) do { _Pragma("unroll") for (int n = 0; n < 2; ++n) _Pragma("unroll") for (int k = 0; k < 2; ++k) dst[n][k] = *(const PG8_LAS bf16x8*)(lds + PG8_SB(b, h) + boff + n * 2048 + k * 1024); } while (0)
; #define PG8_WAIT_V(n) asm volatile("s_waitcnt vmcnt(" #n ")" ::: "memory")
; #define PG8_WAIT_L(n) asm volatile("s_waitcnt lgkmcnt(" #n ")" ::: "memory")
; #define PG8_BAR __builtin_amdgcn_s_barrier()
; #define PG8_SCHED __builtin_amdgcn_sched_barrier(0)
; template <class Epi, class Sched, bool ALIGN_EPI = false, bool SP2 = false>
; __device__ __forceinline__ void gemm_phase(PG8_LAS unsigned char* lds, const Gemm g, const Sched& S, const Epi& E, int tid_in) {
;     ...
;             PG8_LDB(B0, 0, 0); PG8_LDB(B1, 0, 1); PG8_SCHED; PG8_LDA(At, 0, 0); PG8_STAGE(PG8_SA(1, 1), a1 + hstep, voffA);
;             PG8_WAIT_V(8); PG8_WAIT_L(0); PG8_BAR; PG8_MMA(0, 0, At, B0); PG8_MMA(0, 1, At, B1); PG8_BAR; PG8_SCHED;
;             PG8_LDA(At, 0, 1); PG8_STAGE(PG8_SB(0, 0), b2, voffB); PG8_STAGE(PG8_SB(0, 1), b2 + hstep, voffB); PG8_STAGE(PG8_SA(0, 0), a2, voffA);
;             PG8_WAIT_V(8); PG8_WAIT_L(0); PG8_BAR; PG8_MMA(1, 0, At, B0); PG8_MMA(1, 1, At, B1); PG8_BAR; PG8_SCHED;
;             PG8_LDB(B0, 1, 0); PG8_LDB(B1, 1, 1); PG8_SCHED; PG8_LDA(At, 1, 0); PG8_STAGE(PG8_SA(0, 1), a2 + hstep, voffA);
;             PG8_WAIT_V(8); PG8_WAIT_L(0); PG8_BAR; PG8_MMA(0, 0, At, B0); PG8_MMA(0, 1, At, B1); PG8_BAR; PG8_SCHED;
;             PG8_LDA(At, 1, 1); PG8_STAGE(PG8_SB(1, 0), b3, voffB); PG8_STAGE(PG8_SB(1, 1), b3 + hstep, voffB); PG8_STAGE(PG8_SA(1, 0), a3, voffA);
;             PG8_WAIT_V(8); PG8_WAIT_L(0); PG8_BAR; PG8_MMA(1, 0, At, B0); PG8_MMA(1, 1, At, B1); PG8_BAR; PG8_SCHED;
;     ...
;         }
;         if constexpr (ALIGN_EPI) { if (wr == 0) PG8_BAR; }
	v_mfma_f32_16x16x32_bf16 v[68:71], v[128:131], v[188:191], v[68:71]
	v_mfma_f32_16x16x32_bf16 v[56:59], v[136:139], v[188:191], v[56:59]
	v_mfma_f32_16x16x32_bf16 v[52:55], v[128:131], v[196:199], v[52:55]
	v_mfma_f32_16x16x32_bf16 v[48:51], v[136:139], v[196:199], v[48:51]
	v_mfma_f32_16x16x32_bf16 v[44:47], v[128:131], v[204:207], v[44:47]
	v_mfma_f32_16x16x32_bf16 v[40:43], v[136:139], v[204:207], v[40:43]
	v_mfma_f32_16x16x32_bf16 v[36:39], v[128:131], v[212:215], v[36:39]
	v_mfma_f32_16x16x32_bf16 v[32:35], v[136:139], v[212:215], v[32:35]
	v_mfma_f32_16x16x32_bf16 v[68:71], v[132:135], v[192:195], v[68:71]
	v_mfma_f32_16x16x32_bf16 v[56:59], v[140:143], v[192:195], v[56:59]
	v_mfma_f32_16x16x32_bf16 v[52:55], v[132:135], v[200:203], v[52:55]
	v_mfma_f32_16x16x32_bf16 v[48:51], v[140:143], v[200:203], v[48:51]
	v_mfma_f32_16x16x32_bf16 v[44:47], v[132:135], v[208:211], v[44:47]
	v_mfma_f32_16x16x32_bf16 v[40:43], v[140:143], v[208:211], v[40:43]
	v_mfma_f32_16x16x32_bf16 v[36:39], v[132:135], v[216:219], v[36:39]
	v_mfma_f32_16x16x32_bf16 v[32:35], v[140:143], v[216:219], v[32:35]
	v_mfma_f32_16x16x32_bf16 v[124:127], v[166:169], v[188:191], v[124:127]
	v_mfma_f32_16x16x32_bf16 v[120:123], v[174:177], v[188:191], v[120:123]
	v_mfma_f32_16x16x32_bf16 v[116:119], v[166:169], v[196:199], v[116:119]
	v_mfma_f32_16x16x32_bf16 v[112:115], v[174:177], v[196:199], v[112:115]
	v_mfma_f32_16x16x32_bf16 v[108:111], v[166:169], v[204:207], v[108:111]
	v_mfma_f32_16x16x32_bf16 v[104:107], v[174:177], v[204:207], v[104:107]
	v_mfma_f32_16x16x32_bf16 v[100:103], v[166:169], v[212:215], v[100:103]
	v_mfma_f32_16x16x32_bf16 v[96:99], v[174:177], v[212:215], v[96:99]
	v_mfma_f32_16x16x32_bf16 v[124:127], v[170:173], v[192:195], v[124:127]
	v_mfma_f32_16x16x32_bf16 v[120:123], v[184:187], v[192:195], v[120:123]
	v_mfma_f32_16x16x32_bf16 v[116:119], v[170:173], v[200:203], v[116:119]
	v_mfma_f32_16x16x32_bf16 v[112:115], v[184:187], v[200:203], v[112:115]
	v_mfma_f32_16x16x32_bf16 v[108:111], v[170:173], v[208:211], v[108:111]
	v_mfma_f32_16x16x32_bf16 v[104:107], v[184:187], v[208:211], v[104:107]
	v_mfma_f32_16x16x32_bf16 v[100:103], v[170:173], v[216:219], v[100:103]
	v_mfma_f32_16x16x32_bf16 v[96:99], v[184:187], v[216:219], v[96:99]
	s_barrier
	s_add_i32 s50, s53, s29
	s_mov_b32 m0, s50
	ds_read_b128 v[188:191], v182 offset:49152
	global_load_lds_dwordx4 v146, s[98:99]
	s_add_i32 m0, s50, 0x2000
	s_add_u32 s48, s48, 0x40080
	s_addc_u32 s49, s49, 0
	s_add_i32 s50, s88, s29
	global_load_lds_dwordx4 v150, s[98:99]
	s_mov_b32 m0, s50
	ds_read_b128 v[192:195], v182 offset:50176
	global_load_lds_dwordx4 v146, s[48:49]
	s_add_i32 m0, s50, 0x2000
	ds_read_b128 v[196:199], v182 offset:51200
	global_load_lds_dwordx4 v150, s[48:49]
	s_mov_b32 m0, s63
	ds_read_b128 v[200:203], v182 offset:52224
	global_load_lds_dwordx4 v144, s[100:101]
	s_mov_b32 m0, s64
	ds_read_b128 v[204:207], v182 offset:53248
	global_load_lds_dwordx4 v148, s[100:101]
	ds_read_b128 v[208:211], v182 offset:54272
	ds_read_b128 v[212:215], v182 offset:55296
	ds_read_b128 v[216:219], v182 offset:56320
	s_waitcnt vmcnt(8) lgkmcnt(0)
	s_barrier
	v_mfma_f32_16x16x32_bf16 v[28:31], v[128:131], v[188:191], v[28:31]
	v_mfma_f32_16x16x32_bf16 v[24:27], v[136:139], v[188:191], v[24:27]
	v_mfma_f32_16x16x32_bf16 v[20:23], v[128:131], v[196:199], v[20:23]
	v_mfma_f32_16x16x32_bf16 v[16:19], v[136:139], v[196:199], v[16:19]
	v_mfma_f32_16x16x32_bf16 v[12:15], v[128:131], v[204:207], v[12:15]
	v_mfma_f32_16x16x32_bf16 v[8:11], v[136:139], v[204:207], v[8:11]
	v_mfma_f32_16x16x32_bf16 v[4:7], v[128:131], v[212:215], v[4:7]
	v_mfma_f32_16x16x32_bf16 v[0:3], v[136:139], v[212:215], v[0:3]
	v_mfma_f32_16x16x32_bf16 v[28:31], v[132:135], v[192:195], v[28:31]
	v_mfma_f32_16x16x32_bf16 v[24:27], v[140:143], v[192:195], v[24:27]
	v_mfma_f32_16x16x32_bf16 v[20:23], v[132:135], v[200:203], v[20:23]
	v_mfma_f32_16x16x32_bf16 v[16:19], v[140:143], v[200:203], v[16:19]
	v_mfma_f32_16x16x32_bf16 v[12:15], v[132:135], v[208:211], v[12:15]
	v_mfma_f32_16x16x32_bf16 v[8:11], v[140:143], v[208:211], v[8:11]
	v_mfma_f32_16x16x32_bf16 v[4:7], v[132:135], v[216:219], v[4:7]
	v_mfma_f32_16x16x32_bf16 v[0:3], v[140:143], v[216:219], v[0:3]
	v_mfma_f32_16x16x32_bf16 v[92:95], v[166:169], v[188:191], v[92:95]
	v_mfma_f32_16x16x32_bf16 v[88:91], v[174:177], v[188:191], v[88:91]
	v_mfma_f32_16x16x32_bf16 v[84:87], v[166:169], v[196:199], v[84:87]
	v_mfma_f32_16x16x32_bf16 v[80:83], v[174:177], v[196:199], v[80:83]
	v_mfma_f32_16x16x32_bf16 v[76:79], v[166:169], v[204:207], v[76:79]
	v_mfma_f32_16x16x32_bf16 v[72:75], v[174:177], v[204:207], v[72:75]
	v_mfma_f32_16x16x32_bf16 v[64:67], v[166:169], v[212:215], v[64:67]
	v_mfma_f32_16x16x32_bf16 v[60:63], v[174:177], v[212:215], v[60:63]
	v_mfma_f32_16x16x32_bf16 v[92:95], v[170:173], v[192:195], v[92:95]
	v_mfma_f32_16x16x32_bf16 v[88:91], v[184:187], v[192:195], v[88:91]
	v_mfma_f32_16x16x32_bf16 v[84:87], v[170:173], v[200:203], v[84:87]
	v_mfma_f32_16x16x32_bf16 v[80:83], v[184:187], v[200:203], v[80:83]
	v_mfma_f32_16x16x32_bf16 v[76:79], v[170:173], v[208:211], v[76:79]
	v_mfma_f32_16x16x32_bf16 v[72:75], v[184:187], v[208:211], v[72:75]
	v_mfma_f32_16x16x32_bf16 v[64:67], v[170:173], v[216:219], v[64:67]
	v_mfma_f32_16x16x32_bf16 v[60:63], v[184:187], v[216:219], v[60:63]
	s_barrier
	s_add_i32 s52, s52, 2
	s_add_u32 s46, s46, 0x100
	s_addc_u32 s47, s47, 0
	s_add_u32 s35, s35, 0x100
	s_addc_u32 s45, s45, 0
	s_cmp_gt_u32 s52, 13
	s_cbranch_scc0 .LBB0_564
	s_cmp_eq_u32 s86, 1
	s_cbranch_scc0 .Lww_done_p3
	v_readlane_b32 s98, v248, 0
	s_nop 3
	s_cmp_eq_u32 s98, 0
	s_cbranch_scc0 .Lww_bar_p3
	v_readlane_b32 s98, v248, 32
	s_nop 3
	s_cmp_eq_u32 s98, 1
	s_cbranch_scc0 .Lww_bar_p3
	v_mov_b32_e32 v246, 0x3500
	s_mov_b32 s98, 0

; #define PG8_STAGE(bufoff, gbase, voff) do { _Pragma("unroll") for (int _i = 0; _i < 2; ++_i) \
;         __builtin_amdgcn_global_load_lds((const unsigned*)((const char*)(gbase) + (voff)[_i]), (PG8_LAS unsigned*)(lds + (bufoff) + ldsw + _i * 8192), 16, 0, 0); } while (0)
; #define PG8_LDA(dst, b, h) do { _Pragma("unroll") for (int m = 0; m < 4; ++m) _Pragma("unroll") for (int k = 0; k < 2; ++k) dst[m][k] = *(const PG8_LAS bf16x8*)(lds + PG8_SA(b, h) + aoff + m * 2048 + k * 1024); } while (0)
; #define PG8_WAIT_V(n) asm volatile("s_waitcnt vmcnt(" #n ")" ::: "memory")
; template <class Epi, class Sched, bool ALIGN_EPI = false, bool SP2 = false>
; __device__ __forceinline__ void gemm_phase(PG8_LAS unsigned char* lds, const Gemm g, const Sched& S, const Epi& E, int tid_in) {
;     ...
;         for (int t = 0; t < nt; t += 2) {
;             if constexpr (Epi::MIDK) { if (t == Epi::MIDK_T) { if (wr == 0) PG8_BAR; E.mid(acc, cur, wr, wc, fr, fq); if (wr == 1) PG8_BAR; } }
;             const bool last = (t == nt - 2);
;             const char* a1 = cA + (size_t)(t + 1) * kstep;
;             const char* a2 = last ? nA : cA + (size_t)(t + 2) * kstep; const char* b2 = last ? nB : cB + (size_t)(t + 2) * kstep;
;             const char* a3 = a2 + kstep; const char* b3 = b2 + kstep;
;             if (last && has_next) S.a_ready(nxt);
;             if constexpr (SP2) {
;             PG8_LDB(B0, 0, 0); PG8_LDB(B1, 0, 1); PG8_SCHED; PG8_LDA(At, 0, 0); PG8_STAGE(PG8_SA(1, 1), a1 + hstep, voffA);
;             PG8_WAIT_V(8); PG8_WAIT_L(0); PG8_BAR; PG8_MMA(0, 0, At, B0); PG8_MMA(0, 1, At, B1); PG8_BAR; PG8_SCHED;
;             PG8_LDA(At, 0, 1); PG8_STAGE(PG8_SB(0, 0), b2, voffB); PG8_STAGE(PG8_SB(0, 1), b2 + hstep, voffB); PG8_STAGE(PG8_SA(0, 0), a2, voffA);
;             PG8_WAIT_V(8); PG8_WAIT_L(0); PG8_BAR; PG8_MMA(1, 0, At, B0); PG8_MMA(1, 1, At, B1); PG8_BAR; PG8_SCHED;
;             PG8_LDB(B0, 1, 0); PG8_LDB(B1, 1, 1); PG8_SCHED; PG8_LDA(At, 1, 0); PG8_STAGE(PG8_SA(0, 1), a2 + hstep, voffA);
;             PG8_WAIT_V(8); PG8_WAIT_L(0); PG8_BAR; PG8_MMA(0, 0, At, B0); PG8_MMA(0, 1, At, B1); PG8_BAR; PG8_SCHED;
;             PG8_LDA(At, 1, 1); PG8_STAGE(PG8_SB(1, 0), b3, voffB); PG8_STAGE(PG8_SB(1, 1), b3 + hstep, voffB); PG8_STAGE(PG8_SA(1, 0), a3, voffA);
;             PG8_WAIT_V(8); PG8_WAIT_L(0); PG8_BAR; PG8_MMA(1, 0, At, B0); PG8_MMA(1, 1, At, B1); PG8_BAR; PG8_SCHED;
.LBB0_1062:
	s_add_u32 s0, s44, s46
	s_addc_u32 s1, s45, s47
	s_add_u32 s0, s0, 0x100
	s_addc_u32 s1, s1, 0
	s_add_u32 s48, s78, s46
	s_addc_u32 s49, s79, s47
	s_add_i32 s81, 0, 0x10000
	v_add_u32_e32 v1, s81, v214
	ds_read_b128 v[132:135], v1
	ds_read_b128 v[136:139], v1 offset:1024
	ds_read_b128 v[140:143], v1 offset:2048
	ds_read_b128 v[144:147], v1 offset:3072
	v_add_u32_e32 v1, s74, v214
	ds_read_b128 v[148:151], v1
	ds_read_b128 v[152:155], v1 offset:1024
	ds_read_b128 v[156:159], v1 offset:2048
	ds_read_b128 v[160:163], v1 offset:3072
	s_cmpk_eq_i32 s46, 0x700
	s_cselect_b32 s51, s35, s1
	s_cselect_b32 s50, s67, s0
	s_cselect_b32 s49, s75, s49
	s_cselect_b32 s48, s76, s48
	v_lshl_add_u64 v[2:3], v[208:209], 0, s[46:47]
	s_add_i32 m0, s58, 0xc000
	ds_read_b128 v[164:167], v216
	ds_read_b128 v[168:171], v216 offset:1024
	ds_read_b128 v[172:175], v216 offset:2048
	ds_read_b128 v[176:179], v216 offset:3072
	ds_read_b128 v[180:183], v216 offset:4096
	ds_read_b128 v[184:187], v216 offset:5120
	ds_read_b128 v[218:221], v216 offset:6144
	ds_read_b128 v[222:225], v216 offset:7168
	global_load_lds_dwordx4 v[2:3], off
	v_lshl_add_u64 v[2:3], v[210:211], 0, s[46:47]
	s_add_i32 m0, s58, 0xe000
	s_nop 0
	global_load_lds_dwordx4 v[2:3], off
	s_waitcnt vmcnt(8) lgkmcnt(0)
	s_barrier
	v_mfma_f32_16x16x32_bf16 v[128:131], v[132:135], v[164:167], v[128:131]
	v_mfma_f32_16x16x32_bf16 v[124:127], v[140:143], v[164:167], v[124:127]
	v_mfma_f32_16x16x32_bf16 v[112:115], v[132:135], v[172:175], v[112:115]
	v_mfma_f32_16x16x32_bf16 v[108:111], v[140:143], v[172:175], v[108:111]
	v_mfma_f32_16x16x32_bf16 v[96:99], v[132:135], v[180:183], v[96:99]
	v_mfma_f32_16x16x32_bf16 v[92:95], v[140:143], v[180:183], v[92:95]
	v_mfma_f32_16x16x32_bf16 v[80:83], v[132:135], v[218:221], v[80:83]
	v_mfma_f32_16x16x32_bf16 v[76:79], v[140:143], v[218:221], v[76:79]
	v_mfma_f32_16x16x32_bf16 v[128:131], v[136:139], v[168:171], v[128:131]
	v_mfma_f32_16x16x32_bf16 v[124:127], v[144:147], v[168:171], v[124:127]
	v_mfma_f32_16x16x32_bf16 v[112:115], v[136:139], v[176:179], v[112:115]
	v_mfma_f32_16x16x32_bf16 v[108:111], v[144:147], v[176:179], v[108:111]
	v_mfma_f32_16x16x32_bf16 v[96:99], v[136:139], v[184:187], v[96:99]
	v_mfma_f32_16x16x32_bf16 v[92:95], v[144:147], v[184:187], v[92:95]
	v_mfma_f32_16x16x32_bf16 v[80:83], v[136:139], v[222:225], v[80:83]
	v_mfma_f32_16x16x32_bf16 v[76:79], v[144:147], v[222:225], v[76:79]
	v_mfma_f32_16x16x32_bf16 v[120:123], v[148:151], v[164:167], v[120:123]
	v_mfma_f32_16x16x32_bf16 v[116:119], v[156:159], v[164:167], v[116:119]
	v_mfma_f32_16x16x32_bf16 v[104:107], v[148:151], v[172:175], v[104:107]
	v_mfma_f32_16x16x32_bf16 v[100:103], v[156:159], v[172:175], v[100:103]
	v_mfma_f32_16x16x32_bf16 v[88:91], v[148:151], v[180:183], v[88:91]
	v_mfma_f32_16x16x32_bf16 v[84:87], v[156:159], v[180:183], v[84:87]
	v_mfma_f32_16x16x32_bf16 v[72:75], v[148:151], v[218:221], v[72:75]
	v_mfma_f32_16x16x32_bf16 v[68:71], v[156:159], v[218:221], v[68:71]
	v_mfma_f32_16x16x32_bf16 v[120:123], v[152:155], v[168:171], v[120:123]
	v_mfma_f32_16x16x32_bf16 v[116:119], v[160:163], v[168:171], v[116:119]
	v_mfma_f32_16x16x32_bf16 v[104:107], v[152:155], v[176:179], v[104:107]
	v_mfma_f32_16x16x32_bf16 v[100:103], v[160:163], v[176:179], v[100:103]
	v_mfma_f32_16x16x32_bf16 v[88:91], v[152:155], v[184:187], v[88:91]
	v_mfma_f32_16x16x32_bf16 v[84:87], v[160:163], v[184:187], v[84:87]
	v_mfma_f32_16x16x32_bf16 v[72:75], v[152:155], v[222:225], v[72:75]
	v_mfma_f32_16x16x32_bf16 v[68:71], v[160:163], v[222:225], v[68:71]
	s_barrier
	s_add_i32 s0, s81, s57
	v_lshl_add_u64 v[226:227], s[48:49], 0, v[190:191]
	s_mov_b32 m0, s0
	ds_read_b128 v[164:167], v216 offset:16384
	ds_read_b128 v[168:171], v216 offset:17408
	ds_read_b128 v[172:175], v216 offset:18432
	ds_read_b128 v[176:179], v216 offset:19456
	ds_read_b128 v[180:183], v216 offset:20480
	ds_read_b128 v[184:187], v216 offset:21504
	ds_read_b128 v[218:221], v216 offset:22528
	ds_read_b128 v[222:225], v216 offset:23552
	global_load_lds_dwordx4 v[226:227], off
	s_add_i32 m0, s0, 0x2000
	s_add_u32 s0, s48, 0x40000
	v_lshl_add_u64 v[228:229], s[48:49], 0, v[194:195]
	s_addc_u32 s1, s49, 0
	s_add_i32 s81, s74, s57
	global_load_lds_dwordx4 v[228:229], off
	v_lshl_add_u64 v[2:3], s[0:1], 0, v[190:191]
	s_mov_b32 m0, s81
	v_lshl_add_u64 v[232:233], s[50:51], 0, v[188:189]
	global_load_lds_dwordx4 v[2:3], off
	v_lshl_add_u64 v[2:3], s[0:1], 0, v[194:195]
	s_add_i32 m0, s81, 0x2000
	v_lshl_add_u64 v[234:235], s[50:51], 0, v[192:193]
	global_load_lds_dwordx4 v[2:3], off
	s_mov_b32 m0, s58
	s_nop 0
	global_load_lds_dwordx4 v[232:233], off
	s_mov_b32 m0, s59
	s_nop 0
	global_load_lds_dwordx4 v[234:235], off
	s_waitcnt vmcnt(8) lgkmcnt(0)
	s_barrier
; #define PG8_STAGE(bufoff, gbase, voff) do { _Pragma("unroll") for (int _i = 0; _i < 2; ++_i) \
;         __builtin_amdgcn_global_load_lds((const unsigned*)((const char*)(gbase) + (voff)[_i]), (PG8_LAS unsigned*)(lds + (bufoff) + ldsw + _i * 8192), 16, 0, 0); } while (0)
; #define PG8_LDA(dst, b, h) do { _Pragma("unroll") for (int m = 0; m < 4; ++m) _Pragma("unroll") for (int k = 0; k < 2; ++k) dst[m][k] = *(const PG8_LAS bf16x8*)(lds + PG8_SA(b, h) + aoff + m * 2048 + k * 1024); } while (0)
; #define PG8_LDB(dst, b, h) do { _Pragma("unroll") for (int n = 0; n < 2; ++n) _Pragma("unroll") for (int k = 0; k < 2; ++k) dst[n][k] = *(const PG8_LAS bf16x8*)(lds + PG8_SB(b, h) + boff + n * 2048 + k * 1024); } while (0)
; #define PG8_MMA(ai, bj, At, Bt) do { __builtin_amdgcn_s_setprio(1); _Pragma("unroll") for (int m = 0; m < 4; ++m) _Pragma("unroll") for (int n = 0; n < 2; ++n) _Pragma("unroll") for (int k = 0; k < 2; ++k) \
;         acc[ai][bj][m][n] = __builtin_amdgcn_mfma_f32_16x16x32_bf16(Bt[n][k], At[m][k], acc[ai][bj][m][n], 0, 0, 0); __builtin_amdgcn_s_setprio(0); } while (0)
; #define PG8_WAIT_V(n) asm volatile("s_waitcnt vmcnt(" #n ")" ::: "memory")
; #define PG8_WAIT_L(n) asm volatile("s_waitcnt lgkmcnt(" #n ")" ::: "memory")
; #define PG8_BAR __builtin_amdgcn_s_barrier()
; #define PG8_SCHED __builtin_amdgcn_sched_barrier(0)
; template <class Epi, class Sched, bool ALIGN_EPI = false, bool SP2 = false>
; __device__ __forceinline__ void gemm_phase(PG8_LAS unsigned char* lds, const Gemm g, const Sched& S, const Epi& E, int tid_in) {
;     ...
;             PG8_WAIT_V(8); PG8_WAIT_L(0); PG8_BAR; PG8_MMA(1, 0, At, B0); PG8_MMA(1, 1, At, B1); PG8_BAR; PG8_SCHED;
;             PG8_LDB(B0, 1, 0); PG8_LDB(B1, 1, 1); PG8_SCHED; PG8_LDA(At, 1, 0); PG8_STAGE(PG8_SA(0, 1), a2 + hstep, voffA);
;             PG8_WAIT_V(8); PG8_WAIT_L(0); PG8_BAR; PG8_MMA(0, 0, At, B0); PG8_MMA(0, 1, At, B1); PG8_BAR; PG8_SCHED;
	v_mfma_f32_16x16x32_bf16 v[64:67], v[132:135], v[164:167], v[64:67]
	v_mfma_f32_16x16x32_bf16 v[60:63], v[140:143], v[164:167], v[60:63]
	v_mfma_f32_16x16x32_bf16 v[48:51], v[132:135], v[172:175], v[48:51]
	v_mfma_f32_16x16x32_bf16 v[44:47], v[140:143], v[172:175], v[44:47]
	v_mfma_f32_16x16x32_bf16 v[32:35], v[132:135], v[180:183], v[32:35]
	v_mfma_f32_16x16x32_bf16 v[28:31], v[140:143], v[180:183], v[28:31]
	v_mfma_f32_16x16x32_bf16 v[16:19], v[132:135], v[218:221], v[16:19]
	v_mfma_f32_16x16x32_bf16 v[12:15], v[140:143], v[218:221], v[12:15]
	v_mfma_f32_16x16x32_bf16 v[64:67], v[136:139], v[168:171], v[64:67]
	v_mfma_f32_16x16x32_bf16 v[60:63], v[144:147], v[168:171], v[60:63]
	v_mfma_f32_16x16x32_bf16 v[48:51], v[136:139], v[176:179], v[48:51]
	v_mfma_f32_16x16x32_bf16 v[44:47], v[144:147], v[176:179], v[44:47]
	v_mfma_f32_16x16x32_bf16 v[32:35], v[136:139], v[184:187], v[32:35]
	v_mfma_f32_16x16x32_bf16 v[28:31], v[144:147], v[184:187], v[28:31]
	v_mfma_f32_16x16x32_bf16 v[16:19], v[136:139], v[222:225], v[16:19]
	v_mfma_f32_16x16x32_bf16 v[12:15], v[144:147], v[222:225], v[12:15]
	v_mfma_f32_16x16x32_bf16 v[56:59], v[148:151], v[164:167], v[56:59]
	v_mfma_f32_16x16x32_bf16 v[52:55], v[156:159], v[164:167], v[52:55]
	v_mfma_f32_16x16x32_bf16 v[40:43], v[148:151], v[172:175], v[40:43]
	v_mfma_f32_16x16x32_bf16 v[36:39], v[156:159], v[172:175], v[36:39]
	v_mfma_f32_16x16x32_bf16 v[24:27], v[148:151], v[180:183], v[24:27]
	v_mfma_f32_16x16x32_bf16 v[20:23], v[156:159], v[180:183], v[20:23]
	v_mfma_f32_16x16x32_bf16 v[8:11], v[148:151], v[218:221], v[8:11]
	v_mfma_f32_16x16x32_bf16 v[2:5], v[156:159], v[218:221], v[4:7]
	v_mfma_f32_16x16x32_bf16 v[56:59], v[152:155], v[168:171], v[56:59]
	v_mfma_f32_16x16x32_bf16 v[52:55], v[160:163], v[168:171], v[52:55]
	v_mfma_f32_16x16x32_bf16 v[40:43], v[152:155], v[176:179], v[40:43]
	v_mfma_f32_16x16x32_bf16 v[36:39], v[160:163], v[176:179], v[36:39]
	v_mfma_f32_16x16x32_bf16 v[24:27], v[152:155], v[184:187], v[24:27]
	v_mfma_f32_16x16x32_bf16 v[20:23], v[160:163], v[184:187], v[20:23]
	v_mfma_f32_16x16x32_bf16 v[8:11], v[152:155], v[222:225], v[8:11]
	v_mfma_f32_16x16x32_bf16 v[2:5], v[160:163], v[222:225], v[2:5]
	s_barrier
	s_add_i32 s81, 0, 0x18000
	v_add_u32_e32 v1, s81, v214
	s_add_i32 s82, 0, 0x1c000
	ds_read_b128 v[132:135], v1
	ds_read_b128 v[136:139], v1 offset:1024
	ds_read_b128 v[140:143], v1 offset:2048
	ds_read_b128 v[144:147], v1 offset:3072
	v_add_u32_e32 v1, s82, v214
	ds_read_b128 v[148:151], v1
	ds_read_b128 v[152:155], v1 offset:1024
	ds_read_b128 v[156:159], v1 offset:2048
	ds_read_b128 v[160:163], v1 offset:3072
	s_add_u32 s0, s50, 0x40000
	s_addc_u32 s1, s51, 0
	s_mov_b32 m0, s60
	v_lshl_add_u64 v[6:7], s[0:1], 0, v[188:189]
	ds_read_b128 v[164:167], v216 offset:32768
	ds_read_b128 v[168:171], v216 offset:33792
	ds_read_b128 v[172:175], v216 offset:34816
	ds_read_b128 v[176:179], v216 offset:35840
	ds_read_b128 v[180:183], v216 offset:36864
	ds_read_b128 v[184:187], v216 offset:37888
	ds_read_b128 v[218:221], v216 offset:38912
	ds_read_b128 v[222:225], v216 offset:39936
	global_load_lds_dwordx4 v[6:7], off
	v_lshl_add_u64 v[6:7], s[0:1], 0, v[192:193]
	s_mov_b32 m0, s61
	s_nop 0
	global_load_lds_dwordx4 v[6:7], off
	s_waitcnt vmcnt(8) lgkmcnt(0)
	s_barrier
	v_mfma_f32_16x16x32_bf16 v[128:131], v[132:135], v[164:167], v[128:131]
	v_mfma_f32_16x16x32_bf16 v[124:127], v[140:143], v[164:167], v[124:127]
	v_mfma_f32_16x16x32_bf16 v[112:115], v[132:135], v[172:175], v[112:115]
	v_mfma_f32_16x16x32_bf16 v[108:111], v[140:143], v[172:175], v[108:111]
	v_mfma_f32_16x16x32_bf16 v[96:99], v[132:135], v[180:183], v[96:99]
	v_mfma_f32_16x16x32_bf16 v[92:95], v[140:143], v[180:183], v[92:95]
	v_mfma_f32_16x16x32_bf16 v[80:83], v[132:135], v[218:221], v[80:83]
	v_mfma_f32_16x16x32_bf16 v[76:79], v[140:143], v[218:221], v[76:79]
	v_mfma_f32_16x16x32_bf16 v[128:131], v[136:139], v[168:171], v[128:131]
	v_mfma_f32_16x16x32_bf16 v[124:127], v[144:147], v[168:171], v[124:127]
	v_mfma_f32_16x16x32_bf16 v[112:115], v[136:139], v[176:179], v[112:115]
	v_mfma_f32_16x16x32_bf16 v[108:111], v[144:147], v[176:179], v[108:111]
	v_mfma_f32_16x16x32_bf16 v[96:99], v[136:139], v[184:187], v[96:99]
	v_mfma_f32_16x16x32_bf16 v[92:95], v[144:147], v[184:187], v[92:95]
	v_mfma_f32_16x16x32_bf16 v[80:83], v[136:139], v[222:225], v[80:83]
	v_mfma_f32_16x16x32_bf16 v[76:79], v[144:147], v[222:225], v[76:79]
	v_mfma_f32_16x16x32_bf16 v[120:123], v[148:151], v[164:167], v[120:123]
	v_mfma_f32_16x16x32_bf16 v[116:119], v[156:159], v[164:167], v[116:119]
	v_mfma_f32_16x16x32_bf16 v[104:107], v[148:151], v[172:175], v[104:107]
	v_mfma_f32_16x16x32_bf16 v[100:103], v[156:159], v[172:175], v[100:103]
	v_mfma_f32_16x16x32_bf16 v[88:91], v[148:151], v[180:183], v[88:91]
	v_mfma_f32_16x16x32_bf16 v[84:87], v[156:159], v[180:183], v[84:87]
	v_mfma_f32_16x16x32_bf16 v[72:75], v[148:151], v[218:221], v[72:75]
	v_mfma_f32_16x16x32_bf16 v[68:71], v[156:159], v[218:221], v[68:71]
	v_mfma_f32_16x16x32_bf16 v[120:123], v[152:155], v[168:171], v[120:123]
	v_mfma_f32_16x16x32_bf16 v[116:119], v[160:163], v[168:171], v[116:119]
	v_mfma_f32_16x16x32_bf16 v[104:107], v[152:155], v[176:179], v[104:107]
	v_mfma_f32_16x16x32_bf16 v[100:103], v[160:163], v[176:179], v[100:103]
	v_mfma_f32_16x16x32_bf16 v[88:91], v[152:155], v[184:187], v[88:91]
	v_mfma_f32_16x16x32_bf16 v[84:87], v[160:163], v[184:187], v[84:87]
	v_mfma_f32_16x16x32_bf16 v[72:75], v[152:155], v[222:225], v[72:75]
	v_mfma_f32_16x16x32_bf16 v[68:71], v[160:163], v[222:225], v[68:71]
	s_barrier
; #define PG8_STAGE(bufoff, gbase, voff) do { _Pragma("unroll") for (int _i = 0; _i < 2; ++_i) \
;         __builtin_amdgcn_global_load_lds((const unsigned*)((const char*)(gbase) + (voff)[_i]), (PG8_LAS unsigned*)(lds + (bufoff) + ldsw + _i * 8192), 16, 0, 0); } while (0)
; #define PG8_LDA(dst, b, h) do { _Pragma("unroll") for (int m = 0; m < 4; ++m) _Pragma("unroll") for (int k = 0; k < 2; ++k) dst[m][k] = *(const PG8_LAS bf16x8*)(lds + PG8_SA(b, h) + aoff + m * 2048 + k * 1024); } while (0)
; #define PG8_MMA(ai, bj, At, Bt) do { __builtin_amdgcn_s_setprio(1); _Pragma("unroll") for (int m = 0; m < 4; ++m) _Pragma("unroll") for (int n = 0; n < 2; ++n) _Pragma("unroll") for (int k = 0; k < 2; ++k) \
;         acc[ai][bj][m][n] = __builtin_amdgcn_mfma_f32_16x16x32_bf16(Bt[n][k], At[m][k], acc[ai][bj][m][n], 0, 0, 0); __builtin_amdgcn_s_setprio(0); } while (0)
; #define PG8_WAIT_V(n) asm volatile("s_waitcnt vmcnt(" #n ")" ::: "memory")
; #define PG8_WAIT_L(n) asm volatile("s_waitcnt lgkmcnt(" #n ")" ::: "memory")
; #define PG8_BAR __builtin_amdgcn_s_barrier()
; #define PG8_SCHED __builtin_amdgcn_sched_barrier(0)
; template <class Epi, class Sched, bool ALIGN_EPI = false, bool SP2 = false>
; __device__ __forceinline__ void gemm_phase(PG8_LAS unsigned char* lds, const Gemm g, const Sched& S, const Epi& E, int tid_in) {
;     ...
;             PG8_LDA(At, 1, 1); PG8_STAGE(PG8_SB(1, 0), b3, voffB); PG8_STAGE(PG8_SB(1, 1), b3 + hstep, voffB); PG8_STAGE(PG8_SA(1, 0), a3, voffA);
;             PG8_WAIT_V(8); PG8_WAIT_L(0); PG8_BAR; PG8_MMA(1, 0, At, B0); PG8_MMA(1, 1, At, B1); PG8_BAR; PG8_SCHED;
;     ...
;         }
	s_add_i32 s0, s81, s57
	v_lshl_add_u64 v[6:7], v[226:227], 0, s[12:13]
	s_mov_b32 m0, s0
	ds_read_b128 v[164:167], v216 offset:49152
	ds_read_b128 v[168:171], v216 offset:50176
	ds_read_b128 v[172:175], v216 offset:51200
	ds_read_b128 v[176:179], v216 offset:52224
	ds_read_b128 v[180:183], v216 offset:53248
	ds_read_b128 v[184:187], v216 offset:54272
	ds_read_b128 v[218:221], v216 offset:55296
	ds_read_b128 v[222:225], v216 offset:56320
	global_load_lds_dwordx4 v[6:7], off
	s_add_i32 m0, s0, 0x2000
	s_add_u32 s0, s48, 0x40080
	v_lshl_add_u64 v[6:7], v[228:229], 0, s[12:13]
	s_addc_u32 s1, s49, 0
	s_add_i32 s48, s82, s57
	global_load_lds_dwordx4 v[6:7], off
	v_lshl_add_u64 v[6:7], s[0:1], 0, v[190:191]
	s_mov_b32 m0, s48
	s_nop 0
	global_load_lds_dwordx4 v[6:7], off
	v_lshl_add_u64 v[6:7], s[0:1], 0, v[194:195]
	s_add_i32 m0, s48, 0x2000
	s_nop 0
	global_load_lds_dwordx4 v[6:7], off
	v_lshl_add_u64 v[6:7], v[232:233], 0, s[12:13]
	s_mov_b32 m0, s64
	s_nop 0
	global_load_lds_dwordx4 v[6:7], off
	v_lshl_add_u64 v[6:7], v[234:235], 0, s[12:13]
	s_mov_b32 m0, s65
	s_nop 0
	global_load_lds_dwordx4 v[6:7], off
	s_waitcnt vmcnt(8) lgkmcnt(0)
	s_barrier
	v_mfma_f32_16x16x32_bf16 v[64:67], v[132:135], v[164:167], v[64:67]
	v_mfma_f32_16x16x32_bf16 v[60:63], v[140:143], v[164:167], v[60:63]
	v_mfma_f32_16x16x32_bf16 v[48:51], v[132:135], v[172:175], v[48:51]
	v_mfma_f32_16x16x32_bf16 v[44:47], v[140:143], v[172:175], v[44:47]
	v_mfma_f32_16x16x32_bf16 v[32:35], v[132:135], v[180:183], v[32:35]
	v_mfma_f32_16x16x32_bf16 v[28:31], v[140:143], v[180:183], v[28:31]
	v_mfma_f32_16x16x32_bf16 v[16:19], v[132:135], v[218:221], v[16:19]
	v_mfma_f32_16x16x32_bf16 v[12:15], v[140:143], v[218:221], v[12:15]
	v_mfma_f32_16x16x32_bf16 v[64:67], v[136:139], v[168:171], v[64:67]
	v_mfma_f32_16x16x32_bf16 v[60:63], v[144:147], v[168:171], v[60:63]
	v_mfma_f32_16x16x32_bf16 v[48:51], v[136:139], v[176:179], v[48:51]
	v_mfma_f32_16x16x32_bf16 v[44:47], v[144:147], v[176:179], v[44:47]
	v_mfma_f32_16x16x32_bf16 v[32:35], v[136:139], v[184:187], v[32:35]
	v_mfma_f32_16x16x32_bf16 v[28:31], v[144:147], v[184:187], v[28:31]
	v_mfma_f32_16x16x32_bf16 v[16:19], v[136:139], v[222:225], v[16:19]
	v_mfma_f32_16x16x32_bf16 v[12:15], v[144:147], v[222:225], v[12:15]
	v_mfma_f32_16x16x32_bf16 v[56:59], v[148:151], v[164:167], v[56:59]
	v_mfma_f32_16x16x32_bf16 v[52:55], v[156:159], v[164:167], v[52:55]
	v_mfma_f32_16x16x32_bf16 v[40:43], v[148:151], v[172:175], v[40:43]
	v_mfma_f32_16x16x32_bf16 v[36:39], v[156:159], v[172:175], v[36:39]
	v_mfma_f32_16x16x32_bf16 v[24:27], v[148:151], v[180:183], v[24:27]
	v_mfma_f32_16x16x32_bf16 v[20:23], v[156:159], v[180:183], v[20:23]
	v_mfma_f32_16x16x32_bf16 v[6:9], v[148:151], v[218:221], v[8:11]
	v_mfma_f32_16x16x32_bf16 v[2:5], v[156:159], v[218:221], v[2:5]
	v_mfma_f32_16x16x32_bf16 v[56:59], v[152:155], v[168:171], v[56:59]
	v_mfma_f32_16x16x32_bf16 v[52:55], v[160:163], v[168:171], v[52:55]
	v_mfma_f32_16x16x32_bf16 v[40:43], v[152:155], v[176:179], v[40:43]
	v_mfma_f32_16x16x32_bf16 v[36:39], v[160:163], v[176:179], v[36:39]
	v_mfma_f32_16x16x32_bf16 v[24:27], v[152:155], v[184:187], v[24:27]
	v_mfma_f32_16x16x32_bf16 v[20:23], v[160:163], v[184:187], v[20:23]
	v_mfma_f32_16x16x32_bf16 v[8:11], v[152:155], v[222:225], v[6:9]
	v_mfma_f32_16x16x32_bf16 v[4:7], v[160:163], v[222:225], v[2:5]
	s_barrier
	s_add_i32 s80, s80, 2
	s_add_u32 s46, s46, 0x100
	s_addc_u32 s47, s47, 0
	s_cmp_gt_u32 s80, 13
	s_cbranch_scc1 .LBB0_1068

; #define PG8_STAGE(bufoff, gbase, voff) do { _Pragma("unroll") for (int _i = 0; _i < 2; ++_i) \
;         __builtin_amdgcn_global_load_lds((const unsigned*)((const char*)(gbase) + (voff)[_i]), (PG8_LAS unsigned*)(lds + (bufoff) + ldsw + _i * 8192), 16, 0, 0); } while (0)
; #define PG8_WAIT_V(n) asm volatile("s_waitcnt vmcnt(" #n ")" ::: "memory")
; template <class Epi, class Sched, bool ALIGN_EPI = false, bool SP2 = false>
; __device__ __forceinline__ void gemm_phase(PG8_LAS unsigned char* lds, const Gemm g, const Sched& S, const Epi& E, int tid_in) {
;     ...
;         const bool has_next = S.next(ui + 1, nxt);
;         const char* nA = has_next ? (const char*)g.A + (size_t)nxt.pm * tstep : cA; const char* nB = has_next ? (const char*)g.Bt + (size_t)nxt.pn * tstep : cB;
;         for (int t = 0; t < nt; t += 2) {
;             if constexpr (Epi::MIDK) { if (t == Epi::MIDK_T) { if (wr == 0) PG8_BAR; E.mid(acc, cur, wr, wc, fr, fq); if (wr == 1) PG8_BAR; } }
;             const bool last = (t == nt - 2);
;             const char* a1 = cA + (size_t)(t + 1) * kstep;
;             const char* a2 = last ? nA : cA + (size_t)(t + 2) * kstep; const char* b2 = last ? nB : cB + (size_t)(t + 2) * kstep;
;             const char* a3 = a2 + kstep; const char* b3 = b2 + kstep;
;             if (last && has_next) S.a_ready(nxt);
;             if constexpr (SP2) {
;             PG8_LDB(B0, 0, 0); PG8_LDB(B1, 0, 1); PG8_SCHED; PG8_LDA(At, 0, 0); PG8_STAGE(PG8_SA(1, 1), a1 + hstep, voffA);
;             PG8_WAIT_V(8); PG8_WAIT_L(0); PG8_BAR; PG8_MMA(0, 0, At, B0); PG8_MMA(0, 1, At, B1); PG8_BAR; PG8_SCHED;
;             PG8_LDA(At, 0, 1); PG8_STAGE(PG8_SB(0, 0), b2, voffB); PG8_STAGE(PG8_SB(0, 1), b2 + hstep, voffB); PG8_STAGE(PG8_SA(0, 0), a2, voffA);
;             PG8_WAIT_V(8); PG8_WAIT_L(0); PG8_BAR; PG8_MMA(1, 0, At, B0); PG8_MMA(1, 1, At, B1); PG8_BAR; PG8_SCHED;
;             PG8_LDB(B0, 1, 0); PG8_LDB(B1, 1, 1); PG8_SCHED; PG8_LDA(At, 1, 0); PG8_STAGE(PG8_SA(0, 1), a2 + hstep, voffA);
;             PG8_WAIT_V(8); PG8_WAIT_L(0); PG8_BAR; PG8_MMA(0, 0, At, B0); PG8_MMA(0, 1, At, B1); PG8_BAR; PG8_SCHED;
;             PG8_LDA(At, 1, 1); PG8_STAGE(PG8_SB(1, 0), b3, voffB); PG8_STAGE(PG8_SB(1, 1), b3 + hstep, voffB); PG8_STAGE(PG8_SA(1, 0), a3, voffA);
;             PG8_WAIT_V(8); PG8_WAIT_L(0); PG8_BAR; PG8_MMA(1, 0, At, B0); PG8_MMA(1, 1, At, B1); PG8_BAR; PG8_SCHED;
.LBB0_1147:
	s_ashr_i32 s23, s22, 31
	s_lshl_b64 s[24:25], s[22:23], 19
	s_add_u32 s24, s38, s24
	s_addc_u32 s25, s39, s25
	s_and_b64 s[26:27], s[4:5], exec
	s_cselect_b32 s23, s25, s31
	s_cselect_b32 s29, s24, s30
	s_ashr_i32 s21, s20, 31
	s_lshl_b64 s[26:27], s[20:21], 19
	s_add_u32 s26, s44, s26
	s_addc_u32 s27, s45, s27
	s_and_b64 s[36:37], s[4:5], exec
	s_cselect_b32 s21, s27, s35
	s_cselect_b32 s57, s26, s34
	s_add_u32 s30, s30, 0x40080
	s_addc_u32 s31, s31, 0
	s_add_u32 s58, s34, 0x100
	s_addc_u32 s59, s35, 0
	s_mov_b32 s60, -2
	s_waitcnt lgkmcnt(0)
	s_add_u32 s34, s30, 0xfffc0080
	s_addc_u32 s35, s31, -1
	s_cmp_eq_u32 s60, 12
	s_cselect_b32 s37, s23, s35
	s_cselect_b32 s36, s29, s34
	s_cselect_b32 s35, s21, s59
	s_cselect_b32 s34, s57, s58
	s_add_i32 m0, s1, 0xc000
	ds_read_b128 v[128:131], v191
	global_load_lds_dwordx4 v160, s[30:31]
	s_add_i32 m0, s1, 0xe000
	ds_read_b128 v[132:135], v191 offset:1024
	global_load_lds_dwordx4 v162, s[30:31]
	ds_read_b128 v[136:139], v191 offset:2048
	ds_read_b128 v[140:143], v191 offset:3072
	ds_read_b128 v[144:147], v192
	ds_read_b128 v[148:151], v192 offset:1024
	ds_read_b128 v[168:171], v192 offset:2048
	ds_read_b128 v[172:175], v192 offset:3072
	ds_read_b128 v[176:179], v193
	ds_read_b128 v[180:183], v193 offset:1024
	ds_read_b128 v[194:197], v193 offset:2048
	ds_read_b128 v[198:201], v193 offset:3072
	ds_read_b128 v[202:205], v193 offset:4096
	ds_read_b128 v[206:209], v193 offset:5120
	ds_read_b128 v[210:213], v193 offset:6144
	ds_read_b128 v[214:217], v193 offset:7168
	s_waitcnt vmcnt(8) lgkmcnt(0)
	s_barrier
	v_mfma_f32_16x16x32_bf16 v[124:127], v[128:131], v[176:179], 0
	v_mfma_f32_16x16x32_bf16 v[120:123], v[136:139], v[176:179], 0
	v_mfma_f32_16x16x32_bf16 v[108:111], v[128:131], v[194:197], 0
	v_mfma_f32_16x16x32_bf16 v[104:107], v[136:139], v[194:197], 0
	v_mfma_f32_16x16x32_bf16 v[92:95], v[128:131], v[202:205], 0
	v_mfma_f32_16x16x32_bf16 v[88:91], v[136:139], v[202:205], 0
	v_mfma_f32_16x16x32_bf16 v[76:79], v[128:131], v[210:213], 0
	v_mfma_f32_16x16x32_bf16 v[72:75], v[136:139], v[210:213], 0
	v_mfma_f32_16x16x32_bf16 v[124:127], v[132:135], v[180:183], v[124:127]
	v_mfma_f32_16x16x32_bf16 v[120:123], v[140:143], v[180:183], v[120:123]
	v_mfma_f32_16x16x32_bf16 v[108:111], v[132:135], v[198:201], v[108:111]
	v_mfma_f32_16x16x32_bf16 v[104:107], v[140:143], v[198:201], v[104:107]
	v_mfma_f32_16x16x32_bf16 v[92:95], v[132:135], v[206:209], v[92:95]
	v_mfma_f32_16x16x32_bf16 v[88:91], v[140:143], v[206:209], v[88:91]
	v_mfma_f32_16x16x32_bf16 v[76:79], v[132:135], v[214:217], v[76:79]
	v_mfma_f32_16x16x32_bf16 v[72:75], v[140:143], v[214:217], v[72:75]
	v_mfma_f32_16x16x32_bf16 v[116:119], v[144:147], v[176:179], 0
	v_mfma_f32_16x16x32_bf16 v[112:115], v[168:171], v[176:179], 0
	v_mfma_f32_16x16x32_bf16 v[100:103], v[144:147], v[194:197], 0
	v_mfma_f32_16x16x32_bf16 v[96:99], v[168:171], v[194:197], 0
	v_mfma_f32_16x16x32_bf16 v[84:87], v[144:147], v[202:205], 0
	v_mfma_f32_16x16x32_bf16 v[80:83], v[168:171], v[202:205], 0
	v_mfma_f32_16x16x32_bf16 v[68:71], v[144:147], v[210:213], 0
	v_mfma_f32_16x16x32_bf16 v[64:67], v[168:171], v[210:213], 0
	v_mfma_f32_16x16x32_bf16 v[116:119], v[148:151], v[180:183], v[116:119]
	v_mfma_f32_16x16x32_bf16 v[112:115], v[172:175], v[180:183], v[112:115]
	v_mfma_f32_16x16x32_bf16 v[100:103], v[148:151], v[198:201], v[100:103]
	v_mfma_f32_16x16x32_bf16 v[96:99], v[172:175], v[198:201], v[96:99]
	v_mfma_f32_16x16x32_bf16 v[84:87], v[148:151], v[206:209], v[84:87]
	v_mfma_f32_16x16x32_bf16 v[80:83], v[172:175], v[206:209], v[80:83]
	v_mfma_f32_16x16x32_bf16 v[68:71], v[148:151], v[214:217], v[68:71]
	v_mfma_f32_16x16x32_bf16 v[64:67], v[172:175], v[214:217], v[64:67]
	s_barrier
	s_add_u32 s98, s34, s16
	s_addc_u32 s99, s35, s17
	s_add_u32 s100, s36, s16
	s_addc_u32 s101, s37, s17
	s_add_i32 s61, s54, s0
	s_mov_b32 m0, s61
	ds_read_b128 v[176:179], v193 offset:16384
	global_load_lds_dwordx4 v154, s[34:35]
	s_add_i32 m0, s61, 0x2000
	s_add_u32 s62, s34, 0x40000
	s_addc_u32 s63, s35, 0
	s_add_i32 s61, s55, s0
	global_load_lds_dwordx4 v158, s[34:35]
	s_mov_b32 m0, s61
	ds_read_b128 v[180:183], v193 offset:17408
	global_load_lds_dwordx4 v154, s[62:63]
	s_add_i32 m0, s61, 0x2000
	ds_read_b128 v[194:197], v193 offset:18432
	global_load_lds_dwordx4 v158, s[62:63]
	s_mov_b32 m0, s1
	ds_read_b128 v[198:201], v193 offset:19456
	global_load_lds_dwordx4 v152, s[36:37]
	s_mov_b32 m0, s46
	ds_read_b128 v[202:205], v193 offset:20480
	global_load_lds_dwordx4 v156, s[36:37]
	ds_read_b128 v[206:209], v193 offset:21504
	ds_read_b128 v[210:213], v193 offset:22528
	ds_read_b128 v[214:217], v193 offset:23552
	s_waitcnt vmcnt(8) lgkmcnt(0)
	s_barrier
; #define PG8_STAGE(bufoff, gbase, voff) do { _Pragma("unroll") for (int _i = 0; _i < 2; ++_i) \
;         __builtin_amdgcn_global_load_lds((const unsigned*)((const char*)(gbase) + (voff)[_i]), (PG8_LAS unsigned*)(lds + (bufoff) + ldsw + _i * 8192), 16, 0, 0); } while (0)
; #define PG8_LDA(dst, b, h) do { _Pragma("unroll") for (int m = 0; m < 4; ++m) _Pragma("unroll") for (int k = 0; k < 2; ++k) dst[m][k] = *(const PG8_LAS bf16x8*)(lds + PG8_SA(b, h) + aoff + m * 2048 + k * 1024); } while (0)
; #define PG8_LDB(dst, b, h) do { _Pragma("unroll") for (int n = 0; n < 2; ++n) _Pragma("unroll") for (int k = 0; k < 2; ++k) dst[n][k] = *(const PG8_LAS bf16x8*)(lds + PG8_SB(b, h) + boff + n * 2048 + k * 1024); } while (0)
; #define PG8_MMA(ai, bj, At, Bt) do { __builtin_amdgcn_s_setprio(1); _Pragma("unroll") for (int m = 0; m < 4; ++m) _Pragma("unroll") for (int n = 0; n < 2; ++n) _Pragma("unroll") for (int k = 0; k < 2; ++k) \
;         acc[ai][bj][m][n] = __builtin_amdgcn_mfma_f32_16x16x32_bf16(Bt[n][k], At[m][k], acc[ai][bj][m][n], 0, 0, 0); __builtin_amdgcn_s_setprio(0); } while (0)
; #define PG8_WAIT_V(n) asm volatile("s_waitcnt vmcnt(" #n ")" ::: "memory")
; #define PG8_WAIT_L(n) asm volatile("s_waitcnt lgkmcnt(" #n ")" ::: "memory")
; #define PG8_BAR __builtin_amdgcn_s_barrier()
; #define PG8_SCHED __builtin_amdgcn_sched_barrier(0)
; template <class Epi, class Sched, bool ALIGN_EPI = false, bool SP2 = false>
; __device__ __forceinline__ void gemm_phase(PG8_LAS unsigned char* lds, const Gemm g, const Sched& S, const Epi& E, int tid_in) {
;     ...
;             PG8_LDA(At, 0, 1); PG8_STAGE(PG8_SB(0, 0), b2, voffB); PG8_STAGE(PG8_SB(0, 1), b2 + hstep, voffB); PG8_STAGE(PG8_SA(0, 0), a2, voffA);
;             PG8_WAIT_V(8); PG8_WAIT_L(0); PG8_BAR; PG8_MMA(1, 0, At, B0); PG8_MMA(1, 1, At, B1); PG8_BAR; PG8_SCHED;
;             PG8_LDB(B0, 1, 0); PG8_LDB(B1, 1, 1); PG8_SCHED; PG8_LDA(At, 1, 0); PG8_STAGE(PG8_SA(0, 1), a2 + hstep, voffA);
;             PG8_WAIT_V(8); PG8_WAIT_L(0); PG8_BAR; PG8_MMA(0, 0, At, B0); PG8_MMA(0, 1, At, B1); PG8_BAR; PG8_SCHED;
	v_mfma_f32_16x16x32_bf16 v[60:63], v[128:131], v[176:179], 0
	v_mfma_f32_16x16x32_bf16 v[56:59], v[136:139], v[176:179], 0
	v_mfma_f32_16x16x32_bf16 v[44:47], v[128:131], v[194:197], 0
	v_mfma_f32_16x16x32_bf16 v[40:43], v[136:139], v[194:197], 0
	v_mfma_f32_16x16x32_bf16 v[28:31], v[128:131], v[202:205], 0
	v_mfma_f32_16x16x32_bf16 v[24:27], v[136:139], v[202:205], 0
	v_mfma_f32_16x16x32_bf16 v[12:15], v[128:131], v[210:213], 0
	v_mfma_f32_16x16x32_bf16 v[8:11], v[136:139], v[210:213], 0
	v_mfma_f32_16x16x32_bf16 v[60:63], v[132:135], v[180:183], v[60:63]
	v_mfma_f32_16x16x32_bf16 v[56:59], v[140:143], v[180:183], v[56:59]
	v_mfma_f32_16x16x32_bf16 v[44:47], v[132:135], v[198:201], v[44:47]
	v_mfma_f32_16x16x32_bf16 v[40:43], v[140:143], v[198:201], v[40:43]
	v_mfma_f32_16x16x32_bf16 v[28:31], v[132:135], v[206:209], v[28:31]
	v_mfma_f32_16x16x32_bf16 v[24:27], v[140:143], v[206:209], v[24:27]
	v_mfma_f32_16x16x32_bf16 v[12:15], v[132:135], v[214:217], v[12:15]
	v_mfma_f32_16x16x32_bf16 v[8:11], v[140:143], v[214:217], v[8:11]
	v_mfma_f32_16x16x32_bf16 v[52:55], v[144:147], v[176:179], 0
	v_mfma_f32_16x16x32_bf16 v[48:51], v[168:171], v[176:179], 0
	v_mfma_f32_16x16x32_bf16 v[36:39], v[144:147], v[194:197], 0
	v_mfma_f32_16x16x32_bf16 v[32:35], v[168:171], v[194:197], 0
	v_mfma_f32_16x16x32_bf16 v[20:23], v[144:147], v[202:205], 0
	v_mfma_f32_16x16x32_bf16 v[16:19], v[168:171], v[202:205], 0
	v_mfma_f32_16x16x32_bf16 v[4:7], v[144:147], v[210:213], 0
	v_mfma_f32_16x16x32_bf16 v[0:3], v[168:171], v[210:213], 0
	v_mfma_f32_16x16x32_bf16 v[52:55], v[148:151], v[180:183], v[52:55]
	v_mfma_f32_16x16x32_bf16 v[48:51], v[172:175], v[180:183], v[48:51]
	v_mfma_f32_16x16x32_bf16 v[36:39], v[148:151], v[198:201], v[36:39]
	v_mfma_f32_16x16x32_bf16 v[32:35], v[172:175], v[198:201], v[32:35]
	v_mfma_f32_16x16x32_bf16 v[20:23], v[148:151], v[206:209], v[20:23]
	v_mfma_f32_16x16x32_bf16 v[16:19], v[172:175], v[206:209], v[16:19]
	v_mfma_f32_16x16x32_bf16 v[4:7], v[148:151], v[214:217], v[4:7]
	v_mfma_f32_16x16x32_bf16 v[0:3], v[172:175], v[214:217], v[0:3]
	s_barrier
	s_add_i32 s61, 0, 0x18000
	s_add_i32 s62, 0, 0x1c000
	s_add_u32 s36, s36, 0x40000
	s_addc_u32 s37, s37, 0
	s_mov_b32 m0, s47
	s_nop 0
	global_load_lds_dwordx4 v152, s[36:37]
	s_mov_b32 m0, s48
	s_nop 0
	global_load_lds_dwordx4 v156, s[36:37]
	v_add_u32_e32 v140, s61, v187
	v_add_u32_e32 v172, s62, v187
	ds_read_b128 v[128:131], v140
	ds_read_b128 v[132:135], v140 offset:1024
	ds_read_b128 v[136:139], v140 offset:2048
	ds_read_b128 v[140:143], v140 offset:3072
	ds_read_b128 v[144:147], v172
	ds_read_b128 v[148:151], v172 offset:1024
	ds_read_b128 v[168:171], v172 offset:2048
	ds_read_b128 v[172:175], v172 offset:3072
	ds_read_b128 v[176:179], v193 offset:32768
	ds_read_b128 v[180:183], v193 offset:33792
	ds_read_b128 v[194:197], v193 offset:34816
	ds_read_b128 v[198:201], v193 offset:35840
	ds_read_b128 v[202:205], v193 offset:36864
	ds_read_b128 v[206:209], v193 offset:37888
	ds_read_b128 v[210:213], v193 offset:38912
	ds_read_b128 v[214:217], v193 offset:39936
	s_waitcnt vmcnt(8) lgkmcnt(0)
	s_barrier
	v_mfma_f32_16x16x32_bf16 v[124:127], v[128:131], v[176:179], v[124:127]
	v_mfma_f32_16x16x32_bf16 v[120:123], v[136:139], v[176:179], v[120:123]
	v_mfma_f32_16x16x32_bf16 v[108:111], v[128:131], v[194:197], v[108:111]
	v_mfma_f32_16x16x32_bf16 v[104:107], v[136:139], v[194:197], v[104:107]
	v_mfma_f32_16x16x32_bf16 v[92:95], v[128:131], v[202:205], v[92:95]
	v_mfma_f32_16x16x32_bf16 v[88:91], v[136:139], v[202:205], v[88:91]
	v_mfma_f32_16x16x32_bf16 v[76:79], v[128:131], v[210:213], v[76:79]
	v_mfma_f32_16x16x32_bf16 v[72:75], v[136:139], v[210:213], v[72:75]
	v_mfma_f32_16x16x32_bf16 v[124:127], v[132:135], v[180:183], v[124:127]
	v_mfma_f32_16x16x32_bf16 v[120:123], v[140:143], v[180:183], v[120:123]
	v_mfma_f32_16x16x32_bf16 v[108:111], v[132:135], v[198:201], v[108:111]
	v_mfma_f32_16x16x32_bf16 v[104:107], v[140:143], v[198:201], v[104:107]
	v_mfma_f32_16x16x32_bf16 v[92:95], v[132:135], v[206:209], v[92:95]
	v_mfma_f32_16x16x32_bf16 v[88:91], v[140:143], v[206:209], v[88:91]
	v_mfma_f32_16x16x32_bf16 v[76:79], v[132:135], v[214:217], v[76:79]
	v_mfma_f32_16x16x32_bf16 v[72:75], v[140:143], v[214:217], v[72:75]
	v_mfma_f32_16x16x32_bf16 v[116:119], v[144:147], v[176:179], v[116:119]
	v_mfma_f32_16x16x32_bf16 v[112:115], v[168:171], v[176:179], v[112:115]
	v_mfma_f32_16x16x32_bf16 v[100:103], v[144:147], v[194:197], v[100:103]
	v_mfma_f32_16x16x32_bf16 v[96:99], v[168:171], v[194:197], v[96:99]
	v_mfma_f32_16x16x32_bf16 v[84:87], v[144:147], v[202:205], v[84:87]
	v_mfma_f32_16x16x32_bf16 v[80:83], v[168:171], v[202:205], v[80:83]
	v_mfma_f32_16x16x32_bf16 v[68:71], v[144:147], v[210:213], v[68:71]
	v_mfma_f32_16x16x32_bf16 v[64:67], v[168:171], v[210:213], v[64:67]
	v_mfma_f32_16x16x32_bf16 v[116:119], v[148:151], v[180:183], v[116:119]
	v_mfma_f32_16x16x32_bf16 v[112:115], v[172:175], v[180:183], v[112:115]
	v_mfma_f32_16x16x32_bf16 v[100:103], v[148:151], v[198:201], v[100:103]
	v_mfma_f32_16x16x32_bf16 v[96:99], v[172:175], v[198:201], v[96:99]
	v_mfma_f32_16x16x32_bf16 v[84:87], v[148:151], v[206:209], v[84:87]
	v_mfma_f32_16x16x32_bf16 v[80:83], v[172:175], v[206:209], v[80:83]
	v_mfma_f32_16x16x32_bf16 v[68:71], v[148:151], v[214:217], v[68:71]
	v_mfma_f32_16x16x32_bf16 v[64:67], v[172:175], v[214:217], v[64:67]
	s_barrier
; #define PG8_STAGE(bufoff, gbase, voff) do { _Pragma("unroll") for (int _i = 0; _i < 2; ++_i) \
;         __builtin_amdgcn_global_load_lds((const unsigned*)((const char*)(gbase) + (voff)[_i]), (PG8_LAS unsigned*)(lds + (bufoff) + ldsw + _i * 8192), 16, 0, 0); } while (0)
; #define PG8_LDA(dst, b, h) do { _Pragma("unroll") for (int m = 0; m < 4; ++m) _Pragma("unroll") for (int k = 0; k < 2; ++k) dst[m][k] = *(const PG8_LAS bf16x8*)(lds + PG8_SA(b, h) + aoff + m * 2048 + k * 1024); } while (0)
; #define PG8_WAIT_V(n) asm volatile("s_waitcnt vmcnt(" #n ")" ::: "memory")
; template <class Epi, class Sched, bool ALIGN_EPI = false, bool SP2 = false>
; __device__ __forceinline__ void gemm_phase(PG8_LAS unsigned char* lds, const Gemm g, const Sched& S, const Epi& E, int tid_in) {
;     ...
;         for (int t = 0; t < nt; t += 2) {
;             if constexpr (Epi::MIDK) { if (t == Epi::MIDK_T) { if (wr == 0) PG8_BAR; E.mid(acc, cur, wr, wc, fr, fq); if (wr == 1) PG8_BAR; } }
;             const bool last = (t == nt - 2);
;             const char* a1 = cA + (size_t)(t + 1) * kstep;
;             const char* a2 = last ? nA : cA + (size_t)(t + 2) * kstep; const char* b2 = last ? nB : cB + (size_t)(t + 2) * kstep;
;             const char* a3 = a2 + kstep; const char* b3 = b2 + kstep;
;             if (last && has_next) S.a_ready(nxt);
;             if constexpr (SP2) {
;             PG8_LDB(B0, 0, 0); PG8_LDB(B1, 0, 1); PG8_SCHED; PG8_LDA(At, 0, 0); PG8_STAGE(PG8_SA(1, 1), a1 + hstep, voffA);
;             PG8_WAIT_V(8); PG8_WAIT_L(0); PG8_BAR; PG8_MMA(0, 0, At, B0); PG8_MMA(0, 1, At, B1); PG8_BAR; PG8_SCHED;
;             PG8_LDA(At, 0, 1); PG8_STAGE(PG8_SB(0, 0), b2, voffB); PG8_STAGE(PG8_SB(0, 1), b2 + hstep, voffB); PG8_STAGE(PG8_SA(0, 0), a2, voffA);
;             PG8_WAIT_V(8); PG8_WAIT_L(0); PG8_BAR; PG8_MMA(1, 0, At, B0); PG8_MMA(1, 1, At, B1); PG8_BAR; PG8_SCHED;
;             PG8_LDB(B0, 1, 0); PG8_LDB(B1, 1, 1); PG8_SCHED; PG8_LDA(At, 1, 0); PG8_STAGE(PG8_SA(0, 1), a2 + hstep, voffA);
;             PG8_WAIT_V(8); PG8_WAIT_L(0); PG8_BAR; PG8_MMA(0, 0, At, B0); PG8_MMA(0, 1, At, B1); PG8_BAR; PG8_SCHED;
;             PG8_LDA(At, 1, 1); PG8_STAGE(PG8_SB(1, 0), b3, voffB); PG8_STAGE(PG8_SB(1, 1), b3 + hstep, voffB); PG8_STAGE(PG8_SA(1, 0), a3, voffA);
;             PG8_WAIT_V(8); PG8_WAIT_L(0); PG8_BAR; PG8_MMA(1, 0, At, B0); PG8_MMA(1, 1, At, B1); PG8_BAR; PG8_SCHED;
	s_add_i32 s36, s61, s0
	s_mov_b32 m0, s36
	ds_read_b128 v[176:179], v193 offset:49152
	global_load_lds_dwordx4 v154, s[98:99]
	s_add_i32 m0, s36, 0x2000
	s_add_u32 s34, s34, 0x40080
	s_addc_u32 s35, s35, 0
	s_add_i32 s36, s62, s0
	global_load_lds_dwordx4 v158, s[98:99]
	s_mov_b32 m0, s36
	ds_read_b128 v[180:183], v193 offset:50176
	global_load_lds_dwordx4 v154, s[34:35]
	s_add_i32 m0, s36, 0x2000
	ds_read_b128 v[194:197], v193 offset:51200
	global_load_lds_dwordx4 v158, s[34:35]
	s_mov_b32 m0, s50
	ds_read_b128 v[198:201], v193 offset:52224
	global_load_lds_dwordx4 v152, s[100:101]
	s_mov_b32 m0, s51
	ds_read_b128 v[202:205], v193 offset:53248
	global_load_lds_dwordx4 v156, s[100:101]
	ds_read_b128 v[206:209], v193 offset:54272
	ds_read_b128 v[210:213], v193 offset:55296
	ds_read_b128 v[214:217], v193 offset:56320
	s_waitcnt vmcnt(8) lgkmcnt(0)
	s_barrier
	v_mfma_f32_16x16x32_bf16 v[60:63], v[128:131], v[176:179], v[60:63]
	v_mfma_f32_16x16x32_bf16 v[56:59], v[136:139], v[176:179], v[56:59]
	v_mfma_f32_16x16x32_bf16 v[44:47], v[128:131], v[194:197], v[44:47]
	v_mfma_f32_16x16x32_bf16 v[40:43], v[136:139], v[194:197], v[40:43]
	v_mfma_f32_16x16x32_bf16 v[28:31], v[128:131], v[202:205], v[28:31]
	v_mfma_f32_16x16x32_bf16 v[24:27], v[136:139], v[202:205], v[24:27]
	v_mfma_f32_16x16x32_bf16 v[12:15], v[128:131], v[210:213], v[12:15]
	v_mfma_f32_16x16x32_bf16 v[8:11], v[136:139], v[210:213], v[8:11]
	v_mfma_f32_16x16x32_bf16 v[60:63], v[132:135], v[180:183], v[60:63]
	v_mfma_f32_16x16x32_bf16 v[56:59], v[140:143], v[180:183], v[56:59]
	v_mfma_f32_16x16x32_bf16 v[44:47], v[132:135], v[198:201], v[44:47]
	v_mfma_f32_16x16x32_bf16 v[40:43], v[140:143], v[198:201], v[40:43]
	v_mfma_f32_16x16x32_bf16 v[28:31], v[132:135], v[206:209], v[28:31]
	v_mfma_f32_16x16x32_bf16 v[24:27], v[140:143], v[206:209], v[24:27]
	v_mfma_f32_16x16x32_bf16 v[12:15], v[132:135], v[214:217], v[12:15]
	v_mfma_f32_16x16x32_bf16 v[8:11], v[140:143], v[214:217], v[8:11]
	v_mfma_f32_16x16x32_bf16 v[52:55], v[144:147], v[176:179], v[52:55]
	v_mfma_f32_16x16x32_bf16 v[48:51], v[168:171], v[176:179], v[48:51]
	v_mfma_f32_16x16x32_bf16 v[36:39], v[144:147], v[194:197], v[36:39]
	v_mfma_f32_16x16x32_bf16 v[32:35], v[168:171], v[194:197], v[32:35]
	v_mfma_f32_16x16x32_bf16 v[20:23], v[144:147], v[202:205], v[20:23]
	v_mfma_f32_16x16x32_bf16 v[16:19], v[168:171], v[202:205], v[16:19]
	v_mfma_f32_16x16x32_bf16 v[4:7], v[144:147], v[210:213], v[4:7]
	v_mfma_f32_16x16x32_bf16 v[0:3], v[168:171], v[210:213], v[0:3]
	v_mfma_f32_16x16x32_bf16 v[52:55], v[148:151], v[180:183], v[52:55]
	v_mfma_f32_16x16x32_bf16 v[48:51], v[172:175], v[180:183], v[48:51]
	v_mfma_f32_16x16x32_bf16 v[36:39], v[148:151], v[198:201], v[36:39]
	v_mfma_f32_16x16x32_bf16 v[32:35], v[172:175], v[198:201], v[32:35]
	v_mfma_f32_16x16x32_bf16 v[20:23], v[148:151], v[206:209], v[20:23]
	v_mfma_f32_16x16x32_bf16 v[16:19], v[172:175], v[206:209], v[16:19]
	v_mfma_f32_16x16x32_bf16 v[4:7], v[148:151], v[214:217], v[4:7]
	v_mfma_f32_16x16x32_bf16 v[0:3], v[172:175], v[214:217], v[0:3]
	s_barrier
	s_add_i32 s60, s60, 2
	s_add_u32 s30, s30, 0x100
	s_addc_u32 s31, s31, 0
	s_add_u32 s58, s58, 0x100
	s_addc_u32 s59, s59, 0
.LBB0_1148:
	s_add_u32 s34, s30, 0xfffc0080
	s_addc_u32 s35, s31, -1
	s_cmp_eq_u32 s60, 12
	s_cselect_b32 s37, s23, s35
	s_cselect_b32 s36, s29, s34
	s_cselect_b32 s35, s21, s59
	s_cselect_b32 s34, s57, s58
	s_add_i32 m0, s1, 0xc000
	ds_read_b128 v[128:131], v191
	global_load_lds_dwordx4 v160, s[30:31]
	s_add_i32 m0, s1, 0xe000
	ds_read_b128 v[132:135], v191 offset:1024
	global_load_lds_dwordx4 v162, s[30:31]
	ds_read_b128 v[136:139], v191 offset:2048
	ds_read_b128 v[140:143], v191 offset:3072
	ds_read_b128 v[144:147], v192
	ds_read_b128 v[148:151], v192 offset:1024
	ds_read_b128 v[168:171], v192 offset:2048
	ds_read_b128 v[172:175], v192 offset:3072
	ds_read_b128 v[176:179], v193
	ds_read_b128 v[180:183], v193 offset:1024
	ds_read_b128 v[194:197], v193 offset:2048
	ds_read_b128 v[198:201], v193 offset:3072
	ds_read_b128 v[202:205], v193 offset:4096
	ds_read_b128 v[206:209], v193 offset:5120
	ds_read_b128 v[210:213], v193 offset:6144
	ds_read_b128 v[214:217], v193 offset:7168
	s_waitcnt vmcnt(8) lgkmcnt(0)
	s_barrier
	v_mfma_f32_16x16x32_bf16 v[124:127], v[128:131], v[176:179], v[124:127]
	v_mfma_f32_16x16x32_bf16 v[120:123], v[136:139], v[176:179], v[120:123]
	v_mfma_f32_16x16x32_bf16 v[108:111], v[128:131], v[194:197], v[108:111]
	v_mfma_f32_16x16x32_bf16 v[104:107], v[136:139], v[194:197], v[104:107]
	v_mfma_f32_16x16x32_bf16 v[92:95], v[128:131], v[202:205], v[92:95]
	v_mfma_f32_16x16x32_bf16 v[88:91], v[136:139], v[202:205], v[88:91]
	v_mfma_f32_16x16x32_bf16 v[76:79], v[128:131], v[210:213], v[76:79]
	v_mfma_f32_16x16x32_bf16 v[72:75], v[136:139], v[210:213], v[72:75]
	v_mfma_f32_16x16x32_bf16 v[124:127], v[132:135], v[180:183], v[124:127]
	v_mfma_f32_16x16x32_bf16 v[120:123], v[140:143], v[180:183], v[120:123]
	v_mfma_f32_16x16x32_bf16 v[108:111], v[132:135], v[198:201], v[108:111]
	v_mfma_f32_16x16x32_bf16 v[104:107], v[140:143], v[198:201], v[104:107]
	v_mfma_f32_16x16x32_bf16 v[92:95], v[132:135], v[206:209], v[92:95]
	v_mfma_f32_16x16x32_bf16 v[88:91], v[140:143], v[206:209], v[88:91]
	v_mfma_f32_16x16x32_bf16 v[76:79], v[132:135], v[214:217], v[76:79]
	v_mfma_f32_16x16x32_bf16 v[72:75], v[140:143], v[214:217], v[72:75]
	v_mfma_f32_16x16x32_bf16 v[116:119], v[144:147], v[176:179], v[116:119]
	v_mfma_f32_16x16x32_bf16 v[112:115], v[168:171], v[176:179], v[112:115]
	v_mfma_f32_16x16x32_bf16 v[100:103], v[144:147], v[194:197], v[100:103]
	v_mfma_f32_16x16x32_bf16 v[96:99], v[168:171], v[194:197], v[96:99]
	v_mfma_f32_16x16x32_bf16 v[84:87], v[144:147], v[202:205], v[84:87]
	v_mfma_f32_16x16x32_bf16 v[80:83], v[168:171], v[202:205], v[80:83]
	v_mfma_f32_16x16x32_bf16 v[68:71], v[144:147], v[210:213], v[68:71]
	v_mfma_f32_16x16x32_bf16 v[64:67], v[168:171], v[210:213], v[64:67]
	v_mfma_f32_16x16x32_bf16 v[116:119], v[148:151], v[180:183], v[116:119]
	v_mfma_f32_16x16x32_bf16 v[112:115], v[172:175], v[180:183], v[112:115]
	v_mfma_f32_16x16x32_bf16 v[100:103], v[148:151], v[198:201], v[100:103]
	v_mfma_f32_16x16x32_bf16 v[96:99], v[172:175], v[198:201], v[96:99]
	v_mfma_f32_16x16x32_bf16 v[84:87], v[148:151], v[206:209], v[84:87]
	v_mfma_f32_16x16x32_bf16 v[80:83], v[172:175], v[206:209], v[80:83]
	v_mfma_f32_16x16x32_bf16 v[68:71], v[148:151], v[214:217], v[68:71]
	v_mfma_f32_16x16x32_bf16 v[64:67], v[172:175], v[214:217], v[64:67]
	s_barrier
; #define PG8_STAGE(bufoff, gbase, voff) do { _Pragma("unroll") for (int _i = 0; _i < 2; ++_i) \
;         __builtin_amdgcn_global_load_lds((const unsigned*)((const char*)(gbase) + (voff)[_i]), (PG8_LAS unsigned*)(lds + (bufoff) + ldsw + _i * 8192), 16, 0, 0); } while (0)
; #define PG8_LDA(dst, b, h) do { _Pragma("unroll") for (int m = 0; m < 4; ++m) _Pragma("unroll") for (int k = 0; k < 2; ++k) dst[m][k] = *(const PG8_LAS bf16x8*)(lds + PG8_SA(b, h) + aoff + m * 2048 + k * 1024); } while (0)
; #define PG8_LDB(dst, b, h) do { _Pragma("unroll") for (int n = 0; n < 2; ++n) _Pragma("unroll") for (int k = 0; k < 2; ++k) dst[n][k] = *(const PG8_LAS bf16x8*)(lds + PG8_SB(b, h) + boff + n * 2048 + k * 1024); } while (0)
; #define PG8_MMA(ai, bj, At, Bt) do { __builtin_amdgcn_s_setprio(1); _Pragma("unroll") for (int m = 0; m < 4; ++m) _Pragma("unroll") for (int n = 0; n < 2; ++n) _Pragma("unroll") for (int k = 0; k < 2; ++k) \
;         acc[ai][bj][m][n] = __builtin_amdgcn_mfma_f32_16x16x32_bf16(Bt[n][k], At[m][k], acc[ai][bj][m][n], 0, 0, 0); __builtin_amdgcn_s_setprio(0); } while (0)
; #define PG8_WAIT_V(n) asm volatile("s_waitcnt vmcnt(" #n ")" ::: "memory")
; #define PG8_WAIT_L(n) asm volatile("s_waitcnt lgkmcnt(" #n ")" ::: "memory")
; #define PG8_BAR __builtin_amdgcn_s_barrier()
; #define PG8_SCHED __builtin_amdgcn_sched_barrier(0)
; template <class Epi, class Sched, bool ALIGN_EPI = false, bool SP2 = false>
; __device__ __forceinline__ void gemm_phase(PG8_LAS unsigned char* lds, const Gemm g, const Sched& S, const Epi& E, int tid_in) {
;     ...
;             PG8_LDA(At, 0, 1); PG8_STAGE(PG8_SB(0, 0), b2, voffB); PG8_STAGE(PG8_SB(0, 1), b2 + hstep, voffB); PG8_STAGE(PG8_SA(0, 0), a2, voffA);
;             PG8_WAIT_V(8); PG8_WAIT_L(0); PG8_BAR; PG8_MMA(1, 0, At, B0); PG8_MMA(1, 1, At, B1); PG8_BAR; PG8_SCHED;
;             PG8_LDB(B0, 1, 0); PG8_LDB(B1, 1, 1); PG8_SCHED; PG8_LDA(At, 1, 0); PG8_STAGE(PG8_SA(0, 1), a2 + hstep, voffA);
;             PG8_WAIT_V(8); PG8_WAIT_L(0); PG8_BAR; PG8_MMA(0, 0, At, B0); PG8_MMA(0, 1, At, B1); PG8_BAR; PG8_SCHED;
	s_add_u32 s98, s34, s16
	s_addc_u32 s99, s35, s17
	s_add_u32 s100, s36, s16
	s_addc_u32 s101, s37, s17
	s_add_i32 s61, s54, s0
	s_mov_b32 m0, s61
	ds_read_b128 v[176:179], v193 offset:16384
	global_load_lds_dwordx4 v154, s[34:35]
	s_add_i32 m0, s61, 0x2000
	s_add_u32 s62, s34, 0x40000
	s_addc_u32 s63, s35, 0
	s_add_i32 s61, s55, s0
	global_load_lds_dwordx4 v158, s[34:35]
	s_mov_b32 m0, s61
	ds_read_b128 v[180:183], v193 offset:17408
	global_load_lds_dwordx4 v154, s[62:63]
	s_add_i32 m0, s61, 0x2000
	ds_read_b128 v[194:197], v193 offset:18432
	global_load_lds_dwordx4 v158, s[62:63]
	s_mov_b32 m0, s1
	ds_read_b128 v[198:201], v193 offset:19456
	global_load_lds_dwordx4 v152, s[36:37]
	s_mov_b32 m0, s46
	ds_read_b128 v[202:205], v193 offset:20480
	global_load_lds_dwordx4 v156, s[36:37]
	ds_read_b128 v[206:209], v193 offset:21504
	ds_read_b128 v[210:213], v193 offset:22528
	ds_read_b128 v[214:217], v193 offset:23552
	s_waitcnt vmcnt(8) lgkmcnt(0)
	s_barrier
	v_mfma_f32_16x16x32_bf16 v[60:63], v[128:131], v[176:179], v[60:63]
	v_mfma_f32_16x16x32_bf16 v[56:59], v[136:139], v[176:179], v[56:59]
	v_mfma_f32_16x16x32_bf16 v[44:47], v[128:131], v[194:197], v[44:47]
	v_mfma_f32_16x16x32_bf16 v[40:43], v[136:139], v[194:197], v[40:43]
	v_mfma_f32_16x16x32_bf16 v[28:31], v[128:131], v[202:205], v[28:31]
	v_mfma_f32_16x16x32_bf16 v[24:27], v[136:139], v[202:205], v[24:27]
	v_mfma_f32_16x16x32_bf16 v[12:15], v[128:131], v[210:213], v[12:15]
	v_mfma_f32_16x16x32_bf16 v[8:11], v[136:139], v[210:213], v[8:11]
	v_mfma_f32_16x16x32_bf16 v[60:63], v[132:135], v[180:183], v[60:63]
	v_mfma_f32_16x16x32_bf16 v[56:59], v[140:143], v[180:183], v[56:59]
	v_mfma_f32_16x16x32_bf16 v[44:47], v[132:135], v[198:201], v[44:47]
	v_mfma_f32_16x16x32_bf16 v[40:43], v[140:143], v[198:201], v[40:43]
	v_mfma_f32_16x16x32_bf16 v[28:31], v[132:135], v[206:209], v[28:31]
	v_mfma_f32_16x16x32_bf16 v[24:27], v[140:143], v[206:209], v[24:27]
	v_mfma_f32_16x16x32_bf16 v[12:15], v[132:135], v[214:217], v[12:15]
	v_mfma_f32_16x16x32_bf16 v[8:11], v[140:143], v[214:217], v[8:11]
	v_mfma_f32_16x16x32_bf16 v[52:55], v[144:147], v[176:179], v[52:55]
	v_mfma_f32_16x16x32_bf16 v[48:51], v[168:171], v[176:179], v[48:51]
	v_mfma_f32_16x16x32_bf16 v[36:39], v[144:147], v[194:197], v[36:39]
	v_mfma_f32_16x16x32_bf16 v[32:35], v[168:171], v[194:197], v[32:35]
	v_mfma_f32_16x16x32_bf16 v[20:23], v[144:147], v[202:205], v[20:23]
	v_mfma_f32_16x16x32_bf16 v[16:19], v[168:171], v[202:205], v[16:19]
	v_mfma_f32_16x16x32_bf16 v[4:7], v[144:147], v[210:213], v[4:7]
	v_mfma_f32_16x16x32_bf16 v[0:3], v[168:171], v[210:213], v[0:3]
	v_mfma_f32_16x16x32_bf16 v[52:55], v[148:151], v[180:183], v[52:55]
	v_mfma_f32_16x16x32_bf16 v[48:51], v[172:175], v[180:183], v[48:51]
	v_mfma_f32_16x16x32_bf16 v[36:39], v[148:151], v[198:201], v[36:39]
	v_mfma_f32_16x16x32_bf16 v[32:35], v[172:175], v[198:201], v[32:35]
	v_mfma_f32_16x16x32_bf16 v[20:23], v[148:151], v[206:209], v[20:23]
	v_mfma_f32_16x16x32_bf16 v[16:19], v[172:175], v[206:209], v[16:19]
	v_mfma_f32_16x16x32_bf16 v[4:7], v[148:151], v[214:217], v[4:7]
	v_mfma_f32_16x16x32_bf16 v[0:3], v[172:175], v[214:217], v[0:3]
	s_barrier
	s_add_i32 s61, 0, 0x18000
	s_add_i32 s62, 0, 0x1c000
	s_add_u32 s36, s36, 0x40000
	s_addc_u32 s37, s37, 0
	s_mov_b32 m0, s47
	s_nop 0
	global_load_lds_dwordx4 v152, s[36:37]
	s_mov_b32 m0, s48
	s_nop 0
	global_load_lds_dwordx4 v156, s[36:37]
	v_add_u32_e32 v140, s61, v187
	v_add_u32_e32 v172, s62, v187
	ds_read_b128 v[128:131], v140
	ds_read_b128 v[132:135], v140 offset:1024
	ds_read_b128 v[136:139], v140 offset:2048
	ds_read_b128 v[140:143], v140 offset:3072
	ds_read_b128 v[144:147], v172
	ds_read_b128 v[148:151], v172 offset:1024
	ds_read_b128 v[168:171], v172 offset:2048
	ds_read_b128 v[172:175], v172 offset:3072
	ds_read_b128 v[176:179], v193 offset:32768
	ds_read_b128 v[180:183], v193 offset:33792
	ds_read_b128 v[194:197], v193 offset:34816
	ds_read_b128 v[198:201], v193 offset:35840
	ds_read_b128 v[202:205], v193 offset:36864
	ds_read_b128 v[206:209], v193 offset:37888
	ds_read_b128 v[210:213], v193 offset:38912
	ds_read_b128 v[214:217], v193 offset:39936
	s_waitcnt vmcnt(8) lgkmcnt(0)
	s_barrier
; #define PG8_STAGE(bufoff, gbase, voff) do { _Pragma("unroll") for (int _i = 0; _i < 2; ++_i) \
;         __builtin_amdgcn_global_load_lds((const unsigned*)((const char*)(gbase) + (voff)[_i]), (PG8_LAS unsigned*)(lds + (bufoff) + ldsw + _i * 8192), 16, 0, 0); } while (0)
; #define PG8_LDA(dst, b, h) do { _Pragma("unroll") for (int m = 0; m < 4; ++m) _Pragma("unroll") for (int k = 0; k < 2; ++k) dst[m][k] = *(const PG8_LAS bf16x8*)(lds + PG8_SA(b, h) + aoff + m * 2048 + k * 1024); } while (0)
; #define PG8_MMA(ai, bj, At, Bt) do { __builtin_amdgcn_s_setprio(1); _Pragma("unroll") for (int m = 0; m < 4; ++m) _Pragma("unroll") for (int n = 0; n < 2; ++n) _Pragma("unroll") for (int k = 0; k < 2; ++k) \
;         acc[ai][bj][m][n] = __builtin_amdgcn_mfma_f32_16x16x32_bf16(Bt[n][k], At[m][k], acc[ai][bj][m][n], 0, 0, 0); __builtin_amdgcn_s_setprio(0); } while (0)
; #define PG8_WAIT_V(n) asm volatile("s_waitcnt vmcnt(" #n ")" ::: "memory")
; #define PG8_WAIT_L(n) asm volatile("s_waitcnt lgkmcnt(" #n ")" ::: "memory")
; #define PG8_BAR __builtin_amdgcn_s_barrier()
; #define PG8_SCHED __builtin_amdgcn_sched_barrier(0)
; template <class Epi, class Sched, bool ALIGN_EPI = false, bool SP2 = false>
; __device__ __forceinline__ void gemm_phase(PG8_LAS unsigned char* lds, const Gemm g, const Sched& S, const Epi& E, int tid_in) {
;     ...
;             PG8_WAIT_V(8); PG8_WAIT_L(0); PG8_BAR; PG8_MMA(0, 0, At, B0); PG8_MMA(0, 1, At, B1); PG8_BAR; PG8_SCHED;
;             PG8_LDA(At, 1, 1); PG8_STAGE(PG8_SB(1, 0), b3, voffB); PG8_STAGE(PG8_SB(1, 1), b3 + hstep, voffB); PG8_STAGE(PG8_SA(1, 0), a3, voffA);
;             PG8_WAIT_V(8); PG8_WAIT_L(0); PG8_BAR; PG8_MMA(1, 0, At, B0); PG8_MMA(1, 1, At, B1); PG8_BAR; PG8_SCHED;
;     ...
;         }
;         if constexpr (ALIGN_EPI) { if (wr == 0) PG8_BAR; }
	v_mfma_f32_16x16x32_bf16 v[124:127], v[128:131], v[176:179], v[124:127]
	v_mfma_f32_16x16x32_bf16 v[120:123], v[136:139], v[176:179], v[120:123]
	v_mfma_f32_16x16x32_bf16 v[108:111], v[128:131], v[194:197], v[108:111]
	v_mfma_f32_16x16x32_bf16 v[104:107], v[136:139], v[194:197], v[104:107]
	v_mfma_f32_16x16x32_bf16 v[92:95], v[128:131], v[202:205], v[92:95]
	v_mfma_f32_16x16x32_bf16 v[88:91], v[136:139], v[202:205], v[88:91]
	v_mfma_f32_16x16x32_bf16 v[76:79], v[128:131], v[210:213], v[76:79]
	v_mfma_f32_16x16x32_bf16 v[72:75], v[136:139], v[210:213], v[72:75]
	v_mfma_f32_16x16x32_bf16 v[124:127], v[132:135], v[180:183], v[124:127]
	v_mfma_f32_16x16x32_bf16 v[120:123], v[140:143], v[180:183], v[120:123]
	v_mfma_f32_16x16x32_bf16 v[108:111], v[132:135], v[198:201], v[108:111]
	v_mfma_f32_16x16x32_bf16 v[104:107], v[140:143], v[198:201], v[104:107]
	v_mfma_f32_16x16x32_bf16 v[92:95], v[132:135], v[206:209], v[92:95]
	v_mfma_f32_16x16x32_bf16 v[88:91], v[140:143], v[206:209], v[88:91]
	v_mfma_f32_16x16x32_bf16 v[76:79], v[132:135], v[214:217], v[76:79]
	v_mfma_f32_16x16x32_bf16 v[72:75], v[140:143], v[214:217], v[72:75]
	v_mfma_f32_16x16x32_bf16 v[116:119], v[144:147], v[176:179], v[116:119]
	v_mfma_f32_16x16x32_bf16 v[112:115], v[168:171], v[176:179], v[112:115]
	v_mfma_f32_16x16x32_bf16 v[100:103], v[144:147], v[194:197], v[100:103]
	v_mfma_f32_16x16x32_bf16 v[96:99], v[168:171], v[194:197], v[96:99]
	v_mfma_f32_16x16x32_bf16 v[84:87], v[144:147], v[202:205], v[84:87]
	v_mfma_f32_16x16x32_bf16 v[80:83], v[168:171], v[202:205], v[80:83]
	v_mfma_f32_16x16x32_bf16 v[68:71], v[144:147], v[210:213], v[68:71]
	v_mfma_f32_16x16x32_bf16 v[64:67], v[168:171], v[210:213], v[64:67]
	v_mfma_f32_16x16x32_bf16 v[116:119], v[148:151], v[180:183], v[116:119]
	v_mfma_f32_16x16x32_bf16 v[112:115], v[172:175], v[180:183], v[112:115]
	v_mfma_f32_16x16x32_bf16 v[100:103], v[148:151], v[198:201], v[100:103]
	v_mfma_f32_16x16x32_bf16 v[96:99], v[172:175], v[198:201], v[96:99]
	v_mfma_f32_16x16x32_bf16 v[84:87], v[148:151], v[206:209], v[84:87]
	v_mfma_f32_16x16x32_bf16 v[80:83], v[172:175], v[206:209], v[80:83]
	v_mfma_f32_16x16x32_bf16 v[68:71], v[148:151], v[214:217], v[68:71]
	v_mfma_f32_16x16x32_bf16 v[64:67], v[172:175], v[214:217], v[64:67]
	s_barrier
	s_add_i32 s36, s61, s0
	s_mov_b32 m0, s36
	ds_read_b128 v[176:179], v193 offset:49152
	global_load_lds_dwordx4 v154, s[98:99]
	s_add_i32 m0, s36, 0x2000
	s_add_u32 s34, s34, 0x40080
	s_addc_u32 s35, s35, 0
	s_add_i32 s36, s62, s0
	global_load_lds_dwordx4 v158, s[98:99]
	s_mov_b32 m0, s36
	ds_read_b128 v[180:183], v193 offset:50176
	global_load_lds_dwordx4 v154, s[34:35]
	s_add_i32 m0, s36, 0x2000
	ds_read_b128 v[194:197], v193 offset:51200
	global_load_lds_dwordx4 v158, s[34:35]
	s_mov_b32 m0, s50
	ds_read_b128 v[198:201], v193 offset:52224
	global_load_lds_dwordx4 v152, s[100:101]
	s_mov_b32 m0, s51
	ds_read_b128 v[202:205], v193 offset:53248
	global_load_lds_dwordx4 v156, s[100:101]
	ds_read_b128 v[206:209], v193 offset:54272
	ds_read_b128 v[210:213], v193 offset:55296
	ds_read_b128 v[214:217], v193 offset:56320
	s_waitcnt vmcnt(8) lgkmcnt(0)
	s_barrier
	v_mfma_f32_16x16x32_bf16 v[60:63], v[128:131], v[176:179], v[60:63]
	v_mfma_f32_16x16x32_bf16 v[56:59], v[136:139], v[176:179], v[56:59]
	v_mfma_f32_16x16x32_bf16 v[44:47], v[128:131], v[194:197], v[44:47]
	v_mfma_f32_16x16x32_bf16 v[40:43], v[136:139], v[194:197], v[40:43]
	v_mfma_f32_16x16x32_bf16 v[28:31], v[128:131], v[202:205], v[28:31]
	v_mfma_f32_16x16x32_bf16 v[24:27], v[136:139], v[202:205], v[24:27]
	v_mfma_f32_16x16x32_bf16 v[12:15], v[128:131], v[210:213], v[12:15]
	v_mfma_f32_16x16x32_bf16 v[8:11], v[136:139], v[210:213], v[8:11]
	v_mfma_f32_16x16x32_bf16 v[60:63], v[132:135], v[180:183], v[60:63]
	v_mfma_f32_16x16x32_bf16 v[56:59], v[140:143], v[180:183], v[56:59]
	v_mfma_f32_16x16x32_bf16 v[44:47], v[132:135], v[198:201], v[44:47]
	v_mfma_f32_16x16x32_bf16 v[40:43], v[140:143], v[198:201], v[40:43]
	v_mfma_f32_16x16x32_bf16 v[28:31], v[132:135], v[206:209], v[28:31]
	v_mfma_f32_16x16x32_bf16 v[24:27], v[140:143], v[206:209], v[24:27]
	v_mfma_f32_16x16x32_bf16 v[12:15], v[132:135], v[214:217], v[12:15]
	v_mfma_f32_16x16x32_bf16 v[8:11], v[140:143], v[214:217], v[8:11]
	v_mfma_f32_16x16x32_bf16 v[52:55], v[144:147], v[176:179], v[52:55]
	v_mfma_f32_16x16x32_bf16 v[48:51], v[168:171], v[176:179], v[48:51]
	v_mfma_f32_16x16x32_bf16 v[36:39], v[144:147], v[194:197], v[36:39]
	v_mfma_f32_16x16x32_bf16 v[32:35], v[168:171], v[194:197], v[32:35]
	v_mfma_f32_16x16x32_bf16 v[20:23], v[144:147], v[202:205], v[20:23]
	v_mfma_f32_16x16x32_bf16 v[16:19], v[168:171], v[202:205], v[16:19]
	v_mfma_f32_16x16x32_bf16 v[4:7], v[144:147], v[210:213], v[4:7]
	v_mfma_f32_16x16x32_bf16 v[0:3], v[168:171], v[210:213], v[0:3]
	v_mfma_f32_16x16x32_bf16 v[52:55], v[148:151], v[180:183], v[52:55]
	v_mfma_f32_16x16x32_bf16 v[48:51], v[172:175], v[180:183], v[48:51]
	v_mfma_f32_16x16x32_bf16 v[36:39], v[148:151], v[198:201], v[36:39]
	v_mfma_f32_16x16x32_bf16 v[32:35], v[172:175], v[198:201], v[32:35]
	v_mfma_f32_16x16x32_bf16 v[20:23], v[148:151], v[206:209], v[20:23]
	v_mfma_f32_16x16x32_bf16 v[16:19], v[172:175], v[206:209], v[16:19]
	v_mfma_f32_16x16x32_bf16 v[4:7], v[148:151], v[214:217], v[4:7]
	v_mfma_f32_16x16x32_bf16 v[0:3], v[172:175], v[214:217], v[0:3]
	s_barrier
	s_add_i32 s60, s60, 2
	s_add_u32 s30, s30, 0x100
	s_addc_u32 s31, s31, 0
	s_add_u32 s58, s58, 0x100
	s_addc_u32 s59, s59, 0
	s_cmp_gt_u32 s60, 13
	s_cbranch_scc0 .LBB0_1148
	s_and_b64 vcc, exec, s[18:19]
	s_cbranch_vccz .LBB0_1151
	s_barrier

; #define PG8_STAGE(bufoff, gbase, voff) do { _Pragma("unroll") for (int _i = 0; _i < 2; ++_i) \
;         __builtin_amdgcn_global_load_lds((const unsigned*)((const char*)(gbase) + (voff)[_i]), (PG8_LAS unsigned*)(lds + (bufoff) + ldsw + _i * 8192), 16, 0, 0); } while (0)
; #define PG8_WAIT_V(n) asm volatile("s_waitcnt vmcnt(" #n ")" ::: "memory")
; template <class Epi, class Sched, bool ALIGN_EPI = false, bool SP2 = false>
; __device__ __forceinline__ void gemm_phase(PG8_LAS unsigned char* lds, const Gemm g, const Sched& S, const Epi& E, int tid_in) {
;     ...
;         const bool has_next = S.next(ui + 1, nxt);
;         const char* nA = has_next ? (const char*)g.A + (size_t)nxt.pm * tstep : cA; const char* nB = has_next ? (const char*)g.Bt + (size_t)nxt.pn * tstep : cB;
;         for (int t = 0; t < nt; t += 2) {
;             if constexpr (Epi::MIDK) { if (t == Epi::MIDK_T) { if (wr == 0) PG8_BAR; E.mid(acc, cur, wr, wc, fr, fq); if (wr == 1) PG8_BAR; } }
;             const bool last = (t == nt - 2);
;             const char* a1 = cA + (size_t)(t + 1) * kstep;
;             const char* a2 = last ? nA : cA + (size_t)(t + 2) * kstep; const char* b2 = last ? nB : cB + (size_t)(t + 2) * kstep;
;             const char* a3 = a2 + kstep; const char* b3 = b2 + kstep;
;             if (last && has_next) S.a_ready(nxt);
;             if constexpr (SP2) {
;             PG8_LDB(B0, 0, 0); PG8_LDB(B1, 0, 1); PG8_SCHED; PG8_LDA(At, 0, 0); PG8_STAGE(PG8_SA(1, 1), a1 + hstep, voffA);
;             PG8_WAIT_V(8); PG8_WAIT_L(0); PG8_BAR; PG8_MMA(0, 0, At, B0); PG8_MMA(0, 1, At, B1); PG8_BAR; PG8_SCHED;
;             PG8_LDA(At, 0, 1); PG8_STAGE(PG8_SB(0, 0), b2, voffB); PG8_STAGE(PG8_SB(0, 1), b2 + hstep, voffB); PG8_STAGE(PG8_SA(0, 0), a2, voffA);
;             PG8_WAIT_V(8); PG8_WAIT_L(0); PG8_BAR; PG8_MMA(1, 0, At, B0); PG8_MMA(1, 1, At, B1); PG8_BAR; PG8_SCHED;
;             PG8_LDB(B0, 1, 0); PG8_LDB(B1, 1, 1); PG8_SCHED; PG8_LDA(At, 1, 0); PG8_STAGE(PG8_SA(0, 1), a2 + hstep, voffA);
;             PG8_WAIT_V(8); PG8_WAIT_L(0); PG8_BAR; PG8_MMA(0, 0, At, B0); PG8_MMA(0, 1, At, B1); PG8_BAR; PG8_SCHED;
;             PG8_LDA(At, 1, 1); PG8_STAGE(PG8_SB(1, 0), b3, voffB); PG8_STAGE(PG8_SB(1, 1), b3 + hstep, voffB); PG8_STAGE(PG8_SA(1, 0), a3, voffA);
;             PG8_WAIT_V(8); PG8_WAIT_L(0); PG8_BAR; PG8_MMA(1, 0, At, B0); PG8_MMA(1, 1, At, B1); PG8_BAR; PG8_SCHED;
.LBB0_1237:
	s_ashr_i32 s17, s16, 31
	s_lshl_b64 s[18:19], s[16:17], 19
	s_add_u32 s18, s1, s18
	s_addc_u32 s19, s30, s19
	s_and_b64 s[20:21], s[2:3], exec
	s_cselect_b32 s17, s19, s25
	s_cselect_b32 s54, s18, s24
	s_ashr_i32 s15, s14, 31
	s_lshl_b64 s[20:21], s[14:15], 19
	s_add_u32 s20, s31, s20
	s_addc_u32 s21, s34, s21
	s_and_b64 s[28:29], s[2:3], exec
	s_cselect_b32 s15, s21, s27
	s_cselect_b32 s55, s20, s26
	s_add_u32 s24, s24, 0x40080
	s_addc_u32 s25, s25, 0
	s_add_u32 s56, s26, 0x100
	s_addc_u32 s57, s27, 0
	s_mov_b32 s58, -2
	s_add_u32 s26, s24, 0xfffc0080
	s_addc_u32 s27, s25, -1
	s_cmp_eq_u32 s58, 12
	s_cselect_b32 s29, s17, s27
	s_cselect_b32 s28, s54, s26
	s_cselect_b32 s27, s15, s57
	s_cselect_b32 s26, s55, s56
	s_add_i32 m0, s23, 0xc000
	ds_read_b128 v[144:147], v154
	global_load_lds_dwordx4 v136, s[24:25]
	s_add_i32 m0, s23, 0xe000
	ds_read_b128 v[158:161], v154 offset:1024
	global_load_lds_dwordx4 v138, s[24:25]
	ds_read_b128 v[162:165], v154 offset:2048
	ds_read_b128 v[166:169], v154 offset:3072
	ds_read_b128 v[170:173], v155
	ds_read_b128 v[174:177], v155 offset:1024
	ds_read_b128 v[178:181], v155 offset:2048
	ds_read_b128 v[182:185], v155 offset:3072
	ds_read_b128 v[186:189], v156
	ds_read_b128 v[190:193], v156 offset:1024
	ds_read_b128 v[194:197], v156 offset:2048
	ds_read_b128 v[198:201], v156 offset:3072
	ds_read_b128 v[202:205], v156 offset:4096
	ds_read_b128 v[206:209], v156 offset:5120
	ds_read_b128 v[210:213], v156 offset:6144
	ds_read_b128 v[214:217], v156 offset:7168
	s_waitcnt vmcnt(8) lgkmcnt(0)
	s_barrier
	v_mfma_f32_16x16x32_bf16 v[124:127], v[144:147], v[186:189], 0
	v_mfma_f32_16x16x32_bf16 v[120:123], v[162:165], v[186:189], 0
	v_mfma_f32_16x16x32_bf16 v[108:111], v[144:147], v[194:197], 0
	v_mfma_f32_16x16x32_bf16 v[104:107], v[162:165], v[194:197], 0
	v_mfma_f32_16x16x32_bf16 v[92:95], v[144:147], v[202:205], 0
	v_mfma_f32_16x16x32_bf16 v[88:91], v[162:165], v[202:205], 0
	v_mfma_f32_16x16x32_bf16 v[76:79], v[144:147], v[210:213], 0
	v_mfma_f32_16x16x32_bf16 v[72:75], v[162:165], v[210:213], 0
	v_mfma_f32_16x16x32_bf16 v[124:127], v[158:161], v[190:193], v[124:127]
	v_mfma_f32_16x16x32_bf16 v[120:123], v[166:169], v[190:193], v[120:123]
	v_mfma_f32_16x16x32_bf16 v[108:111], v[158:161], v[198:201], v[108:111]
	v_mfma_f32_16x16x32_bf16 v[104:107], v[166:169], v[198:201], v[104:107]
	v_mfma_f32_16x16x32_bf16 v[92:95], v[158:161], v[206:209], v[92:95]
	v_mfma_f32_16x16x32_bf16 v[88:91], v[166:169], v[206:209], v[88:91]
	v_mfma_f32_16x16x32_bf16 v[76:79], v[158:161], v[214:217], v[76:79]
	v_mfma_f32_16x16x32_bf16 v[72:75], v[166:169], v[214:217], v[72:75]
	v_mfma_f32_16x16x32_bf16 v[116:119], v[170:173], v[186:189], 0
	v_mfma_f32_16x16x32_bf16 v[112:115], v[178:181], v[186:189], 0
	v_mfma_f32_16x16x32_bf16 v[100:103], v[170:173], v[194:197], 0
	v_mfma_f32_16x16x32_bf16 v[96:99], v[178:181], v[194:197], 0
	v_mfma_f32_16x16x32_bf16 v[84:87], v[170:173], v[202:205], 0
	v_mfma_f32_16x16x32_bf16 v[80:83], v[178:181], v[202:205], 0
	v_mfma_f32_16x16x32_bf16 v[68:71], v[170:173], v[210:213], 0
	v_mfma_f32_16x16x32_bf16 v[64:67], v[178:181], v[210:213], 0
	v_mfma_f32_16x16x32_bf16 v[116:119], v[174:177], v[190:193], v[116:119]
	v_mfma_f32_16x16x32_bf16 v[112:115], v[182:185], v[190:193], v[112:115]
	v_mfma_f32_16x16x32_bf16 v[100:103], v[174:177], v[198:201], v[100:103]
	v_mfma_f32_16x16x32_bf16 v[96:99], v[182:185], v[198:201], v[96:99]
	v_mfma_f32_16x16x32_bf16 v[84:87], v[174:177], v[206:209], v[84:87]
	v_mfma_f32_16x16x32_bf16 v[80:83], v[182:185], v[206:209], v[80:83]
	v_mfma_f32_16x16x32_bf16 v[68:71], v[174:177], v[214:217], v[68:71]
	v_mfma_f32_16x16x32_bf16 v[64:67], v[182:185], v[214:217], v[64:67]
	s_barrier
	s_add_u32 s98, s26, s10
	s_addc_u32 s99, s27, s11
	s_add_u32 s100, s28, s10
	s_addc_u32 s101, s29, s11
	s_add_i32 s59, s47, s0
	s_mov_b32 m0, s59
	ds_read_b128 v[186:189], v156 offset:16384
	global_load_lds_dwordx4 v132, s[26:27]
	s_add_i32 m0, s59, 0x2000
	s_add_u32 s60, s26, 0x40000
	s_addc_u32 s61, s27, 0
	s_add_i32 s59, s48, s0
	global_load_lds_dwordx4 v128, s[26:27]
	s_mov_b32 m0, s59
	ds_read_b128 v[190:193], v156 offset:17408
	global_load_lds_dwordx4 v132, s[60:61]
	s_add_i32 m0, s59, 0x2000
	ds_read_b128 v[194:197], v156 offset:18432
	global_load_lds_dwordx4 v128, s[60:61]
	s_mov_b32 m0, s23
	ds_read_b128 v[198:201], v156 offset:19456
	global_load_lds_dwordx4 v134, s[28:29]
	s_mov_b32 m0, s37
	ds_read_b128 v[202:205], v156 offset:20480
	global_load_lds_dwordx4 v130, s[28:29]
	ds_read_b128 v[206:209], v156 offset:21504
	ds_read_b128 v[210:213], v156 offset:22528
	ds_read_b128 v[214:217], v156 offset:23552
	s_waitcnt vmcnt(8) lgkmcnt(0)
	s_barrier
; #define PG8_STAGE(bufoff, gbase, voff) do { _Pragma("unroll") for (int _i = 0; _i < 2; ++_i) \
;         __builtin_amdgcn_global_load_lds((const unsigned*)((const char*)(gbase) + (voff)[_i]), (PG8_LAS unsigned*)(lds + (bufoff) + ldsw + _i * 8192), 16, 0, 0); } while (0)
; #define PG8_LDA(dst, b, h) do { _Pragma("unroll") for (int m = 0; m < 4; ++m) _Pragma("unroll") for (int k = 0; k < 2; ++k) dst[m][k] = *(const PG8_LAS bf16x8*)(lds + PG8_SA(b, h) + aoff + m * 2048 + k * 1024); } while (0)
; #define PG8_LDB(dst, b, h) do { _Pragma("unroll") for (int n = 0; n < 2; ++n) _Pragma("unroll") for (int k = 0; k < 2; ++k) dst[n][k] = *(const PG8_LAS bf16x8*)(lds + PG8_SB(b, h) + boff + n * 2048 + k * 1024); } while (0)
; #define PG8_MMA(ai, bj, At, Bt) do { __builtin_amdgcn_s_setprio(1); _Pragma("unroll") for (int m = 0; m < 4; ++m) _Pragma("unroll") for (int n = 0; n < 2; ++n) _Pragma("unroll") for (int k = 0; k < 2; ++k) \
;         acc[ai][bj][m][n] = __builtin_amdgcn_mfma_f32_16x16x32_bf16(Bt[n][k], At[m][k], acc[ai][bj][m][n], 0, 0, 0); __builtin_amdgcn_s_setprio(0); } while (0)
; #define PG8_WAIT_V(n) asm volatile("s_waitcnt vmcnt(" #n ")" ::: "memory")
; #define PG8_WAIT_L(n) asm volatile("s_waitcnt lgkmcnt(" #n ")" ::: "memory")
; #define PG8_BAR __builtin_amdgcn_s_barrier()
; #define PG8_SCHED __builtin_amdgcn_sched_barrier(0)
; template <class Epi, class Sched, bool ALIGN_EPI = false, bool SP2 = false>
; __device__ __forceinline__ void gemm_phase(PG8_LAS unsigned char* lds, const Gemm g, const Sched& S, const Epi& E, int tid_in) {
;     ...
;             PG8_LDA(At, 0, 1); PG8_STAGE(PG8_SB(0, 0), b2, voffB); PG8_STAGE(PG8_SB(0, 1), b2 + hstep, voffB); PG8_STAGE(PG8_SA(0, 0), a2, voffA);
;             PG8_WAIT_V(8); PG8_WAIT_L(0); PG8_BAR; PG8_MMA(1, 0, At, B0); PG8_MMA(1, 1, At, B1); PG8_BAR; PG8_SCHED;
;             PG8_LDB(B0, 1, 0); PG8_LDB(B1, 1, 1); PG8_SCHED; PG8_LDA(At, 1, 0); PG8_STAGE(PG8_SA(0, 1), a2 + hstep, voffA);
;             PG8_WAIT_V(8); PG8_WAIT_L(0); PG8_BAR; PG8_MMA(0, 0, At, B0); PG8_MMA(0, 1, At, B1); PG8_BAR; PG8_SCHED;
	v_mfma_f32_16x16x32_bf16 v[60:63], v[144:147], v[186:189], 0
	v_mfma_f32_16x16x32_bf16 v[56:59], v[162:165], v[186:189], 0
	v_mfma_f32_16x16x32_bf16 v[44:47], v[144:147], v[194:197], 0
	v_mfma_f32_16x16x32_bf16 v[40:43], v[162:165], v[194:197], 0
	v_mfma_f32_16x16x32_bf16 v[28:31], v[144:147], v[202:205], 0
	v_mfma_f32_16x16x32_bf16 v[24:27], v[162:165], v[202:205], 0
	v_mfma_f32_16x16x32_bf16 v[12:15], v[144:147], v[210:213], 0
	v_mfma_f32_16x16x32_bf16 v[8:11], v[162:165], v[210:213], 0
	v_mfma_f32_16x16x32_bf16 v[60:63], v[158:161], v[190:193], v[60:63]
	v_mfma_f32_16x16x32_bf16 v[56:59], v[166:169], v[190:193], v[56:59]
	v_mfma_f32_16x16x32_bf16 v[44:47], v[158:161], v[198:201], v[44:47]
	v_mfma_f32_16x16x32_bf16 v[40:43], v[166:169], v[198:201], v[40:43]
	v_mfma_f32_16x16x32_bf16 v[28:31], v[158:161], v[206:209], v[28:31]
	v_mfma_f32_16x16x32_bf16 v[24:27], v[166:169], v[206:209], v[24:27]
	v_mfma_f32_16x16x32_bf16 v[12:15], v[158:161], v[214:217], v[12:15]
	v_mfma_f32_16x16x32_bf16 v[8:11], v[166:169], v[214:217], v[8:11]
	v_mfma_f32_16x16x32_bf16 v[52:55], v[170:173], v[186:189], 0
	v_mfma_f32_16x16x32_bf16 v[48:51], v[178:181], v[186:189], 0
	v_mfma_f32_16x16x32_bf16 v[36:39], v[170:173], v[194:197], 0
	v_mfma_f32_16x16x32_bf16 v[32:35], v[178:181], v[194:197], 0
	v_mfma_f32_16x16x32_bf16 v[20:23], v[170:173], v[202:205], 0
	v_mfma_f32_16x16x32_bf16 v[16:19], v[178:181], v[202:205], 0
	v_mfma_f32_16x16x32_bf16 v[4:7], v[170:173], v[210:213], 0
	v_mfma_f32_16x16x32_bf16 v[0:3], v[178:181], v[210:213], 0
	v_mfma_f32_16x16x32_bf16 v[52:55], v[174:177], v[190:193], v[52:55]
	v_mfma_f32_16x16x32_bf16 v[48:51], v[182:185], v[190:193], v[48:51]
	v_mfma_f32_16x16x32_bf16 v[36:39], v[174:177], v[198:201], v[36:39]
	v_mfma_f32_16x16x32_bf16 v[32:35], v[182:185], v[198:201], v[32:35]
	v_mfma_f32_16x16x32_bf16 v[20:23], v[174:177], v[206:209], v[20:23]
	v_mfma_f32_16x16x32_bf16 v[16:19], v[182:185], v[206:209], v[16:19]
	v_mfma_f32_16x16x32_bf16 v[4:7], v[174:177], v[214:217], v[4:7]
	v_mfma_f32_16x16x32_bf16 v[0:3], v[182:185], v[214:217], v[0:3]
	s_barrier
	s_add_i32 s59, 0, 0x18000
	s_add_i32 s60, 0, 0x1c000
	s_add_u32 s28, s28, 0x40000
	s_addc_u32 s29, s29, 0
	s_mov_b32 m0, s38
	v_add_u32_e32 v157, s59, v151
	global_load_lds_dwordx4 v134, s[28:29]
	s_mov_b32 m0, s39
	ds_read_b128 v[144:147], v157
	global_load_lds_dwordx4 v130, s[28:29]
	ds_read_b128 v[158:161], v157 offset:1024
	ds_read_b128 v[162:165], v157 offset:2048
	ds_read_b128 v[166:169], v157 offset:3072
	v_add_u32_e32 v157, s60, v151
	ds_read_b128 v[170:173], v157
	ds_read_b128 v[174:177], v157 offset:1024
	ds_read_b128 v[178:181], v157 offset:2048
	ds_read_b128 v[182:185], v157 offset:3072
	ds_read_b128 v[186:189], v156 offset:32768
	ds_read_b128 v[190:193], v156 offset:33792
	ds_read_b128 v[194:197], v156 offset:34816
	ds_read_b128 v[198:201], v156 offset:35840
	ds_read_b128 v[202:205], v156 offset:36864
	ds_read_b128 v[206:209], v156 offset:37888
	ds_read_b128 v[210:213], v156 offset:38912
	ds_read_b128 v[214:217], v156 offset:39936
	s_waitcnt vmcnt(8) lgkmcnt(0)
	s_barrier
	v_mfma_f32_16x16x32_bf16 v[124:127], v[144:147], v[186:189], v[124:127]
	v_mfma_f32_16x16x32_bf16 v[120:123], v[162:165], v[186:189], v[120:123]
	v_mfma_f32_16x16x32_bf16 v[108:111], v[144:147], v[194:197], v[108:111]
	v_mfma_f32_16x16x32_bf16 v[104:107], v[162:165], v[194:197], v[104:107]
	v_mfma_f32_16x16x32_bf16 v[92:95], v[144:147], v[202:205], v[92:95]
	v_mfma_f32_16x16x32_bf16 v[88:91], v[162:165], v[202:205], v[88:91]
	v_mfma_f32_16x16x32_bf16 v[76:79], v[144:147], v[210:213], v[76:79]
	v_mfma_f32_16x16x32_bf16 v[72:75], v[162:165], v[210:213], v[72:75]
	v_mfma_f32_16x16x32_bf16 v[124:127], v[158:161], v[190:193], v[124:127]
	v_mfma_f32_16x16x32_bf16 v[120:123], v[166:169], v[190:193], v[120:123]
	v_mfma_f32_16x16x32_bf16 v[108:111], v[158:161], v[198:201], v[108:111]
	v_mfma_f32_16x16x32_bf16 v[104:107], v[166:169], v[198:201], v[104:107]
	v_mfma_f32_16x16x32_bf16 v[92:95], v[158:161], v[206:209], v[92:95]
	v_mfma_f32_16x16x32_bf16 v[88:91], v[166:169], v[206:209], v[88:91]
	v_mfma_f32_16x16x32_bf16 v[76:79], v[158:161], v[214:217], v[76:79]
	v_mfma_f32_16x16x32_bf16 v[72:75], v[166:169], v[214:217], v[72:75]
	v_mfma_f32_16x16x32_bf16 v[116:119], v[170:173], v[186:189], v[116:119]
	v_mfma_f32_16x16x32_bf16 v[112:115], v[178:181], v[186:189], v[112:115]
	v_mfma_f32_16x16x32_bf16 v[100:103], v[170:173], v[194:197], v[100:103]
	v_mfma_f32_16x16x32_bf16 v[96:99], v[178:181], v[194:197], v[96:99]
	v_mfma_f32_16x16x32_bf16 v[84:87], v[170:173], v[202:205], v[84:87]
	v_mfma_f32_16x16x32_bf16 v[80:83], v[178:181], v[202:205], v[80:83]
	v_mfma_f32_16x16x32_bf16 v[68:71], v[170:173], v[210:213], v[68:71]
	v_mfma_f32_16x16x32_bf16 v[64:67], v[178:181], v[210:213], v[64:67]
	v_mfma_f32_16x16x32_bf16 v[116:119], v[174:177], v[190:193], v[116:119]
	v_mfma_f32_16x16x32_bf16 v[112:115], v[182:185], v[190:193], v[112:115]
	v_mfma_f32_16x16x32_bf16 v[100:103], v[174:177], v[198:201], v[100:103]
	v_mfma_f32_16x16x32_bf16 v[96:99], v[182:185], v[198:201], v[96:99]
	v_mfma_f32_16x16x32_bf16 v[84:87], v[174:177], v[206:209], v[84:87]
	v_mfma_f32_16x16x32_bf16 v[80:83], v[182:185], v[206:209], v[80:83]
	v_mfma_f32_16x16x32_bf16 v[68:71], v[174:177], v[214:217], v[68:71]
	v_mfma_f32_16x16x32_bf16 v[64:67], v[182:185], v[214:217], v[64:67]
	s_barrier
; #define PG8_STAGE(bufoff, gbase, voff) do { _Pragma("unroll") for (int _i = 0; _i < 2; ++_i) \
;         __builtin_amdgcn_global_load_lds((const unsigned*)((const char*)(gbase) + (voff)[_i]), (PG8_LAS unsigned*)(lds + (bufoff) + ldsw + _i * 8192), 16, 0, 0); } while (0)
; #define PG8_LDA(dst, b, h) do { _Pragma("unroll") for (int m = 0; m < 4; ++m) _Pragma("unroll") for (int k = 0; k < 2; ++k) dst[m][k] = *(const PG8_LAS bf16x8*)(lds + PG8_SA(b, h) + aoff + m * 2048 + k * 1024); } while (0)
; #define PG8_WAIT_V(n) asm volatile("s_waitcnt vmcnt(" #n ")" ::: "memory")
; template <class Epi, class Sched, bool ALIGN_EPI = false, bool SP2 = false>
; __device__ __forceinline__ void gemm_phase(PG8_LAS unsigned char* lds, const Gemm g, const Sched& S, const Epi& E, int tid_in) {
;     ...
;         for (int t = 0; t < nt; t += 2) {
;             if constexpr (Epi::MIDK) { if (t == Epi::MIDK_T) { if (wr == 0) PG8_BAR; E.mid(acc, cur, wr, wc, fr, fq); if (wr == 1) PG8_BAR; } }
;             const bool last = (t == nt - 2);
;             const char* a1 = cA + (size_t)(t + 1) * kstep;
;             const char* a2 = last ? nA : cA + (size_t)(t + 2) * kstep; const char* b2 = last ? nB : cB + (size_t)(t + 2) * kstep;
;             const char* a3 = a2 + kstep; const char* b3 = b2 + kstep;
;             if (last && has_next) S.a_ready(nxt);
;             if constexpr (SP2) {
;             PG8_LDB(B0, 0, 0); PG8_LDB(B1, 0, 1); PG8_SCHED; PG8_LDA(At, 0, 0); PG8_STAGE(PG8_SA(1, 1), a1 + hstep, voffA);
;             PG8_WAIT_V(8); PG8_WAIT_L(0); PG8_BAR; PG8_MMA(0, 0, At, B0); PG8_MMA(0, 1, At, B1); PG8_BAR; PG8_SCHED;
;             PG8_LDA(At, 0, 1); PG8_STAGE(PG8_SB(0, 0), b2, voffB); PG8_STAGE(PG8_SB(0, 1), b2 + hstep, voffB); PG8_STAGE(PG8_SA(0, 0), a2, voffA);
;             PG8_WAIT_V(8); PG8_WAIT_L(0); PG8_BAR; PG8_MMA(1, 0, At, B0); PG8_MMA(1, 1, At, B1); PG8_BAR; PG8_SCHED;
;             PG8_LDB(B0, 1, 0); PG8_LDB(B1, 1, 1); PG8_SCHED; PG8_LDA(At, 1, 0); PG8_STAGE(PG8_SA(0, 1), a2 + hstep, voffA);
;             PG8_WAIT_V(8); PG8_WAIT_L(0); PG8_BAR; PG8_MMA(0, 0, At, B0); PG8_MMA(0, 1, At, B1); PG8_BAR; PG8_SCHED;
;             PG8_LDA(At, 1, 1); PG8_STAGE(PG8_SB(1, 0), b3, voffB); PG8_STAGE(PG8_SB(1, 1), b3 + hstep, voffB); PG8_STAGE(PG8_SA(1, 0), a3, voffA);
;             PG8_WAIT_V(8); PG8_WAIT_L(0); PG8_BAR; PG8_MMA(1, 0, At, B0); PG8_MMA(1, 1, At, B1); PG8_BAR; PG8_SCHED;
	s_add_i32 s28, s59, s0
	s_mov_b32 m0, s28
	ds_read_b128 v[186:189], v156 offset:49152
	global_load_lds_dwordx4 v132, s[98:99]
	s_add_i32 m0, s28, 0x2000
	s_add_u32 s26, s26, 0x40080
	s_addc_u32 s27, s27, 0
	s_add_i32 s28, s60, s0
	global_load_lds_dwordx4 v128, s[98:99]
	s_mov_b32 m0, s28
	ds_read_b128 v[190:193], v156 offset:50176
	global_load_lds_dwordx4 v132, s[26:27]
	s_add_i32 m0, s28, 0x2000
	ds_read_b128 v[194:197], v156 offset:51200
	global_load_lds_dwordx4 v128, s[26:27]
	s_mov_b32 m0, s44
	ds_read_b128 v[198:201], v156 offset:52224
	global_load_lds_dwordx4 v134, s[100:101]
	s_mov_b32 m0, s45
	ds_read_b128 v[202:205], v156 offset:53248
	global_load_lds_dwordx4 v130, s[100:101]
	ds_read_b128 v[206:209], v156 offset:54272
	ds_read_b128 v[210:213], v156 offset:55296
	ds_read_b128 v[214:217], v156 offset:56320
	s_waitcnt vmcnt(8) lgkmcnt(0)
	s_barrier
	v_mfma_f32_16x16x32_bf16 v[60:63], v[144:147], v[186:189], v[60:63]
	v_mfma_f32_16x16x32_bf16 v[56:59], v[162:165], v[186:189], v[56:59]
	v_mfma_f32_16x16x32_bf16 v[44:47], v[144:147], v[194:197], v[44:47]
	v_mfma_f32_16x16x32_bf16 v[40:43], v[162:165], v[194:197], v[40:43]
	v_mfma_f32_16x16x32_bf16 v[28:31], v[144:147], v[202:205], v[28:31]
	v_mfma_f32_16x16x32_bf16 v[24:27], v[162:165], v[202:205], v[24:27]
	v_mfma_f32_16x16x32_bf16 v[12:15], v[144:147], v[210:213], v[12:15]
	v_mfma_f32_16x16x32_bf16 v[8:11], v[162:165], v[210:213], v[8:11]
	v_mfma_f32_16x16x32_bf16 v[60:63], v[158:161], v[190:193], v[60:63]
	v_mfma_f32_16x16x32_bf16 v[56:59], v[166:169], v[190:193], v[56:59]
	v_mfma_f32_16x16x32_bf16 v[44:47], v[158:161], v[198:201], v[44:47]
	v_mfma_f32_16x16x32_bf16 v[40:43], v[166:169], v[198:201], v[40:43]
	v_mfma_f32_16x16x32_bf16 v[28:31], v[158:161], v[206:209], v[28:31]
	v_mfma_f32_16x16x32_bf16 v[24:27], v[166:169], v[206:209], v[24:27]
	v_mfma_f32_16x16x32_bf16 v[12:15], v[158:161], v[214:217], v[12:15]
	v_mfma_f32_16x16x32_bf16 v[8:11], v[166:169], v[214:217], v[8:11]
	v_mfma_f32_16x16x32_bf16 v[52:55], v[170:173], v[186:189], v[52:55]
	v_mfma_f32_16x16x32_bf16 v[48:51], v[178:181], v[186:189], v[48:51]
	v_mfma_f32_16x16x32_bf16 v[36:39], v[170:173], v[194:197], v[36:39]
	v_mfma_f32_16x16x32_bf16 v[32:35], v[178:181], v[194:197], v[32:35]
	v_mfma_f32_16x16x32_bf16 v[20:23], v[170:173], v[202:205], v[20:23]
	v_mfma_f32_16x16x32_bf16 v[16:19], v[178:181], v[202:205], v[16:19]
	v_mfma_f32_16x16x32_bf16 v[4:7], v[170:173], v[210:213], v[4:7]
	v_mfma_f32_16x16x32_bf16 v[0:3], v[178:181], v[210:213], v[0:3]
	v_mfma_f32_16x16x32_bf16 v[52:55], v[174:177], v[190:193], v[52:55]
	v_mfma_f32_16x16x32_bf16 v[48:51], v[182:185], v[190:193], v[48:51]
	v_mfma_f32_16x16x32_bf16 v[36:39], v[174:177], v[198:201], v[36:39]
	v_mfma_f32_16x16x32_bf16 v[32:35], v[182:185], v[198:201], v[32:35]
	v_mfma_f32_16x16x32_bf16 v[20:23], v[174:177], v[206:209], v[20:23]
	v_mfma_f32_16x16x32_bf16 v[16:19], v[182:185], v[206:209], v[16:19]
	v_mfma_f32_16x16x32_bf16 v[4:7], v[174:177], v[214:217], v[4:7]
	v_mfma_f32_16x16x32_bf16 v[0:3], v[182:185], v[214:217], v[0:3]
	s_barrier
	s_add_i32 s58, s58, 2
	s_add_u32 s24, s24, 0x100
	s_addc_u32 s25, s25, 0
	s_add_u32 s56, s56, 0x100
	s_addc_u32 s57, s57, 0
.LBB0_1238:
	s_add_u32 s26, s24, 0xfffc0080
	s_addc_u32 s27, s25, -1
	s_cmp_eq_u32 s58, 12
	s_cselect_b32 s29, s17, s27
	s_cselect_b32 s28, s54, s26
	s_cselect_b32 s27, s15, s57
	s_cselect_b32 s26, s55, s56
	s_add_i32 m0, s23, 0xc000
	ds_read_b128 v[144:147], v154
	global_load_lds_dwordx4 v136, s[24:25]
	s_add_i32 m0, s23, 0xe000
	ds_read_b128 v[158:161], v154 offset:1024
	global_load_lds_dwordx4 v138, s[24:25]
	ds_read_b128 v[162:165], v154 offset:2048
	ds_read_b128 v[166:169], v154 offset:3072
	ds_read_b128 v[170:173], v155
	ds_read_b128 v[174:177], v155 offset:1024
	ds_read_b128 v[178:181], v155 offset:2048
	ds_read_b128 v[182:185], v155 offset:3072
	ds_read_b128 v[186:189], v156
	ds_read_b128 v[190:193], v156 offset:1024
	ds_read_b128 v[194:197], v156 offset:2048
	ds_read_b128 v[198:201], v156 offset:3072
	ds_read_b128 v[202:205], v156 offset:4096
	ds_read_b128 v[206:209], v156 offset:5120
	ds_read_b128 v[210:213], v156 offset:6144
	ds_read_b128 v[214:217], v156 offset:7168
	s_waitcnt vmcnt(8) lgkmcnt(0)
	s_barrier
	v_mfma_f32_16x16x32_bf16 v[124:127], v[144:147], v[186:189], v[124:127]
	v_mfma_f32_16x16x32_bf16 v[120:123], v[162:165], v[186:189], v[120:123]
	v_mfma_f32_16x16x32_bf16 v[108:111], v[144:147], v[194:197], v[108:111]
	v_mfma_f32_16x16x32_bf16 v[104:107], v[162:165], v[194:197], v[104:107]
	v_mfma_f32_16x16x32_bf16 v[92:95], v[144:147], v[202:205], v[92:95]
	v_mfma_f32_16x16x32_bf16 v[88:91], v[162:165], v[202:205], v[88:91]
	v_mfma_f32_16x16x32_bf16 v[76:79], v[144:147], v[210:213], v[76:79]
	v_mfma_f32_16x16x32_bf16 v[72:75], v[162:165], v[210:213], v[72:75]
	v_mfma_f32_16x16x32_bf16 v[124:127], v[158:161], v[190:193], v[124:127]
	v_mfma_f32_16x16x32_bf16 v[120:123], v[166:169], v[190:193], v[120:123]
	v_mfma_f32_16x16x32_bf16 v[108:111], v[158:161], v[198:201], v[108:111]
	v_mfma_f32_16x16x32_bf16 v[104:107], v[166:169], v[198:201], v[104:107]
	v_mfma_f32_16x16x32_bf16 v[92:95], v[158:161], v[206:209], v[92:95]
	v_mfma_f32_16x16x32_bf16 v[88:91], v[166:169], v[206:209], v[88:91]
	v_mfma_f32_16x16x32_bf16 v[76:79], v[158:161], v[214:217], v[76:79]
	v_mfma_f32_16x16x32_bf16 v[72:75], v[166:169], v[214:217], v[72:75]
	v_mfma_f32_16x16x32_bf16 v[116:119], v[170:173], v[186:189], v[116:119]
	v_mfma_f32_16x16x32_bf16 v[112:115], v[178:181], v[186:189], v[112:115]
	v_mfma_f32_16x16x32_bf16 v[100:103], v[170:173], v[194:197], v[100:103]
	v_mfma_f32_16x16x32_bf16 v[96:99], v[178:181], v[194:197], v[96:99]
	v_mfma_f32_16x16x32_bf16 v[84:87], v[170:173], v[202:205], v[84:87]
	v_mfma_f32_16x16x32_bf16 v[80:83], v[178:181], v[202:205], v[80:83]
	v_mfma_f32_16x16x32_bf16 v[68:71], v[170:173], v[210:213], v[68:71]
	v_mfma_f32_16x16x32_bf16 v[64:67], v[178:181], v[210:213], v[64:67]
	v_mfma_f32_16x16x32_bf16 v[116:119], v[174:177], v[190:193], v[116:119]
	v_mfma_f32_16x16x32_bf16 v[112:115], v[182:185], v[190:193], v[112:115]
	v_mfma_f32_16x16x32_bf16 v[100:103], v[174:177], v[198:201], v[100:103]
	v_mfma_f32_16x16x32_bf16 v[96:99], v[182:185], v[198:201], v[96:99]
	v_mfma_f32_16x16x32_bf16 v[84:87], v[174:177], v[206:209], v[84:87]
	v_mfma_f32_16x16x32_bf16 v[80:83], v[182:185], v[206:209], v[80:83]
	v_mfma_f32_16x16x32_bf16 v[68:71], v[174:177], v[214:217], v[68:71]
	v_mfma_f32_16x16x32_bf16 v[64:67], v[182:185], v[214:217], v[64:67]
	s_barrier
; #define PG8_STAGE(bufoff, gbase, voff) do { _Pragma("unroll") for (int _i = 0; _i < 2; ++_i) \
;         __builtin_amdgcn_global_load_lds((const unsigned*)((const char*)(gbase) + (voff)[_i]), (PG8_LAS unsigned*)(lds + (bufoff) + ldsw + _i * 8192), 16, 0, 0); } while (0)
; #define PG8_LDA(dst, b, h) do { _Pragma("unroll") for (int m = 0; m < 4; ++m) _Pragma("unroll") for (int k = 0; k < 2; ++k) dst[m][k] = *(const PG8_LAS bf16x8*)(lds + PG8_SA(b, h) + aoff + m * 2048 + k * 1024); } while (0)
; #define PG8_LDB(dst, b, h) do { _Pragma("unroll") for (int n = 0; n < 2; ++n) _Pragma("unroll") for (int k = 0; k < 2; ++k) dst[n][k] = *(const PG8_LAS bf16x8*)(lds + PG8_SB(b, h) + boff + n * 2048 + k * 1024); } while (0)
; #define PG8_MMA(ai, bj, At, Bt) do { __builtin_amdgcn_s_setprio(1); _Pragma("unroll") for (int m = 0; m < 4; ++m) _Pragma("unroll") for (int n = 0; n < 2; ++n) _Pragma("unroll") for (int k = 0; k < 2; ++k) \
;         acc[ai][bj][m][n] = __builtin_amdgcn_mfma_f32_16x16x32_bf16(Bt[n][k], At[m][k], acc[ai][bj][m][n], 0, 0, 0); __builtin_amdgcn_s_setprio(0); } while (0)
; #define PG8_WAIT_V(n) asm volatile("s_waitcnt vmcnt(" #n ")" ::: "memory")
; #define PG8_WAIT_L(n) asm volatile("s_waitcnt lgkmcnt(" #n ")" ::: "memory")
; #define PG8_BAR __builtin_amdgcn_s_barrier()
; #define PG8_SCHED __builtin_amdgcn_sched_barrier(0)
; template <class Epi, class Sched, bool ALIGN_EPI = false, bool SP2 = false>
; __device__ __forceinline__ void gemm_phase(PG8_LAS unsigned char* lds, const Gemm g, const Sched& S, const Epi& E, int tid_in) {
;     ...
;             PG8_LDA(At, 0, 1); PG8_STAGE(PG8_SB(0, 0), b2, voffB); PG8_STAGE(PG8_SB(0, 1), b2 + hstep, voffB); PG8_STAGE(PG8_SA(0, 0), a2, voffA);
;             PG8_WAIT_V(8); PG8_WAIT_L(0); PG8_BAR; PG8_MMA(1, 0, At, B0); PG8_MMA(1, 1, At, B1); PG8_BAR; PG8_SCHED;
;             PG8_LDB(B0, 1, 0); PG8_LDB(B1, 1, 1); PG8_SCHED; PG8_LDA(At, 1, 0); PG8_STAGE(PG8_SA(0, 1), a2 + hstep, voffA);
;             PG8_WAIT_V(8); PG8_WAIT_L(0); PG8_BAR; PG8_MMA(0, 0, At, B0); PG8_MMA(0, 1, At, B1); PG8_BAR; PG8_SCHED;
	s_add_u32 s98, s26, s10
	s_addc_u32 s99, s27, s11
	s_add_u32 s100, s28, s10
	s_addc_u32 s101, s29, s11
	s_add_i32 s59, s47, s0
	s_mov_b32 m0, s59
	ds_read_b128 v[186:189], v156 offset:16384
	global_load_lds_dwordx4 v132, s[26:27]
	s_add_i32 m0, s59, 0x2000
	s_add_u32 s60, s26, 0x40000
	s_addc_u32 s61, s27, 0
	s_add_i32 s59, s48, s0
	global_load_lds_dwordx4 v128, s[26:27]
	s_mov_b32 m0, s59
	ds_read_b128 v[190:193], v156 offset:17408
	global_load_lds_dwordx4 v132, s[60:61]
	s_add_i32 m0, s59, 0x2000
	ds_read_b128 v[194:197], v156 offset:18432
	global_load_lds_dwordx4 v128, s[60:61]
	s_mov_b32 m0, s23
	ds_read_b128 v[198:201], v156 offset:19456
	global_load_lds_dwordx4 v134, s[28:29]
	s_mov_b32 m0, s37
	ds_read_b128 v[202:205], v156 offset:20480
	global_load_lds_dwordx4 v130, s[28:29]
	ds_read_b128 v[206:209], v156 offset:21504
	ds_read_b128 v[210:213], v156 offset:22528
	ds_read_b128 v[214:217], v156 offset:23552
	s_waitcnt vmcnt(8) lgkmcnt(0)
	s_barrier
	v_mfma_f32_16x16x32_bf16 v[60:63], v[144:147], v[186:189], v[60:63]
	v_mfma_f32_16x16x32_bf16 v[56:59], v[162:165], v[186:189], v[56:59]
	v_mfma_f32_16x16x32_bf16 v[44:47], v[144:147], v[194:197], v[44:47]
	v_mfma_f32_16x16x32_bf16 v[40:43], v[162:165], v[194:197], v[40:43]
	v_mfma_f32_16x16x32_bf16 v[28:31], v[144:147], v[202:205], v[28:31]
	v_mfma_f32_16x16x32_bf16 v[24:27], v[162:165], v[202:205], v[24:27]
	v_mfma_f32_16x16x32_bf16 v[12:15], v[144:147], v[210:213], v[12:15]
	v_mfma_f32_16x16x32_bf16 v[8:11], v[162:165], v[210:213], v[8:11]
	v_mfma_f32_16x16x32_bf16 v[60:63], v[158:161], v[190:193], v[60:63]
	v_mfma_f32_16x16x32_bf16 v[56:59], v[166:169], v[190:193], v[56:59]
	v_mfma_f32_16x16x32_bf16 v[44:47], v[158:161], v[198:201], v[44:47]
	v_mfma_f32_16x16x32_bf16 v[40:43], v[166:169], v[198:201], v[40:43]
	v_mfma_f32_16x16x32_bf16 v[28:31], v[158:161], v[206:209], v[28:31]
	v_mfma_f32_16x16x32_bf16 v[24:27], v[166:169], v[206:209], v[24:27]
	v_mfma_f32_16x16x32_bf16 v[12:15], v[158:161], v[214:217], v[12:15]
	v_mfma_f32_16x16x32_bf16 v[8:11], v[166:169], v[214:217], v[8:11]
	v_mfma_f32_16x16x32_bf16 v[52:55], v[170:173], v[186:189], v[52:55]
	v_mfma_f32_16x16x32_bf16 v[48:51], v[178:181], v[186:189], v[48:51]
	v_mfma_f32_16x16x32_bf16 v[36:39], v[170:173], v[194:197], v[36:39]
	v_mfma_f32_16x16x32_bf16 v[32:35], v[178:181], v[194:197], v[32:35]
	v_mfma_f32_16x16x32_bf16 v[20:23], v[170:173], v[202:205], v[20:23]
	v_mfma_f32_16x16x32_bf16 v[16:19], v[178:181], v[202:205], v[16:19]
	v_mfma_f32_16x16x32_bf16 v[4:7], v[170:173], v[210:213], v[4:7]
	v_mfma_f32_16x16x32_bf16 v[0:3], v[178:181], v[210:213], v[0:3]
	v_mfma_f32_16x16x32_bf16 v[52:55], v[174:177], v[190:193], v[52:55]
	v_mfma_f32_16x16x32_bf16 v[48:51], v[182:185], v[190:193], v[48:51]
	v_mfma_f32_16x16x32_bf16 v[36:39], v[174:177], v[198:201], v[36:39]
	v_mfma_f32_16x16x32_bf16 v[32:35], v[182:185], v[198:201], v[32:35]
	v_mfma_f32_16x16x32_bf16 v[20:23], v[174:177], v[206:209], v[20:23]
	v_mfma_f32_16x16x32_bf16 v[16:19], v[182:185], v[206:209], v[16:19]
	v_mfma_f32_16x16x32_bf16 v[4:7], v[174:177], v[214:217], v[4:7]
	v_mfma_f32_16x16x32_bf16 v[0:3], v[182:185], v[214:217], v[0:3]
	s_barrier
	s_add_i32 s59, 0, 0x18000
	s_add_i32 s60, 0, 0x1c000
	s_add_u32 s28, s28, 0x40000
	s_addc_u32 s29, s29, 0
	s_mov_b32 m0, s38
	v_add_u32_e32 v157, s59, v151
	global_load_lds_dwordx4 v134, s[28:29]
	s_mov_b32 m0, s39
	ds_read_b128 v[144:147], v157
	global_load_lds_dwordx4 v130, s[28:29]
	ds_read_b128 v[158:161], v157 offset:1024
	ds_read_b128 v[162:165], v157 offset:2048
	ds_read_b128 v[166:169], v157 offset:3072
	v_add_u32_e32 v157, s60, v151
	ds_read_b128 v[170:173], v157
	ds_read_b128 v[174:177], v157 offset:1024
	ds_read_b128 v[178:181], v157 offset:2048
	ds_read_b128 v[182:185], v157 offset:3072
	ds_read_b128 v[186:189], v156 offset:32768
	ds_read_b128 v[190:193], v156 offset:33792
	ds_read_b128 v[194:197], v156 offset:34816
	ds_read_b128 v[198:201], v156 offset:35840
	ds_read_b128 v[202:205], v156 offset:36864
	ds_read_b128 v[206:209], v156 offset:37888
	ds_read_b128 v[210:213], v156 offset:38912
	ds_read_b128 v[214:217], v156 offset:39936
	s_waitcnt vmcnt(8) lgkmcnt(0)
	s_barrier
; #define PG8_STAGE(bufoff, gbase, voff) do { _Pragma("unroll") for (int _i = 0; _i < 2; ++_i) \
;         __builtin_amdgcn_global_load_lds((const unsigned*)((const char*)(gbase) + (voff)[_i]), (PG8_LAS unsigned*)(lds + (bufoff) + ldsw + _i * 8192), 16, 0, 0); } while (0)
; #define PG8_LDA(dst, b, h) do { _Pragma("unroll") for (int m = 0; m < 4; ++m) _Pragma("unroll") for (int k = 0; k < 2; ++k) dst[m][k] = *(const PG8_LAS bf16x8*)(lds + PG8_SA(b, h) + aoff + m * 2048 + k * 1024); } while (0)
; #define PG8_MMA(ai, bj, At, Bt) do { __builtin_amdgcn_s_setprio(1); _Pragma("unroll") for (int m = 0; m < 4; ++m) _Pragma("unroll") for (int n = 0; n < 2; ++n) _Pragma("unroll") for (int k = 0; k < 2; ++k) \
;         acc[ai][bj][m][n] = __builtin_amdgcn_mfma_f32_16x16x32_bf16(Bt[n][k], At[m][k], acc[ai][bj][m][n], 0, 0, 0); __builtin_amdgcn_s_setprio(0); } while (0)
; #define PG8_WAIT_V(n) asm volatile("s_waitcnt vmcnt(" #n ")" ::: "memory")
; #define PG8_WAIT_L(n) asm volatile("s_waitcnt lgkmcnt(" #n ")" ::: "memory")
; #define PG8_BAR __builtin_amdgcn_s_barrier()
; #define PG8_SCHED __builtin_amdgcn_sched_barrier(0)
; template <class Epi, class Sched, bool ALIGN_EPI = false, bool SP2 = false>
; __device__ __forceinline__ void gemm_phase(PG8_LAS unsigned char* lds, const Gemm g, const Sched& S, const Epi& E, int tid_in) {
;     ...
;             PG8_WAIT_V(8); PG8_WAIT_L(0); PG8_BAR; PG8_MMA(0, 0, At, B0); PG8_MMA(0, 1, At, B1); PG8_BAR; PG8_SCHED;
;             PG8_LDA(At, 1, 1); PG8_STAGE(PG8_SB(1, 0), b3, voffB); PG8_STAGE(PG8_SB(1, 1), b3 + hstep, voffB); PG8_STAGE(PG8_SA(1, 0), a3, voffA);
;             PG8_WAIT_V(8); PG8_WAIT_L(0); PG8_BAR; PG8_MMA(1, 0, At, B0); PG8_MMA(1, 1, At, B1); PG8_BAR; PG8_SCHED;
;     ...
;         }
	v_mfma_f32_16x16x32_bf16 v[124:127], v[144:147], v[186:189], v[124:127]
	v_mfma_f32_16x16x32_bf16 v[120:123], v[162:165], v[186:189], v[120:123]
	v_mfma_f32_16x16x32_bf16 v[108:111], v[144:147], v[194:197], v[108:111]
	v_mfma_f32_16x16x32_bf16 v[104:107], v[162:165], v[194:197], v[104:107]
	v_mfma_f32_16x16x32_bf16 v[92:95], v[144:147], v[202:205], v[92:95]
	v_mfma_f32_16x16x32_bf16 v[88:91], v[162:165], v[202:205], v[88:91]
	v_mfma_f32_16x16x32_bf16 v[76:79], v[144:147], v[210:213], v[76:79]
	v_mfma_f32_16x16x32_bf16 v[72:75], v[162:165], v[210:213], v[72:75]
	v_mfma_f32_16x16x32_bf16 v[124:127], v[158:161], v[190:193], v[124:127]
	v_mfma_f32_16x16x32_bf16 v[120:123], v[166:169], v[190:193], v[120:123]
	v_mfma_f32_16x16x32_bf16 v[108:111], v[158:161], v[198:201], v[108:111]
	v_mfma_f32_16x16x32_bf16 v[104:107], v[166:169], v[198:201], v[104:107]
	v_mfma_f32_16x16x32_bf16 v[92:95], v[158:161], v[206:209], v[92:95]
	v_mfma_f32_16x16x32_bf16 v[88:91], v[166:169], v[206:209], v[88:91]
	v_mfma_f32_16x16x32_bf16 v[76:79], v[158:161], v[214:217], v[76:79]
	v_mfma_f32_16x16x32_bf16 v[72:75], v[166:169], v[214:217], v[72:75]
	v_mfma_f32_16x16x32_bf16 v[116:119], v[170:173], v[186:189], v[116:119]
	v_mfma_f32_16x16x32_bf16 v[112:115], v[178:181], v[186:189], v[112:115]
	v_mfma_f32_16x16x32_bf16 v[100:103], v[170:173], v[194:197], v[100:103]
	v_mfma_f32_16x16x32_bf16 v[96:99], v[178:181], v[194:197], v[96:99]
	v_mfma_f32_16x16x32_bf16 v[84:87], v[170:173], v[202:205], v[84:87]
	v_mfma_f32_16x16x32_bf16 v[80:83], v[178:181], v[202:205], v[80:83]
	v_mfma_f32_16x16x32_bf16 v[68:71], v[170:173], v[210:213], v[68:71]
	v_mfma_f32_16x16x32_bf16 v[64:67], v[178:181], v[210:213], v[64:67]
	v_mfma_f32_16x16x32_bf16 v[116:119], v[174:177], v[190:193], v[116:119]
	v_mfma_f32_16x16x32_bf16 v[112:115], v[182:185], v[190:193], v[112:115]
	v_mfma_f32_16x16x32_bf16 v[100:103], v[174:177], v[198:201], v[100:103]
	v_mfma_f32_16x16x32_bf16 v[96:99], v[182:185], v[198:201], v[96:99]
	v_mfma_f32_16x16x32_bf16 v[84:87], v[174:177], v[206:209], v[84:87]
	v_mfma_f32_16x16x32_bf16 v[80:83], v[182:185], v[206:209], v[80:83]
	v_mfma_f32_16x16x32_bf16 v[68:71], v[174:177], v[214:217], v[68:71]
	v_mfma_f32_16x16x32_bf16 v[64:67], v[182:185], v[214:217], v[64:67]
	s_barrier
	s_add_i32 s28, s59, s0
	s_mov_b32 m0, s28
	ds_read_b128 v[186:189], v156 offset:49152
	global_load_lds_dwordx4 v132, s[98:99]
	s_add_i32 m0, s28, 0x2000
	s_add_u32 s26, s26, 0x40080
	s_addc_u32 s27, s27, 0
	s_add_i32 s28, s60, s0
	global_load_lds_dwordx4 v128, s[98:99]
	s_mov_b32 m0, s28
	ds_read_b128 v[190:193], v156 offset:50176
	global_load_lds_dwordx4 v132, s[26:27]
	s_add_i32 m0, s28, 0x2000
	ds_read_b128 v[194:197], v156 offset:51200
	global_load_lds_dwordx4 v128, s[26:27]
	s_mov_b32 m0, s44
	ds_read_b128 v[198:201], v156 offset:52224
	global_load_lds_dwordx4 v134, s[100:101]
	s_mov_b32 m0, s45
	ds_read_b128 v[202:205], v156 offset:53248
	global_load_lds_dwordx4 v130, s[100:101]
	ds_read_b128 v[206:209], v156 offset:54272
	ds_read_b128 v[210:213], v156 offset:55296
	ds_read_b128 v[214:217], v156 offset:56320
	s_waitcnt vmcnt(8) lgkmcnt(0)
	s_barrier
	v_mfma_f32_16x16x32_bf16 v[60:63], v[144:147], v[186:189], v[60:63]
	v_mfma_f32_16x16x32_bf16 v[56:59], v[162:165], v[186:189], v[56:59]
	v_mfma_f32_16x16x32_bf16 v[44:47], v[144:147], v[194:197], v[44:47]
	v_mfma_f32_16x16x32_bf16 v[40:43], v[162:165], v[194:197], v[40:43]
	v_mfma_f32_16x16x32_bf16 v[28:31], v[144:147], v[202:205], v[28:31]
	v_mfma_f32_16x16x32_bf16 v[24:27], v[162:165], v[202:205], v[24:27]
	v_mfma_f32_16x16x32_bf16 v[12:15], v[144:147], v[210:213], v[12:15]
	v_mfma_f32_16x16x32_bf16 v[8:11], v[162:165], v[210:213], v[8:11]
	v_mfma_f32_16x16x32_bf16 v[60:63], v[158:161], v[190:193], v[60:63]
	v_mfma_f32_16x16x32_bf16 v[56:59], v[166:169], v[190:193], v[56:59]
	v_mfma_f32_16x16x32_bf16 v[44:47], v[158:161], v[198:201], v[44:47]
	v_mfma_f32_16x16x32_bf16 v[40:43], v[166:169], v[198:201], v[40:43]
	v_mfma_f32_16x16x32_bf16 v[28:31], v[158:161], v[206:209], v[28:31]
	v_mfma_f32_16x16x32_bf16 v[24:27], v[166:169], v[206:209], v[24:27]
	v_mfma_f32_16x16x32_bf16 v[12:15], v[158:161], v[214:217], v[12:15]
	v_mfma_f32_16x16x32_bf16 v[8:11], v[166:169], v[214:217], v[8:11]
	v_mfma_f32_16x16x32_bf16 v[52:55], v[170:173], v[186:189], v[52:55]
	v_mfma_f32_16x16x32_bf16 v[48:51], v[178:181], v[186:189], v[48:51]
	v_mfma_f32_16x16x32_bf16 v[36:39], v[170:173], v[194:197], v[36:39]
	v_mfma_f32_16x16x32_bf16 v[32:35], v[178:181], v[194:197], v[32:35]
	v_mfma_f32_16x16x32_bf16 v[20:23], v[170:173], v[202:205], v[20:23]
	v_mfma_f32_16x16x32_bf16 v[16:19], v[178:181], v[202:205], v[16:19]
	v_mfma_f32_16x16x32_bf16 v[4:7], v[170:173], v[210:213], v[4:7]
	v_mfma_f32_16x16x32_bf16 v[0:3], v[178:181], v[210:213], v[0:3]
	v_mfma_f32_16x16x32_bf16 v[52:55], v[174:177], v[190:193], v[52:55]
	v_mfma_f32_16x16x32_bf16 v[48:51], v[182:185], v[190:193], v[48:51]
	v_mfma_f32_16x16x32_bf16 v[36:39], v[174:177], v[198:201], v[36:39]
	v_mfma_f32_16x16x32_bf16 v[32:35], v[182:185], v[198:201], v[32:35]
	v_mfma_f32_16x16x32_bf16 v[20:23], v[174:177], v[206:209], v[20:23]
	v_mfma_f32_16x16x32_bf16 v[16:19], v[182:185], v[206:209], v[16:19]
	v_mfma_f32_16x16x32_bf16 v[4:7], v[174:177], v[214:217], v[4:7]
	v_mfma_f32_16x16x32_bf16 v[0:3], v[182:185], v[214:217], v[0:3]
	s_barrier
	s_add_i32 s58, s58, 2
	s_add_u32 s24, s24, 0x100
	s_addc_u32 s25, s25, 0
	s_add_u32 s56, s56, 0x100
	s_addc_u32 s57, s57, 0
	s_cmp_gt_u32 s58, 13
	s_cbranch_scc0 .LBB0_1238
	s_cmp_eq_u32 s50, 1
	s_cbranch_scc0 .Lww_done_p9
	v_readlane_b32 s98, v248, 0
	s_nop 3
	s_cmp_eq_u32 s98, 0
	s_cbranch_scc0 .Lww_bar_p9
	v_readlane_b32 s98, v248, 32
	s_nop 3
	s_cmp_eq_u32 s98, 1
	s_cbranch_scc0 .Lww_bar_p9
	v_mov_b32_e32 v246, 0x3500
	s_mov_b32 s98, 0

; #define PG8_STAGE(bufoff, gbase, voff) do { _Pragma("unroll") for (int _i = 0; _i < 2; ++_i) \
;         __builtin_amdgcn_global_load_lds((const unsigned*)((const char*)(gbase) + (voff)[_i]), (PG8_LAS unsigned*)(lds + (bufoff) + ldsw + _i * 8192), 16, 0, 0); } while (0)
; #define PG8_WAIT_V(n) asm volatile("s_waitcnt vmcnt(" #n ")" ::: "memory")
; template <class Epi, class Sched, bool ALIGN_EPI = false, bool SP2 = false>
; __device__ __forceinline__ void gemm_phase(PG8_LAS unsigned char* lds, const Gemm g, const Sched& S, const Epi& E, int tid_in) {
;     ...
;         const bool has_next = S.next(ui + 1, nxt);
;         const char* nA = has_next ? (const char*)g.A + (size_t)nxt.pm * tstep : cA; const char* nB = has_next ? (const char*)g.Bt + (size_t)nxt.pn * tstep : cB;
;         for (int t = 0; t < nt; t += 2) {
;             if constexpr (Epi::MIDK) { if (t == Epi::MIDK_T) { if (wr == 0) PG8_BAR; E.mid(acc, cur, wr, wc, fr, fq); if (wr == 1) PG8_BAR; } }
;             const bool last = (t == nt - 2);
;             const char* a1 = cA + (size_t)(t + 1) * kstep;
;             const char* a2 = last ? nA : cA + (size_t)(t + 2) * kstep; const char* b2 = last ? nB : cB + (size_t)(t + 2) * kstep;
;             const char* a3 = a2 + kstep; const char* b3 = b2 + kstep;
;             if (last && has_next) S.a_ready(nxt);
;             if constexpr (SP2) {
;             PG8_LDB(B0, 0, 0); PG8_LDB(B1, 0, 1); PG8_SCHED; PG8_LDA(At, 0, 0); PG8_STAGE(PG8_SA(1, 1), a1 + hstep, voffA);
;             PG8_WAIT_V(8); PG8_WAIT_L(0); PG8_BAR; PG8_MMA(0, 0, At, B0); PG8_MMA(0, 1, At, B1); PG8_BAR; PG8_SCHED;
;             PG8_LDA(At, 0, 1); PG8_STAGE(PG8_SB(0, 0), b2, voffB); PG8_STAGE(PG8_SB(0, 1), b2 + hstep, voffB); PG8_STAGE(PG8_SA(0, 0), a2, voffA);
;             PG8_WAIT_V(8); PG8_WAIT_L(0); PG8_BAR; PG8_MMA(1, 0, At, B0); PG8_MMA(1, 1, At, B1); PG8_BAR; PG8_SCHED;
;             PG8_LDB(B0, 1, 0); PG8_LDB(B1, 1, 1); PG8_SCHED; PG8_LDA(At, 1, 0); PG8_STAGE(PG8_SA(0, 1), a2 + hstep, voffA);
;             PG8_WAIT_V(8); PG8_WAIT_L(0); PG8_BAR; PG8_MMA(0, 0, At, B0); PG8_MMA(0, 1, At, B1); PG8_BAR; PG8_SCHED;
;             PG8_LDA(At, 1, 1); PG8_STAGE(PG8_SB(1, 0), b3, voffB); PG8_STAGE(PG8_SB(1, 1), b3 + hstep, voffB); PG8_STAGE(PG8_SA(1, 0), a3, voffA);
;             PG8_WAIT_V(8); PG8_WAIT_L(0); PG8_BAR; PG8_MMA(1, 0, At, B0); PG8_MMA(1, 1, At, B1); PG8_BAR; PG8_SCHED;
.LBB0_1320:
	s_add_u32 s48, s22, 0x100
	s_addc_u32 s49, s23, 0
	s_mov_b32 s50, -2
	s_waitcnt vmcnt(0)
	s_add_u32 s2, s20, 0x100
	s_addc_u32 s3, s21, 0
	s_cmp_eq_u32 s50, 40
	s_cselect_b32 s25, s17, s3
	s_cselect_b32 s24, s16, s2
	s_cselect_b32 s23, s19, s49
	s_cselect_b32 s22, s18, s48
	s_add_i32 m0, s34, 0xc000
	ds_read_b128 v[128:131], v195
	global_load_lds_dwordx4 v168, s[20:21]
	s_add_i32 m0, s34, 0xe000
	ds_read_b128 v[132:135], v195 offset:1024
	global_load_lds_dwordx4 v170, s[20:21]
	ds_read_b128 v[136:139], v195 offset:2048
	ds_read_b128 v[140:143], v195 offset:3072
	ds_read_b128 v[144:147], v196
	ds_read_b128 v[148:151], v196 offset:1024
	ds_read_b128 v[152:155], v196 offset:2048
	ds_read_b128 v[156:159], v196 offset:3072
	ds_read_b128 v[176:179], v197
	ds_read_b128 v[180:183], v197 offset:1024
	ds_read_b128 v[184:187], v197 offset:2048
	ds_read_b128 v[188:191], v197 offset:3072
	ds_read_b128 v[198:201], v197 offset:4096
	ds_read_b128 v[202:205], v197 offset:5120
	ds_read_b128 v[206:209], v197 offset:6144
	ds_read_b128 v[210:213], v197 offset:7168
	s_waitcnt vmcnt(8) lgkmcnt(0)
	s_barrier
	v_mfma_f32_16x16x32_bf16 v[120:123], v[128:131], v[176:179], 0
	v_mfma_f32_16x16x32_bf16 v[124:127], v[136:139], v[176:179], 0
	v_mfma_f32_16x16x32_bf16 v[104:107], v[128:131], v[184:187], 0
	v_mfma_f32_16x16x32_bf16 v[108:111], v[136:139], v[184:187], 0
	v_mfma_f32_16x16x32_bf16 v[88:91], v[128:131], v[198:201], 0
	v_mfma_f32_16x16x32_bf16 v[92:95], v[136:139], v[198:201], 0
	v_mfma_f32_16x16x32_bf16 v[72:75], v[128:131], v[206:209], 0
	v_mfma_f32_16x16x32_bf16 v[76:79], v[136:139], v[206:209], 0
	v_mfma_f32_16x16x32_bf16 v[120:123], v[132:135], v[180:183], v[120:123]
	v_mfma_f32_16x16x32_bf16 v[124:127], v[140:143], v[180:183], v[124:127]
	v_mfma_f32_16x16x32_bf16 v[104:107], v[132:135], v[188:191], v[104:107]
	v_mfma_f32_16x16x32_bf16 v[108:111], v[140:143], v[188:191], v[108:111]
	v_mfma_f32_16x16x32_bf16 v[88:91], v[132:135], v[202:205], v[88:91]
	v_mfma_f32_16x16x32_bf16 v[92:95], v[140:143], v[202:205], v[92:95]
	v_mfma_f32_16x16x32_bf16 v[72:75], v[132:135], v[210:213], v[72:75]
	v_mfma_f32_16x16x32_bf16 v[76:79], v[140:143], v[210:213], v[76:79]
	v_mfma_f32_16x16x32_bf16 v[112:115], v[144:147], v[176:179], 0
	v_mfma_f32_16x16x32_bf16 v[116:119], v[152:155], v[176:179], 0
	v_mfma_f32_16x16x32_bf16 v[96:99], v[144:147], v[184:187], 0
	v_mfma_f32_16x16x32_bf16 v[100:103], v[152:155], v[184:187], 0
	v_mfma_f32_16x16x32_bf16 v[80:83], v[144:147], v[198:201], 0
	v_mfma_f32_16x16x32_bf16 v[84:87], v[152:155], v[198:201], 0
	v_mfma_f32_16x16x32_bf16 v[64:67], v[144:147], v[206:209], 0
	v_mfma_f32_16x16x32_bf16 v[68:71], v[152:155], v[206:209], 0
	v_mfma_f32_16x16x32_bf16 v[112:115], v[148:151], v[180:183], v[112:115]
	v_mfma_f32_16x16x32_bf16 v[116:119], v[156:159], v[180:183], v[116:119]
	v_mfma_f32_16x16x32_bf16 v[96:99], v[148:151], v[188:191], v[96:99]
	v_mfma_f32_16x16x32_bf16 v[100:103], v[156:159], v[188:191], v[100:103]
	v_mfma_f32_16x16x32_bf16 v[80:83], v[148:151], v[202:205], v[80:83]
	v_mfma_f32_16x16x32_bf16 v[84:87], v[156:159], v[202:205], v[84:87]
	v_mfma_f32_16x16x32_bf16 v[64:67], v[148:151], v[210:213], v[64:67]
	v_mfma_f32_16x16x32_bf16 v[68:71], v[156:159], v[210:213], v[68:71]
	s_barrier
	s_add_u32 s98, s22, s10
	s_addc_u32 s99, s23, s11
	s_add_u32 s100, s24, s10
	s_addc_u32 s101, s25, s11
	s_add_i32 s20, s42, s31
	s_mov_b32 m0, s20
	ds_read_b128 v[176:179], v197 offset:16384
	global_load_lds_dwordx4 v162, s[22:23]
	s_add_i32 m0, s20, 0x2000
	s_add_u32 s20, s22, 0xb0000
	s_addc_u32 s21, s23, 0
	s_add_i32 s51, s43, s31
	global_load_lds_dwordx4 v166, s[22:23]
	s_mov_b32 m0, s51
	ds_read_b128 v[180:183], v197 offset:17408
	global_load_lds_dwordx4 v162, s[20:21]
	s_add_i32 m0, s51, 0x2000
	ds_read_b128 v[184:187], v197 offset:18432
	global_load_lds_dwordx4 v166, s[20:21]
	s_mov_b32 m0, s34
	ds_read_b128 v[188:191], v197 offset:19456
	global_load_lds_dwordx4 v160, s[24:25]
	s_mov_b32 m0, s35
	ds_read_b128 v[198:201], v197 offset:20480
	global_load_lds_dwordx4 v164, s[24:25]
	ds_read_b128 v[202:205], v197 offset:21504
	ds_read_b128 v[206:209], v197 offset:22528
	ds_read_b128 v[210:213], v197 offset:23552
	s_waitcnt vmcnt(8) lgkmcnt(0)
	s_barrier
	v_mfma_f32_16x16x32_bf16 v[56:59], v[128:131], v[176:179], 0
	v_mfma_f32_16x16x32_bf16 v[60:63], v[136:139], v[176:179], 0
	v_mfma_f32_16x16x32_bf16 v[40:43], v[128:131], v[184:187], 0
	v_mfma_f32_16x16x32_bf16 v[44:47], v[136:139], v[184:187], 0
	v_mfma_f32_16x16x32_bf16 v[24:27], v[128:131], v[198:201], 0
	v_mfma_f32_16x16x32_bf16 v[28:31], v[136:139], v[198:201], 0
	v_mfma_f32_16x16x32_bf16 v[8:11], v[128:131], v[206:209], 0
	v_mfma_f32_16x16x32_bf16 v[12:15], v[136:139], v[206:209], 0
	v_mfma_f32_16x16x32_bf16 v[56:59], v[132:135], v[180:183], v[56:59]
	v_mfma_f32_16x16x32_bf16 v[60:63], v[140:143], v[180:183], v[60:63]
	v_mfma_f32_16x16x32_bf16 v[40:43], v[132:135], v[188:191], v[40:43]
	v_mfma_f32_16x16x32_bf16 v[44:47], v[140:143], v[188:191], v[44:47]
	v_mfma_f32_16x16x32_bf16 v[24:27], v[132:135], v[202:205], v[24:27]
	v_mfma_f32_16x16x32_bf16 v[28:31], v[140:143], v[202:205], v[28:31]
	v_mfma_f32_16x16x32_bf16 v[8:11], v[132:135], v[210:213], v[8:11]
	v_mfma_f32_16x16x32_bf16 v[12:15], v[140:143], v[210:213], v[12:15]
	v_mfma_f32_16x16x32_bf16 v[48:51], v[144:147], v[176:179], 0
	v_mfma_f32_16x16x32_bf16 v[52:55], v[152:155], v[176:179], 0
	v_mfma_f32_16x16x32_bf16 v[32:35], v[144:147], v[184:187], 0
	v_mfma_f32_16x16x32_bf16 v[36:39], v[152:155], v[184:187], 0
	v_mfma_f32_16x16x32_bf16 v[16:19], v[144:147], v[198:201], 0
	v_mfma_f32_16x16x32_bf16 v[20:23], v[152:155], v[198:201], 0
	v_mfma_f32_16x16x32_bf16 v[4:7], v[144:147], v[206:209], 0
	v_mfma_f32_16x16x32_bf16 v[0:3], v[152:155], v[206:209], 0
	v_mfma_f32_16x16x32_bf16 v[48:51], v[148:151], v[180:183], v[48:51]
	v_mfma_f32_16x16x32_bf16 v[52:55], v[156:159], v[180:183], v[52:55]
	v_mfma_f32_16x16x32_bf16 v[32:35], v[148:151], v[188:191], v[32:35]
	v_mfma_f32_16x16x32_bf16 v[36:39], v[156:159], v[188:191], v[36:39]
	v_mfma_f32_16x16x32_bf16 v[16:19], v[148:151], v[202:205], v[16:19]
	v_mfma_f32_16x16x32_bf16 v[20:23], v[156:159], v[202:205], v[20:23]
	v_mfma_f32_16x16x32_bf16 v[4:7], v[148:151], v[210:213], v[4:7]
	v_mfma_f32_16x16x32_bf16 v[0:3], v[156:159], v[210:213], v[0:3]
	s_barrier
; #define PG8_STAGE(bufoff, gbase, voff) do { _Pragma("unroll") for (int _i = 0; _i < 2; ++_i) \
;         __builtin_amdgcn_global_load_lds((const unsigned*)((const char*)(gbase) + (voff)[_i]), (PG8_LAS unsigned*)(lds + (bufoff) + ldsw + _i * 8192), 16, 0, 0); } while (0)
; #define PG8_LDA(dst, b, h) do { _Pragma("unroll") for (int m = 0; m < 4; ++m) _Pragma("unroll") for (int k = 0; k < 2; ++k) dst[m][k] = *(const PG8_LAS bf16x8*)(lds + PG8_SA(b, h) + aoff + m * 2048 + k * 1024); } while (0)
; #define PG8_LDB(dst, b, h) do { _Pragma("unroll") for (int n = 0; n < 2; ++n) _Pragma("unroll") for (int k = 0; k < 2; ++k) dst[n][k] = *(const PG8_LAS bf16x8*)(lds + PG8_SB(b, h) + boff + n * 2048 + k * 1024); } while (0)
; #define PG8_MMA(ai, bj, At, Bt) do { __builtin_amdgcn_s_setprio(1); _Pragma("unroll") for (int m = 0; m < 4; ++m) _Pragma("unroll") for (int n = 0; n < 2; ++n) _Pragma("unroll") for (int k = 0; k < 2; ++k) \
;         acc[ai][bj][m][n] = __builtin_amdgcn_mfma_f32_16x16x32_bf16(Bt[n][k], At[m][k], acc[ai][bj][m][n], 0, 0, 0); __builtin_amdgcn_s_setprio(0); } while (0)
; #define PG8_WAIT_V(n) asm volatile("s_waitcnt vmcnt(" #n ")" ::: "memory")
; #define PG8_WAIT_L(n) asm volatile("s_waitcnt lgkmcnt(" #n ")" ::: "memory")
; #define PG8_BAR __builtin_amdgcn_s_barrier()
; #define PG8_SCHED __builtin_amdgcn_sched_barrier(0)
; template <class Epi, class Sched, bool ALIGN_EPI = false, bool SP2 = false>
; __device__ __forceinline__ void gemm_phase(PG8_LAS unsigned char* lds, const Gemm g, const Sched& S, const Epi& E, int tid_in) {
;     ...
;             PG8_LDA(At, 0, 1); PG8_STAGE(PG8_SB(0, 0), b2, voffB); PG8_STAGE(PG8_SB(0, 1), b2 + hstep, voffB); PG8_STAGE(PG8_SA(0, 0), a2, voffA);
;             PG8_WAIT_V(8); PG8_WAIT_L(0); PG8_BAR; PG8_MMA(1, 0, At, B0); PG8_MMA(1, 1, At, B1); PG8_BAR; PG8_SCHED;
;             PG8_LDB(B0, 1, 0); PG8_LDB(B1, 1, 1); PG8_SCHED; PG8_LDA(At, 1, 0); PG8_STAGE(PG8_SA(0, 1), a2 + hstep, voffA);
;             PG8_WAIT_V(8); PG8_WAIT_L(0); PG8_BAR; PG8_MMA(0, 0, At, B0); PG8_MMA(0, 1, At, B1); PG8_BAR; PG8_SCHED;
;             PG8_LDA(At, 1, 1); PG8_STAGE(PG8_SB(1, 0), b3, voffB); PG8_STAGE(PG8_SB(1, 1), b3 + hstep, voffB); PG8_STAGE(PG8_SA(1, 0), a3, voffA);
;             PG8_WAIT_V(8); PG8_WAIT_L(0); PG8_BAR; PG8_MMA(1, 0, At, B0); PG8_MMA(1, 1, At, B1); PG8_BAR; PG8_SCHED;
	s_add_i32 s51, 0, 0x18000
	s_add_i32 s52, 0, 0x1c000
	s_add_u32 s20, s24, 0xb0000
	s_addc_u32 s21, s25, 0
	s_mov_b32 m0, s36
	s_nop 0
	global_load_lds_dwordx4 v160, s[20:21]
	s_mov_b32 m0, s37
	s_nop 0
	global_load_lds_dwordx4 v164, s[20:21]
	v_add_u32_e32 v140, s51, v193
	v_add_u32_e32 v156, s52, v193
	ds_read_b128 v[128:131], v140
	ds_read_b128 v[132:135], v140 offset:1024
	ds_read_b128 v[136:139], v140 offset:2048
	ds_read_b128 v[140:143], v140 offset:3072
	ds_read_b128 v[144:147], v156
	ds_read_b128 v[148:151], v156 offset:1024
	ds_read_b128 v[152:155], v156 offset:2048
	ds_read_b128 v[156:159], v156 offset:3072
	ds_read_b128 v[176:179], v197 offset:32768
	ds_read_b128 v[180:183], v197 offset:33792
	ds_read_b128 v[184:187], v197 offset:34816
	ds_read_b128 v[188:191], v197 offset:35840
	ds_read_b128 v[198:201], v197 offset:36864
	ds_read_b128 v[202:205], v197 offset:37888
	ds_read_b128 v[206:209], v197 offset:38912
	ds_read_b128 v[210:213], v197 offset:39936
	s_waitcnt vmcnt(8) lgkmcnt(0)
	s_barrier
	v_mfma_f32_16x16x32_bf16 v[120:123], v[128:131], v[176:179], v[120:123]
	v_mfma_f32_16x16x32_bf16 v[124:127], v[136:139], v[176:179], v[124:127]
	v_mfma_f32_16x16x32_bf16 v[104:107], v[128:131], v[184:187], v[104:107]
	v_mfma_f32_16x16x32_bf16 v[108:111], v[136:139], v[184:187], v[108:111]
	v_mfma_f32_16x16x32_bf16 v[88:91], v[128:131], v[198:201], v[88:91]
	v_mfma_f32_16x16x32_bf16 v[92:95], v[136:139], v[198:201], v[92:95]
	v_mfma_f32_16x16x32_bf16 v[72:75], v[128:131], v[206:209], v[72:75]
	v_mfma_f32_16x16x32_bf16 v[76:79], v[136:139], v[206:209], v[76:79]
	v_mfma_f32_16x16x32_bf16 v[120:123], v[132:135], v[180:183], v[120:123]
	v_mfma_f32_16x16x32_bf16 v[124:127], v[140:143], v[180:183], v[124:127]
	v_mfma_f32_16x16x32_bf16 v[104:107], v[132:135], v[188:191], v[104:107]
	v_mfma_f32_16x16x32_bf16 v[108:111], v[140:143], v[188:191], v[108:111]
	v_mfma_f32_16x16x32_bf16 v[88:91], v[132:135], v[202:205], v[88:91]
	v_mfma_f32_16x16x32_bf16 v[92:95], v[140:143], v[202:205], v[92:95]
	v_mfma_f32_16x16x32_bf16 v[72:75], v[132:135], v[210:213], v[72:75]
	v_mfma_f32_16x16x32_bf16 v[76:79], v[140:143], v[210:213], v[76:79]
	v_mfma_f32_16x16x32_bf16 v[112:115], v[144:147], v[176:179], v[112:115]
	v_mfma_f32_16x16x32_bf16 v[116:119], v[152:155], v[176:179], v[116:119]
	v_mfma_f32_16x16x32_bf16 v[96:99], v[144:147], v[184:187], v[96:99]
	v_mfma_f32_16x16x32_bf16 v[100:103], v[152:155], v[184:187], v[100:103]
	v_mfma_f32_16x16x32_bf16 v[80:83], v[144:147], v[198:201], v[80:83]
	v_mfma_f32_16x16x32_bf16 v[84:87], v[152:155], v[198:201], v[84:87]
	v_mfma_f32_16x16x32_bf16 v[64:67], v[144:147], v[206:209], v[64:67]
	v_mfma_f32_16x16x32_bf16 v[68:71], v[152:155], v[206:209], v[68:71]
	v_mfma_f32_16x16x32_bf16 v[112:115], v[148:151], v[180:183], v[112:115]
	v_mfma_f32_16x16x32_bf16 v[116:119], v[156:159], v[180:183], v[116:119]
	v_mfma_f32_16x16x32_bf16 v[96:99], v[148:151], v[188:191], v[96:99]
	v_mfma_f32_16x16x32_bf16 v[100:103], v[156:159], v[188:191], v[100:103]
	v_mfma_f32_16x16x32_bf16 v[80:83], v[148:151], v[202:205], v[80:83]
	v_mfma_f32_16x16x32_bf16 v[84:87], v[156:159], v[202:205], v[84:87]
	v_mfma_f32_16x16x32_bf16 v[64:67], v[148:151], v[210:213], v[64:67]
	v_mfma_f32_16x16x32_bf16 v[68:71], v[156:159], v[210:213], v[68:71]
	s_barrier
	s_add_i32 s20, s51, s31
	s_mov_b32 m0, s20
	ds_read_b128 v[176:179], v197 offset:49152
	global_load_lds_dwordx4 v162, s[98:99]
	s_add_i32 m0, s20, 0x2000
	s_add_u32 s20, s22, 0xb0080
	s_addc_u32 s21, s23, 0
	s_add_i32 s22, s52, s31
	global_load_lds_dwordx4 v166, s[98:99]
	s_mov_b32 m0, s22
	ds_read_b128 v[180:183], v197 offset:50176
	global_load_lds_dwordx4 v162, s[20:21]
	s_add_i32 m0, s22, 0x2000
	ds_read_b128 v[184:187], v197 offset:51200
	global_load_lds_dwordx4 v166, s[20:21]
	s_mov_b32 m0, s39
	ds_read_b128 v[188:191], v197 offset:52224
	global_load_lds_dwordx4 v160, s[100:101]
	s_mov_b32 m0, s40
	ds_read_b128 v[198:201], v197 offset:53248
	global_load_lds_dwordx4 v164, s[100:101]
	ds_read_b128 v[202:205], v197 offset:54272
	ds_read_b128 v[206:209], v197 offset:55296
	ds_read_b128 v[210:213], v197 offset:56320
	s_waitcnt vmcnt(8) lgkmcnt(0)
	s_barrier
	v_mfma_f32_16x16x32_bf16 v[56:59], v[128:131], v[176:179], v[56:59]
	v_mfma_f32_16x16x32_bf16 v[60:63], v[136:139], v[176:179], v[60:63]
	v_mfma_f32_16x16x32_bf16 v[40:43], v[128:131], v[184:187], v[40:43]
	v_mfma_f32_16x16x32_bf16 v[44:47], v[136:139], v[184:187], v[44:47]
	v_mfma_f32_16x16x32_bf16 v[24:27], v[128:131], v[198:201], v[24:27]
	v_mfma_f32_16x16x32_bf16 v[28:31], v[136:139], v[198:201], v[28:31]
	v_mfma_f32_16x16x32_bf16 v[8:11], v[128:131], v[206:209], v[8:11]
	v_mfma_f32_16x16x32_bf16 v[12:15], v[136:139], v[206:209], v[12:15]
	v_mfma_f32_16x16x32_bf16 v[56:59], v[132:135], v[180:183], v[56:59]
	v_mfma_f32_16x16x32_bf16 v[60:63], v[140:143], v[180:183], v[60:63]
	v_mfma_f32_16x16x32_bf16 v[40:43], v[132:135], v[188:191], v[40:43]
	v_mfma_f32_16x16x32_bf16 v[44:47], v[140:143], v[188:191], v[44:47]
	v_mfma_f32_16x16x32_bf16 v[24:27], v[132:135], v[202:205], v[24:27]
	v_mfma_f32_16x16x32_bf16 v[28:31], v[140:143], v[202:205], v[28:31]
	v_mfma_f32_16x16x32_bf16 v[8:11], v[132:135], v[210:213], v[8:11]
	v_mfma_f32_16x16x32_bf16 v[12:15], v[140:143], v[210:213], v[12:15]
	v_mfma_f32_16x16x32_bf16 v[48:51], v[144:147], v[176:179], v[48:51]
	v_mfma_f32_16x16x32_bf16 v[52:55], v[152:155], v[176:179], v[52:55]
	v_mfma_f32_16x16x32_bf16 v[32:35], v[144:147], v[184:187], v[32:35]
	v_mfma_f32_16x16x32_bf16 v[36:39], v[152:155], v[184:187], v[36:39]
	v_mfma_f32_16x16x32_bf16 v[16:19], v[144:147], v[198:201], v[16:19]
	v_mfma_f32_16x16x32_bf16 v[20:23], v[152:155], v[198:201], v[20:23]
	v_mfma_f32_16x16x32_bf16 v[4:7], v[144:147], v[206:209], v[4:7]
	v_mfma_f32_16x16x32_bf16 v[0:3], v[152:155], v[206:209], v[0:3]
	v_mfma_f32_16x16x32_bf16 v[48:51], v[148:151], v[180:183], v[48:51]
	v_mfma_f32_16x16x32_bf16 v[52:55], v[156:159], v[180:183], v[52:55]
	v_mfma_f32_16x16x32_bf16 v[32:35], v[148:151], v[188:191], v[32:35]
	v_mfma_f32_16x16x32_bf16 v[36:39], v[156:159], v[188:191], v[36:39]
	v_mfma_f32_16x16x32_bf16 v[16:19], v[148:151], v[202:205], v[16:19]
	v_mfma_f32_16x16x32_bf16 v[20:23], v[156:159], v[202:205], v[20:23]
	v_mfma_f32_16x16x32_bf16 v[4:7], v[148:151], v[210:213], v[4:7]
	v_mfma_f32_16x16x32_bf16 v[0:3], v[156:159], v[210:213], v[0:3]
	s_barrier
	s_add_i32 s50, s50, 2
	s_add_u32 s48, s48, 0x100
	s_addc_u32 s49, s49, 0
	s_mov_b64 s[20:21], s[2:3]
; #define PG8_STAGE(bufoff, gbase, voff) do { _Pragma("unroll") for (int _i = 0; _i < 2; ++_i) \
;         __builtin_amdgcn_global_load_lds((const unsigned*)((const char*)(gbase) + (voff)[_i]), (PG8_LAS unsigned*)(lds + (bufoff) + ldsw + _i * 8192), 16, 0, 0); } while (0)
; #define PG8_LDA(dst, b, h) do { _Pragma("unroll") for (int m = 0; m < 4; ++m) _Pragma("unroll") for (int k = 0; k < 2; ++k) dst[m][k] = *(const PG8_LAS bf16x8*)(lds + PG8_SA(b, h) + aoff + m * 2048 + k * 1024); } while (0)
; #define PG8_WAIT_V(n) asm volatile("s_waitcnt vmcnt(" #n ")" ::: "memory")
; template <class Epi, class Sched, bool ALIGN_EPI = false, bool SP2 = false>
; __device__ __forceinline__ void gemm_phase(PG8_LAS unsigned char* lds, const Gemm g, const Sched& S, const Epi& E, int tid_in) {
;     ...
;         for (int t = 0; t < nt; t += 2) {
;             if constexpr (Epi::MIDK) { if (t == Epi::MIDK_T) { if (wr == 0) PG8_BAR; E.mid(acc, cur, wr, wc, fr, fq); if (wr == 1) PG8_BAR; } }
;             const bool last = (t == nt - 2);
;             const char* a1 = cA + (size_t)(t + 1) * kstep;
;             const char* a2 = last ? nA : cA + (size_t)(t + 2) * kstep; const char* b2 = last ? nB : cB + (size_t)(t + 2) * kstep;
;             const char* a3 = a2 + kstep; const char* b3 = b2 + kstep;
;             if (last && has_next) S.a_ready(nxt);
;             if constexpr (SP2) {
;             PG8_LDB(B0, 0, 0); PG8_LDB(B1, 0, 1); PG8_SCHED; PG8_LDA(At, 0, 0); PG8_STAGE(PG8_SA(1, 1), a1 + hstep, voffA);
;             PG8_WAIT_V(8); PG8_WAIT_L(0); PG8_BAR; PG8_MMA(0, 0, At, B0); PG8_MMA(0, 1, At, B1); PG8_BAR; PG8_SCHED;
;             PG8_LDA(At, 0, 1); PG8_STAGE(PG8_SB(0, 0), b2, voffB); PG8_STAGE(PG8_SB(0, 1), b2 + hstep, voffB); PG8_STAGE(PG8_SA(0, 0), a2, voffA);
;             PG8_WAIT_V(8); PG8_WAIT_L(0); PG8_BAR; PG8_MMA(1, 0, At, B0); PG8_MMA(1, 1, At, B1); PG8_BAR; PG8_SCHED;
;             PG8_LDB(B0, 1, 0); PG8_LDB(B1, 1, 1); PG8_SCHED; PG8_LDA(At, 1, 0); PG8_STAGE(PG8_SA(0, 1), a2 + hstep, voffA);
;             PG8_WAIT_V(8); PG8_WAIT_L(0); PG8_BAR; PG8_MMA(0, 0, At, B0); PG8_MMA(0, 1, At, B1); PG8_BAR; PG8_SCHED;
;             PG8_LDA(At, 1, 1); PG8_STAGE(PG8_SB(1, 0), b3, voffB); PG8_STAGE(PG8_SB(1, 1), b3 + hstep, voffB); PG8_STAGE(PG8_SA(1, 0), a3, voffA);
;             PG8_WAIT_V(8); PG8_WAIT_L(0); PG8_BAR; PG8_MMA(1, 0, At, B0); PG8_MMA(1, 1, At, B1); PG8_BAR; PG8_SCHED;
.LBB0_1321:
	s_add_u32 s2, s20, 0x100
	s_addc_u32 s3, s21, 0
	s_cmp_eq_u32 s50, 40
	s_cselect_b32 s25, s17, s3
	s_cselect_b32 s24, s16, s2
	s_cselect_b32 s23, s19, s49
	s_cselect_b32 s22, s18, s48
	s_add_i32 m0, s34, 0xc000
	ds_read_b128 v[128:131], v195
	global_load_lds_dwordx4 v168, s[20:21]
	s_add_i32 m0, s34, 0xe000
	ds_read_b128 v[132:135], v195 offset:1024
	global_load_lds_dwordx4 v170, s[20:21]
	ds_read_b128 v[136:139], v195 offset:2048
	ds_read_b128 v[140:143], v195 offset:3072
	ds_read_b128 v[144:147], v196
	ds_read_b128 v[148:151], v196 offset:1024
	ds_read_b128 v[152:155], v196 offset:2048
	ds_read_b128 v[156:159], v196 offset:3072
	ds_read_b128 v[176:179], v197
	ds_read_b128 v[180:183], v197 offset:1024
	ds_read_b128 v[184:187], v197 offset:2048
	ds_read_b128 v[188:191], v197 offset:3072
	ds_read_b128 v[198:201], v197 offset:4096
	ds_read_b128 v[202:205], v197 offset:5120
	ds_read_b128 v[206:209], v197 offset:6144
	ds_read_b128 v[210:213], v197 offset:7168
	s_waitcnt vmcnt(8) lgkmcnt(0)
	s_barrier
	v_mfma_f32_16x16x32_bf16 v[120:123], v[128:131], v[176:179], v[120:123]
	v_mfma_f32_16x16x32_bf16 v[124:127], v[136:139], v[176:179], v[124:127]
	v_mfma_f32_16x16x32_bf16 v[104:107], v[128:131], v[184:187], v[104:107]
	v_mfma_f32_16x16x32_bf16 v[108:111], v[136:139], v[184:187], v[108:111]
	v_mfma_f32_16x16x32_bf16 v[88:91], v[128:131], v[198:201], v[88:91]
	v_mfma_f32_16x16x32_bf16 v[92:95], v[136:139], v[198:201], v[92:95]
	v_mfma_f32_16x16x32_bf16 v[72:75], v[128:131], v[206:209], v[72:75]
	v_mfma_f32_16x16x32_bf16 v[76:79], v[136:139], v[206:209], v[76:79]
	v_mfma_f32_16x16x32_bf16 v[120:123], v[132:135], v[180:183], v[120:123]
	v_mfma_f32_16x16x32_bf16 v[124:127], v[140:143], v[180:183], v[124:127]
	v_mfma_f32_16x16x32_bf16 v[104:107], v[132:135], v[188:191], v[104:107]
	v_mfma_f32_16x16x32_bf16 v[108:111], v[140:143], v[188:191], v[108:111]
	v_mfma_f32_16x16x32_bf16 v[88:91], v[132:135], v[202:205], v[88:91]
	v_mfma_f32_16x16x32_bf16 v[92:95], v[140:143], v[202:205], v[92:95]
	v_mfma_f32_16x16x32_bf16 v[72:75], v[132:135], v[210:213], v[72:75]
	v_mfma_f32_16x16x32_bf16 v[76:79], v[140:143], v[210:213], v[76:79]
	v_mfma_f32_16x16x32_bf16 v[112:115], v[144:147], v[176:179], v[112:115]
	v_mfma_f32_16x16x32_bf16 v[116:119], v[152:155], v[176:179], v[116:119]
	v_mfma_f32_16x16x32_bf16 v[96:99], v[144:147], v[184:187], v[96:99]
	v_mfma_f32_16x16x32_bf16 v[100:103], v[152:155], v[184:187], v[100:103]
	v_mfma_f32_16x16x32_bf16 v[80:83], v[144:147], v[198:201], v[80:83]
	v_mfma_f32_16x16x32_bf16 v[84:87], v[152:155], v[198:201], v[84:87]
	v_mfma_f32_16x16x32_bf16 v[64:67], v[144:147], v[206:209], v[64:67]
	v_mfma_f32_16x16x32_bf16 v[68:71], v[152:155], v[206:209], v[68:71]
	v_mfma_f32_16x16x32_bf16 v[112:115], v[148:151], v[180:183], v[112:115]
	v_mfma_f32_16x16x32_bf16 v[116:119], v[156:159], v[180:183], v[116:119]
	v_mfma_f32_16x16x32_bf16 v[96:99], v[148:151], v[188:191], v[96:99]
	v_mfma_f32_16x16x32_bf16 v[100:103], v[156:159], v[188:191], v[100:103]
	v_mfma_f32_16x16x32_bf16 v[80:83], v[148:151], v[202:205], v[80:83]
	v_mfma_f32_16x16x32_bf16 v[84:87], v[156:159], v[202:205], v[84:87]
	v_mfma_f32_16x16x32_bf16 v[64:67], v[148:151], v[210:213], v[64:67]
	v_mfma_f32_16x16x32_bf16 v[68:71], v[156:159], v[210:213], v[68:71]
	s_barrier
	s_add_u32 s98, s22, s10
	s_addc_u32 s99, s23, s11
	s_add_u32 s100, s24, s10
	s_addc_u32 s101, s25, s11
	s_add_i32 s20, s42, s31
	s_mov_b32 m0, s20
	ds_read_b128 v[176:179], v197 offset:16384
	global_load_lds_dwordx4 v162, s[22:23]
	s_add_i32 m0, s20, 0x2000
	s_add_u32 s20, s22, 0xb0000
	s_addc_u32 s21, s23, 0
	s_add_i32 s51, s43, s31
	global_load_lds_dwordx4 v166, s[22:23]
	s_mov_b32 m0, s51
	ds_read_b128 v[180:183], v197 offset:17408
	global_load_lds_dwordx4 v162, s[20:21]
	s_add_i32 m0, s51, 0x2000
	ds_read_b128 v[184:187], v197 offset:18432
	global_load_lds_dwordx4 v166, s[20:21]
	s_mov_b32 m0, s34
	ds_read_b128 v[188:191], v197 offset:19456
	global_load_lds_dwordx4 v160, s[24:25]
	s_mov_b32 m0, s35
	ds_read_b128 v[198:201], v197 offset:20480
	global_load_lds_dwordx4 v164, s[24:25]
	ds_read_b128 v[202:205], v197 offset:21504
	ds_read_b128 v[206:209], v197 offset:22528
	ds_read_b128 v[210:213], v197 offset:23552
	s_waitcnt vmcnt(8) lgkmcnt(0)
	s_barrier
	v_mfma_f32_16x16x32_bf16 v[56:59], v[128:131], v[176:179], v[56:59]
	v_mfma_f32_16x16x32_bf16 v[60:63], v[136:139], v[176:179], v[60:63]
	v_mfma_f32_16x16x32_bf16 v[40:43], v[128:131], v[184:187], v[40:43]
	v_mfma_f32_16x16x32_bf16 v[44:47], v[136:139], v[184:187], v[44:47]
	v_mfma_f32_16x16x32_bf16 v[24:27], v[128:131], v[198:201], v[24:27]
	v_mfma_f32_16x16x32_bf16 v[28:31], v[136:139], v[198:201], v[28:31]
	v_mfma_f32_16x16x32_bf16 v[8:11], v[128:131], v[206:209], v[8:11]
	v_mfma_f32_16x16x32_bf16 v[12:15], v[136:139], v[206:209], v[12:15]
	v_mfma_f32_16x16x32_bf16 v[56:59], v[132:135], v[180:183], v[56:59]
	v_mfma_f32_16x16x32_bf16 v[60:63], v[140:143], v[180:183], v[60:63]
	v_mfma_f32_16x16x32_bf16 v[40:43], v[132:135], v[188:191], v[40:43]
	v_mfma_f32_16x16x32_bf16 v[44:47], v[140:143], v[188:191], v[44:47]
	v_mfma_f32_16x16x32_bf16 v[24:27], v[132:135], v[202:205], v[24:27]
	v_mfma_f32_16x16x32_bf16 v[28:31], v[140:143], v[202:205], v[28:31]
	v_mfma_f32_16x16x32_bf16 v[8:11], v[132:135], v[210:213], v[8:11]
	v_mfma_f32_16x16x32_bf16 v[12:15], v[140:143], v[210:213], v[12:15]
	v_mfma_f32_16x16x32_bf16 v[48:51], v[144:147], v[176:179], v[48:51]
	v_mfma_f32_16x16x32_bf16 v[52:55], v[152:155], v[176:179], v[52:55]
	v_mfma_f32_16x16x32_bf16 v[32:35], v[144:147], v[184:187], v[32:35]
	v_mfma_f32_16x16x32_bf16 v[36:39], v[152:155], v[184:187], v[36:39]
	v_mfma_f32_16x16x32_bf16 v[16:19], v[144:147], v[198:201], v[16:19]
	v_mfma_f32_16x16x32_bf16 v[20:23], v[152:155], v[198:201], v[20:23]
	v_mfma_f32_16x16x32_bf16 v[4:7], v[144:147], v[206:209], v[4:7]
	v_mfma_f32_16x16x32_bf16 v[0:3], v[152:155], v[206:209], v[0:3]
	v_mfma_f32_16x16x32_bf16 v[48:51], v[148:151], v[180:183], v[48:51]
	v_mfma_f32_16x16x32_bf16 v[52:55], v[156:159], v[180:183], v[52:55]
	v_mfma_f32_16x16x32_bf16 v[32:35], v[148:151], v[188:191], v[32:35]
	v_mfma_f32_16x16x32_bf16 v[36:39], v[156:159], v[188:191], v[36:39]
	v_mfma_f32_16x16x32_bf16 v[16:19], v[148:151], v[202:205], v[16:19]
	v_mfma_f32_16x16x32_bf16 v[20:23], v[156:159], v[202:205], v[20:23]
	v_mfma_f32_16x16x32_bf16 v[4:7], v[148:151], v[210:213], v[4:7]
	v_mfma_f32_16x16x32_bf16 v[0:3], v[156:159], v[210:213], v[0:3]
	s_barrier
; #define PG8_STAGE(bufoff, gbase, voff) do { _Pragma("unroll") for (int _i = 0; _i < 2; ++_i) \
;         __builtin_amdgcn_global_load_lds((const unsigned*)((const char*)(gbase) + (voff)[_i]), (PG8_LAS unsigned*)(lds + (bufoff) + ldsw + _i * 8192), 16, 0, 0); } while (0)
; #define PG8_LDA(dst, b, h) do { _Pragma("unroll") for (int m = 0; m < 4; ++m) _Pragma("unroll") for (int k = 0; k < 2; ++k) dst[m][k] = *(const PG8_LAS bf16x8*)(lds + PG8_SA(b, h) + aoff + m * 2048 + k * 1024); } while (0)
; #define PG8_LDB(dst, b, h) do { _Pragma("unroll") for (int n = 0; n < 2; ++n) _Pragma("unroll") for (int k = 0; k < 2; ++k) dst[n][k] = *(const PG8_LAS bf16x8*)(lds + PG8_SB(b, h) + boff + n * 2048 + k * 1024); } while (0)
; #define PG8_MMA(ai, bj, At, Bt) do { __builtin_amdgcn_s_setprio(1); _Pragma("unroll") for (int m = 0; m < 4; ++m) _Pragma("unroll") for (int n = 0; n < 2; ++n) _Pragma("unroll") for (int k = 0; k < 2; ++k) \
;         acc[ai][bj][m][n] = __builtin_amdgcn_mfma_f32_16x16x32_bf16(Bt[n][k], At[m][k], acc[ai][bj][m][n], 0, 0, 0); __builtin_amdgcn_s_setprio(0); } while (0)
; #define PG8_WAIT_V(n) asm volatile("s_waitcnt vmcnt(" #n ")" ::: "memory")
; #define PG8_WAIT_L(n) asm volatile("s_waitcnt lgkmcnt(" #n ")" ::: "memory")
; #define PG8_BAR __builtin_amdgcn_s_barrier()
; template <class Epi, class Sched, bool ALIGN_EPI = false, bool SP2 = false>
; __device__ __forceinline__ void gemm_phase(PG8_LAS unsigned char* lds, const Gemm g, const Sched& S, const Epi& E, int tid_in) {
;     ...
;             PG8_LDA(At, 0, 1); PG8_STAGE(PG8_SB(0, 0), b2, voffB); PG8_STAGE(PG8_SB(0, 1), b2 + hstep, voffB); PG8_STAGE(PG8_SA(0, 0), a2, voffA);
;             PG8_WAIT_V(8); PG8_WAIT_L(0); PG8_BAR; PG8_MMA(1, 0, At, B0); PG8_MMA(1, 1, At, B1); PG8_BAR; PG8_SCHED;
;             PG8_LDB(B0, 1, 0); PG8_LDB(B1, 1, 1); PG8_SCHED; PG8_LDA(At, 1, 0); PG8_STAGE(PG8_SA(0, 1), a2 + hstep, voffA);
;             PG8_WAIT_V(8); PG8_WAIT_L(0); PG8_BAR; PG8_MMA(0, 0, At, B0); PG8_MMA(0, 1, At, B1); PG8_BAR; PG8_SCHED;
;             PG8_LDA(At, 1, 1); PG8_STAGE(PG8_SB(1, 0), b3, voffB); PG8_STAGE(PG8_SB(1, 1), b3 + hstep, voffB); PG8_STAGE(PG8_SA(1, 0), a3, voffA);
;             PG8_WAIT_V(8); PG8_WAIT_L(0); PG8_BAR; PG8_MMA(1, 0, At, B0); PG8_MMA(1, 1, At, B1); PG8_BAR; PG8_SCHED;
;     ...
;         }
;         if constexpr (ALIGN_EPI) { if (wr == 0) PG8_BAR; }
	s_add_i32 s51, 0, 0x18000
	s_add_i32 s52, 0, 0x1c000
	s_add_u32 s20, s24, 0xb0000
	s_addc_u32 s21, s25, 0
	s_mov_b32 m0, s36
	s_nop 0
	global_load_lds_dwordx4 v160, s[20:21]
	s_mov_b32 m0, s37
	s_nop 0
	global_load_lds_dwordx4 v164, s[20:21]
	v_add_u32_e32 v140, s51, v193
	v_add_u32_e32 v156, s52, v193
	ds_read_b128 v[128:131], v140
	ds_read_b128 v[132:135], v140 offset:1024
	ds_read_b128 v[136:139], v140 offset:2048
	ds_read_b128 v[140:143], v140 offset:3072
	ds_read_b128 v[144:147], v156
	ds_read_b128 v[148:151], v156 offset:1024
	ds_read_b128 v[152:155], v156 offset:2048
	ds_read_b128 v[156:159], v156 offset:3072
	ds_read_b128 v[176:179], v197 offset:32768
	ds_read_b128 v[180:183], v197 offset:33792
	ds_read_b128 v[184:187], v197 offset:34816
	ds_read_b128 v[188:191], v197 offset:35840
	ds_read_b128 v[198:201], v197 offset:36864
	ds_read_b128 v[202:205], v197 offset:37888
	ds_read_b128 v[206:209], v197 offset:38912
	ds_read_b128 v[210:213], v197 offset:39936
	s_waitcnt vmcnt(8) lgkmcnt(0)
	s_barrier
	v_mfma_f32_16x16x32_bf16 v[120:123], v[128:131], v[176:179], v[120:123]
	v_mfma_f32_16x16x32_bf16 v[124:127], v[136:139], v[176:179], v[124:127]
	v_mfma_f32_16x16x32_bf16 v[104:107], v[128:131], v[184:187], v[104:107]
	v_mfma_f32_16x16x32_bf16 v[108:111], v[136:139], v[184:187], v[108:111]
	v_mfma_f32_16x16x32_bf16 v[88:91], v[128:131], v[198:201], v[88:91]
	v_mfma_f32_16x16x32_bf16 v[92:95], v[136:139], v[198:201], v[92:95]
	v_mfma_f32_16x16x32_bf16 v[72:75], v[128:131], v[206:209], v[72:75]
	v_mfma_f32_16x16x32_bf16 v[76:79], v[136:139], v[206:209], v[76:79]
	v_mfma_f32_16x16x32_bf16 v[120:123], v[132:135], v[180:183], v[120:123]
	v_mfma_f32_16x16x32_bf16 v[124:127], v[140:143], v[180:183], v[124:127]
	v_mfma_f32_16x16x32_bf16 v[104:107], v[132:135], v[188:191], v[104:107]
	v_mfma_f32_16x16x32_bf16 v[108:111], v[140:143], v[188:191], v[108:111]
	v_mfma_f32_16x16x32_bf16 v[88:91], v[132:135], v[202:205], v[88:91]
	v_mfma_f32_16x16x32_bf16 v[92:95], v[140:143], v[202:205], v[92:95]
	v_mfma_f32_16x16x32_bf16 v[72:75], v[132:135], v[210:213], v[72:75]
	v_mfma_f32_16x16x32_bf16 v[76:79], v[140:143], v[210:213], v[76:79]
	v_mfma_f32_16x16x32_bf16 v[112:115], v[144:147], v[176:179], v[112:115]
	v_mfma_f32_16x16x32_bf16 v[116:119], v[152:155], v[176:179], v[116:119]
	v_mfma_f32_16x16x32_bf16 v[96:99], v[144:147], v[184:187], v[96:99]
	v_mfma_f32_16x16x32_bf16 v[100:103], v[152:155], v[184:187], v[100:103]
	v_mfma_f32_16x16x32_bf16 v[80:83], v[144:147], v[198:201], v[80:83]
	v_mfma_f32_16x16x32_bf16 v[84:87], v[152:155], v[198:201], v[84:87]
	v_mfma_f32_16x16x32_bf16 v[64:67], v[144:147], v[206:209], v[64:67]
	v_mfma_f32_16x16x32_bf16 v[68:71], v[152:155], v[206:209], v[68:71]
	v_mfma_f32_16x16x32_bf16 v[112:115], v[148:151], v[180:183], v[112:115]
	v_mfma_f32_16x16x32_bf16 v[116:119], v[156:159], v[180:183], v[116:119]
	v_mfma_f32_16x16x32_bf16 v[96:99], v[148:151], v[188:191], v[96:99]
	v_mfma_f32_16x16x32_bf16 v[100:103], v[156:159], v[188:191], v[100:103]
	v_mfma_f32_16x16x32_bf16 v[80:83], v[148:151], v[202:205], v[80:83]
	v_mfma_f32_16x16x32_bf16 v[84:87], v[156:159], v[202:205], v[84:87]
	v_mfma_f32_16x16x32_bf16 v[64:67], v[148:151], v[210:213], v[64:67]
	v_mfma_f32_16x16x32_bf16 v[68:71], v[156:159], v[210:213], v[68:71]
	s_barrier
	s_add_i32 s20, s51, s31
	s_mov_b32 m0, s20
	ds_read_b128 v[176:179], v197 offset:49152
	global_load_lds_dwordx4 v162, s[98:99]
	s_add_i32 m0, s20, 0x2000
	s_add_u32 s20, s22, 0xb0080
	s_addc_u32 s21, s23, 0
	s_add_i32 s22, s52, s31
	global_load_lds_dwordx4 v166, s[98:99]
	s_mov_b32 m0, s22
	ds_read_b128 v[180:183], v197 offset:50176
	global_load_lds_dwordx4 v162, s[20:21]
	s_add_i32 m0, s22, 0x2000
	ds_read_b128 v[184:187], v197 offset:51200
	global_load_lds_dwordx4 v166, s[20:21]
	s_mov_b32 m0, s39
	ds_read_b128 v[188:191], v197 offset:52224
	global_load_lds_dwordx4 v160, s[100:101]
	s_mov_b32 m0, s40
	ds_read_b128 v[198:201], v197 offset:53248
	global_load_lds_dwordx4 v164, s[100:101]
	ds_read_b128 v[202:205], v197 offset:54272
	ds_read_b128 v[206:209], v197 offset:55296
	ds_read_b128 v[210:213], v197 offset:56320
	s_waitcnt vmcnt(8) lgkmcnt(0)
	s_barrier
	v_mfma_f32_16x16x32_bf16 v[56:59], v[128:131], v[176:179], v[56:59]
	v_mfma_f32_16x16x32_bf16 v[60:63], v[136:139], v[176:179], v[60:63]
	v_mfma_f32_16x16x32_bf16 v[40:43], v[128:131], v[184:187], v[40:43]
	v_mfma_f32_16x16x32_bf16 v[44:47], v[136:139], v[184:187], v[44:47]
	v_mfma_f32_16x16x32_bf16 v[24:27], v[128:131], v[198:201], v[24:27]
	v_mfma_f32_16x16x32_bf16 v[28:31], v[136:139], v[198:201], v[28:31]
	v_mfma_f32_16x16x32_bf16 v[8:11], v[128:131], v[206:209], v[8:11]
	v_mfma_f32_16x16x32_bf16 v[12:15], v[136:139], v[206:209], v[12:15]
	v_mfma_f32_16x16x32_bf16 v[56:59], v[132:135], v[180:183], v[56:59]
	v_mfma_f32_16x16x32_bf16 v[60:63], v[140:143], v[180:183], v[60:63]
	v_mfma_f32_16x16x32_bf16 v[40:43], v[132:135], v[188:191], v[40:43]
	v_mfma_f32_16x16x32_bf16 v[44:47], v[140:143], v[188:191], v[44:47]
	v_mfma_f32_16x16x32_bf16 v[24:27], v[132:135], v[202:205], v[24:27]
	v_mfma_f32_16x16x32_bf16 v[28:31], v[140:143], v[202:205], v[28:31]
	v_mfma_f32_16x16x32_bf16 v[8:11], v[132:135], v[210:213], v[8:11]
	v_mfma_f32_16x16x32_bf16 v[12:15], v[140:143], v[210:213], v[12:15]
	v_mfma_f32_16x16x32_bf16 v[48:51], v[144:147], v[176:179], v[48:51]
	v_mfma_f32_16x16x32_bf16 v[52:55], v[152:155], v[176:179], v[52:55]
	v_mfma_f32_16x16x32_bf16 v[32:35], v[144:147], v[184:187], v[32:35]
	v_mfma_f32_16x16x32_bf16 v[36:39], v[152:155], v[184:187], v[36:39]
	v_mfma_f32_16x16x32_bf16 v[16:19], v[144:147], v[198:201], v[16:19]
	v_mfma_f32_16x16x32_bf16 v[20:23], v[152:155], v[198:201], v[20:23]
	v_mfma_f32_16x16x32_bf16 v[4:7], v[144:147], v[206:209], v[4:7]
	v_mfma_f32_16x16x32_bf16 v[0:3], v[152:155], v[206:209], v[0:3]
	v_mfma_f32_16x16x32_bf16 v[48:51], v[148:151], v[180:183], v[48:51]
	v_mfma_f32_16x16x32_bf16 v[52:55], v[156:159], v[180:183], v[52:55]
	v_mfma_f32_16x16x32_bf16 v[32:35], v[148:151], v[188:191], v[32:35]
	v_mfma_f32_16x16x32_bf16 v[36:39], v[156:159], v[188:191], v[36:39]
	v_mfma_f32_16x16x32_bf16 v[16:19], v[148:151], v[202:205], v[16:19]
	v_mfma_f32_16x16x32_bf16 v[20:23], v[156:159], v[202:205], v[20:23]
	v_mfma_f32_16x16x32_bf16 v[4:7], v[148:151], v[210:213], v[4:7]
	v_mfma_f32_16x16x32_bf16 v[0:3], v[156:159], v[210:213], v[0:3]
	s_barrier
	s_add_i32 s50, s50, 2
	s_add_u32 s48, s48, 0x100
	s_addc_u32 s49, s49, 0
	s_cmp_gt_u32 s50, 41
	s_mov_b64 s[20:21], s[2:3]
	s_cbranch_scc0 .LBB0_1321
	s_and_b64 vcc, exec, s[12:13]
	s_cbranch_vccz .LBB0_1324
	s_barrier
